# v063 + GEMM epilogue row sum-of-squares butterflies via v_permlane16/32_swap instead of ds_bpermute round trips
# baseline (speedup 1.0000x reference)
.LBB0_192:
	s_and_b64 vcc, exec, s[58:59]
	s_cbranch_vccz .LBB0_227
	s_cmp_eq_u32 s55, 4
	s_cselect_b64 s[60:61], -1, 0
	s_lshl_b32 s6, s56, 2
	v_lshl_or_b32 v154, s56, 8, v159
	s_ashr_i32 s7, s6, 31
	v_ashrrev_i32_e32 v155, 31, v154
	s_lshl_b64 s[6:7], s[6:7], 2
	v_lshl_add_u64 v[154:155], v[154:155], 1, v[152:153]
	s_or_b64 s[58:59], s[16:17], s[6:7]
	v_mad_i64_i32 v[156:157], s[6:7], s51, v150, 0
	s_cmp_lg_u32 s55, 4
	v_lshl_add_u64 v[156:157], v[156:157], 1, v[154:155]
	v_cvt_pk_bf16_f32 v164, v122, v123
	v_cvt_pk_bf16_f32 v165, v124, v125
	v_cvt_pk_bf16_f32 v166, v118, v119
	v_cvt_pk_bf16_f32 v167, v120, v121
	global_store_dwordx4 v[156:157], v[164:167], off
	s_nop 1
	v_cvt_pk_bf16_f32 v164, v126, v127
	v_cvt_pk_bf16_f32 v165, v128, v129
	v_cvt_pk_bf16_f32 v166, v114, v115
	v_cvt_pk_bf16_f32 v167, v116, v117
	global_store_dwordx4 v[156:157], v[164:167], off offset:256
	s_cbranch_scc1 .LBB0_197
	v_mul_f32_e32 v151, v123, v123
	v_mul_f32_e32 v156, v125, v125
	v_fmac_f32_e32 v151, v122, v122
	v_fmac_f32_e32 v156, v124, v124
	v_add_f32_e32 v151, v151, v156
	v_mul_f32_e32 v156, v119, v119
	v_fmac_f32_e32 v156, v118, v118
	v_add_f32_e32 v151, v156, v151
	v_mul_f32_e32 v156, v127, v127
	v_mul_f32_e32 v157, v129, v129
	v_mul_f32_e32 v138, v121, v121
	v_fmac_f32_e32 v156, v126, v126
	v_fmac_f32_e32 v157, v128, v128
	v_fmac_f32_e32 v138, v120, v120
	v_add_f32_e32 v156, v156, v157
	v_mul_f32_e32 v157, v115, v115
	v_add_f32_e32 v138, v138, v151
	v_mul_f32_e32 v151, v117, v117
	v_fmac_f32_e32 v157, v114, v114
	v_fmac_f32_e32 v151, v116, v116
	v_add_f32_e32 v156, v157, v156
	v_add_f32_e32 v151, v151, v156
	v_and_b32_e32 v156, 64, v161
	v_add_f32_e32 v138, v151, v138
	v_xor_b32_e32 v151, 16, v161
	v_add_u32_e32 v156, 64, v156
	v_cmp_lt_i32_e32 vcc, v151, v156
	s_nop 1
	v_cndmask_b32_e32 v151, v161, v151, vcc
	v_lshlrev_b32_e32 v151, 2, v151
	v_mov_b32_e32 v151, v138
	s_nop 1
	v_permlane16_swap_b32 v151, v138
	s_waitcnt lgkmcnt(0)
	v_add_f32_e32 v138, v138, v151
	v_xor_b32_e32 v151, 32, v161
	v_cmp_lt_i32_e32 vcc, v151, v156
	s_nop 1
	v_cndmask_b32_e32 v151, v161, v151, vcc
	v_lshlrev_b32_e32 v151, 2, v151
	v_mov_b32_e32 v156, v138
	s_nop 1
	v_permlane32_swap_b32 v156, v138
	s_and_saveexec_b64 s[6:7], s[4:5]
	s_cbranch_execz .LBB0_196
	v_ashrrev_i32_e32 v151, 31, v150
	s_waitcnt lgkmcnt(0)
	v_add_f32_e32 v138, v138, v156
	v_lshlrev_b64 v[156:157], 6, v[150:151]
	v_lshl_add_u64 v[156:157], s[58:59], 0, v[156:157]
	global_store_dword v[156:157], v138, off

.LBB0_197:
	s_waitcnt lgkmcnt(0)
	v_or_b32_e32 v156, 16, v150
	v_mad_i64_i32 v[164:165], s[6:7], s51, v156, 0
	v_cndmask_b32_e64 v138, 0, 1, s[60:61]
	v_lshl_add_u64 v[168:169], v[164:165], 1, v[154:155]
	v_cvt_pk_bf16_f32 v164, v110, v111
	v_cvt_pk_bf16_f32 v165, v112, v113
	v_cvt_pk_bf16_f32 v166, v102, v103
	v_cvt_pk_bf16_f32 v167, v104, v105
	v_cmp_ne_u32_e64 s[6:7], 1, v138
	s_andn2_b64 vcc, exec, s[60:61]
	global_store_dwordx4 v[168:169], v[164:167], off
	s_nop 1
	v_cvt_pk_bf16_f32 v164, v106, v107
	v_cvt_pk_bf16_f32 v165, v108, v109
	v_cvt_pk_bf16_f32 v166, v98, v99
	v_cvt_pk_bf16_f32 v167, v100, v101
	global_store_dwordx4 v[168:169], v[164:167], off offset:256
	s_cbranch_vccnz .LBB0_201
	v_mul_f32_e32 v151, v111, v111
	v_mul_f32_e32 v157, v113, v113
	v_fmac_f32_e32 v151, v110, v110
	v_fmac_f32_e32 v157, v112, v112
	v_add_f32_e32 v151, v151, v157
	v_mul_f32_e32 v157, v103, v103
	v_fmac_f32_e32 v157, v102, v102
	v_add_f32_e32 v151, v157, v151
	v_mul_f32_e32 v157, v107, v107
	v_mul_f32_e32 v163, v109, v109
	v_mul_f32_e32 v138, v105, v105
	v_fmac_f32_e32 v157, v106, v106
	v_fmac_f32_e32 v163, v108, v108
	v_fmac_f32_e32 v138, v104, v104
	v_add_f32_e32 v157, v157, v163
	v_mul_f32_e32 v163, v99, v99
	v_add_f32_e32 v138, v138, v151
	v_mul_f32_e32 v151, v101, v101
	v_fmac_f32_e32 v163, v98, v98
	v_fmac_f32_e32 v151, v100, v100
	v_add_f32_e32 v157, v163, v157
	v_add_f32_e32 v151, v151, v157
	v_and_b32_e32 v157, 64, v161
	v_add_f32_e32 v138, v151, v138
	v_xor_b32_e32 v151, 16, v161
	v_add_u32_e32 v157, 64, v157
	v_cmp_lt_i32_e32 vcc, v151, v157
	s_nop 1
	v_cndmask_b32_e32 v151, v161, v151, vcc
	v_lshlrev_b32_e32 v151, 2, v151
	v_mov_b32_e32 v151, v138
	s_nop 1
	v_permlane16_swap_b32 v151, v138
	s_waitcnt lgkmcnt(0)
	v_add_f32_e32 v138, v138, v151
	v_xor_b32_e32 v151, 32, v161
	v_cmp_lt_i32_e32 vcc, v151, v157
	s_nop 1
	v_cndmask_b32_e32 v151, v161, v151, vcc
	v_lshlrev_b32_e32 v151, 2, v151
	v_mov_b32_e32 v151, v138
	s_nop 1
	v_permlane32_swap_b32 v151, v138
	s_and_saveexec_b64 s[60:61], s[4:5]
	s_cbranch_execz .LBB0_200
	v_ashrrev_i32_e32 v157, 31, v156
	v_lshlrev_b64 v[156:157], 6, v[156:157]
	s_waitcnt lgkmcnt(0)
	v_add_f32_e32 v138, v138, v151
	v_lshl_add_u64 v[156:157], s[58:59], 0, v[156:157]
	global_store_dword v[156:157], v138, off

.LBB0_201:
	v_or_b32_e32 v156, 32, v150
	v_mad_i64_i32 v[164:165], s[60:61], s51, v156, 0
	v_lshl_add_u64 v[168:169], v[164:165], 1, v[154:155]
	v_cvt_pk_bf16_f32 v164, v94, v95
	v_cvt_pk_bf16_f32 v165, v96, v97
	v_cvt_pk_bf16_f32 v166, v86, v87
	v_cvt_pk_bf16_f32 v167, v88, v89
	s_and_b64 vcc, exec, s[6:7]
	global_store_dwordx4 v[168:169], v[164:167], off
	s_nop 1
	v_cvt_pk_bf16_f32 v164, v90, v91
	v_cvt_pk_bf16_f32 v165, v92, v93
	v_cvt_pk_bf16_f32 v166, v82, v83
	v_cvt_pk_bf16_f32 v167, v84, v85
	global_store_dwordx4 v[168:169], v[164:167], off offset:256
	s_cbranch_vccnz .LBB0_205
	s_waitcnt lgkmcnt(0)
	v_mul_f32_e32 v151, v95, v95
	v_mul_f32_e32 v157, v97, v97
	v_fmac_f32_e32 v151, v94, v94
	v_fmac_f32_e32 v157, v96, v96
	v_add_f32_e32 v151, v151, v157
	v_mul_f32_e32 v157, v87, v87
	v_fmac_f32_e32 v157, v86, v86
	v_add_f32_e32 v151, v157, v151
	v_mul_f32_e32 v157, v91, v91
	v_mul_f32_e32 v163, v93, v93
	v_mul_f32_e32 v138, v89, v89
	v_fmac_f32_e32 v157, v90, v90
	v_fmac_f32_e32 v163, v92, v92
	v_fmac_f32_e32 v138, v88, v88
	v_add_f32_e32 v157, v157, v163
	v_mul_f32_e32 v163, v83, v83
	v_add_f32_e32 v138, v138, v151
	v_mul_f32_e32 v151, v85, v85
	v_fmac_f32_e32 v163, v82, v82
	v_fmac_f32_e32 v151, v84, v84
	v_add_f32_e32 v157, v163, v157
	v_add_f32_e32 v151, v151, v157
	v_and_b32_e32 v157, 64, v161
	v_add_f32_e32 v138, v151, v138
	v_xor_b32_e32 v151, 16, v161
	v_add_u32_e32 v157, 64, v157
	v_cmp_lt_i32_e32 vcc, v151, v157
	s_nop 1
	v_cndmask_b32_e32 v151, v161, v151, vcc
	v_lshlrev_b32_e32 v151, 2, v151
	v_mov_b32_e32 v151, v138
	s_nop 1
	v_permlane16_swap_b32 v151, v138
	s_waitcnt lgkmcnt(0)
	v_add_f32_e32 v138, v138, v151
	v_xor_b32_e32 v151, 32, v161
	v_cmp_lt_i32_e32 vcc, v151, v157
	s_nop 1
	v_cndmask_b32_e32 v151, v161, v151, vcc
	v_lshlrev_b32_e32 v151, 2, v151
	v_mov_b32_e32 v151, v138
	s_nop 1
	v_permlane32_swap_b32 v151, v138
	s_and_saveexec_b64 s[60:61], s[4:5]
	s_cbranch_execz .LBB0_204
	v_ashrrev_i32_e32 v157, 31, v156
	v_lshlrev_b64 v[156:157], 6, v[156:157]
	s_waitcnt lgkmcnt(0)
	v_add_f32_e32 v138, v138, v151
	v_lshl_add_u64 v[156:157], s[58:59], 0, v[156:157]
	global_store_dword v[156:157], v138, off

.LBB0_205:
	v_or_b32_e32 v156, 48, v150
	v_mad_i64_i32 v[164:165], s[60:61], s51, v156, 0
	v_lshl_add_u64 v[168:169], v[164:165], 1, v[154:155]
	v_cvt_pk_bf16_f32 v164, v78, v79
	v_cvt_pk_bf16_f32 v165, v80, v81
	v_cvt_pk_bf16_f32 v166, v70, v71
	v_cvt_pk_bf16_f32 v167, v72, v73
	s_and_b64 vcc, exec, s[6:7]
	global_store_dwordx4 v[168:169], v[164:167], off
	s_nop 1
	v_cvt_pk_bf16_f32 v164, v74, v75
	v_cvt_pk_bf16_f32 v165, v76, v77
	v_cvt_pk_bf16_f32 v166, v66, v67
	v_cvt_pk_bf16_f32 v167, v68, v69
	global_store_dwordx4 v[168:169], v[164:167], off offset:256
	s_cbranch_vccnz .LBB0_209
	s_waitcnt lgkmcnt(0)
	v_mul_f32_e32 v151, v79, v79
	v_mul_f32_e32 v157, v81, v81
	v_fmac_f32_e32 v151, v78, v78
	v_fmac_f32_e32 v157, v80, v80
	v_add_f32_e32 v151, v151, v157
	v_mul_f32_e32 v157, v71, v71
	v_fmac_f32_e32 v157, v70, v70
	v_add_f32_e32 v151, v157, v151
	v_mul_f32_e32 v157, v75, v75
	v_mul_f32_e32 v163, v77, v77
	v_mul_f32_e32 v138, v73, v73
	v_fmac_f32_e32 v157, v74, v74
	v_fmac_f32_e32 v163, v76, v76
	v_fmac_f32_e32 v138, v72, v72
	v_add_f32_e32 v157, v157, v163
	v_mul_f32_e32 v163, v67, v67
	v_add_f32_e32 v138, v138, v151
	v_mul_f32_e32 v151, v69, v69
	v_fmac_f32_e32 v163, v66, v66
	v_fmac_f32_e32 v151, v68, v68
	v_add_f32_e32 v157, v163, v157
	v_add_f32_e32 v151, v151, v157
	v_and_b32_e32 v157, 64, v161
	v_add_f32_e32 v138, v151, v138
	v_xor_b32_e32 v151, 16, v161
	v_add_u32_e32 v157, 64, v157
	v_cmp_lt_i32_e32 vcc, v151, v157
	s_nop 1
	v_cndmask_b32_e32 v151, v161, v151, vcc
	v_lshlrev_b32_e32 v151, 2, v151
	v_mov_b32_e32 v151, v138
	s_nop 1
	v_permlane16_swap_b32 v151, v138
	s_waitcnt lgkmcnt(0)
	v_add_f32_e32 v138, v138, v151
	v_xor_b32_e32 v151, 32, v161
	v_cmp_lt_i32_e32 vcc, v151, v157
	s_nop 1
	v_cndmask_b32_e32 v151, v161, v151, vcc
	v_lshlrev_b32_e32 v151, 2, v151
	v_mov_b32_e32 v151, v138
	s_nop 1
	v_permlane32_swap_b32 v151, v138
	s_and_saveexec_b64 s[60:61], s[4:5]
	s_cbranch_execz .LBB0_208
	v_ashrrev_i32_e32 v157, 31, v156
	v_lshlrev_b64 v[156:157], 6, v[156:157]
	s_waitcnt lgkmcnt(0)
	v_add_f32_e32 v138, v138, v151
	v_lshl_add_u64 v[156:157], s[58:59], 0, v[156:157]
	global_store_dword v[156:157], v138, off

.LBB0_209:
	v_add_u32_e32 v156, 0x80, v150
	v_mad_i64_i32 v[164:165], s[60:61], s51, v156, 0
	v_lshl_add_u64 v[168:169], v[164:165], 1, v[154:155]
	v_cvt_pk_bf16_f32 v164, v62, v63
	v_cvt_pk_bf16_f32 v165, v64, v65
	v_cvt_pk_bf16_f32 v166, v54, v55
	v_cvt_pk_bf16_f32 v167, v56, v57
	s_and_b64 vcc, exec, s[6:7]
	global_store_dwordx4 v[168:169], v[164:167], off
	s_nop 1
	v_cvt_pk_bf16_f32 v164, v58, v59
	v_cvt_pk_bf16_f32 v165, v60, v61
	v_cvt_pk_bf16_f32 v166, v50, v51
	v_cvt_pk_bf16_f32 v167, v52, v53
	global_store_dwordx4 v[168:169], v[164:167], off offset:256
	s_cbranch_vccnz .LBB0_213
	s_waitcnt lgkmcnt(0)
	v_mul_f32_e32 v151, v63, v63
	v_mul_f32_e32 v157, v65, v65
	v_fmac_f32_e32 v151, v62, v62
	v_fmac_f32_e32 v157, v64, v64
	v_add_f32_e32 v151, v151, v157
	v_mul_f32_e32 v157, v55, v55
	v_fmac_f32_e32 v157, v54, v54
	v_add_f32_e32 v151, v157, v151
	v_mul_f32_e32 v157, v59, v59
	v_mul_f32_e32 v163, v61, v61
	v_mul_f32_e32 v138, v57, v57
	v_fmac_f32_e32 v157, v58, v58
	v_fmac_f32_e32 v163, v60, v60
	v_fmac_f32_e32 v138, v56, v56
	v_add_f32_e32 v157, v157, v163
	v_mul_f32_e32 v163, v51, v51
	v_add_f32_e32 v138, v138, v151
	v_mul_f32_e32 v151, v53, v53
	v_fmac_f32_e32 v163, v50, v50
	v_fmac_f32_e32 v151, v52, v52
	v_add_f32_e32 v157, v163, v157
	v_add_f32_e32 v151, v151, v157
	v_and_b32_e32 v157, 64, v161
	v_add_f32_e32 v138, v151, v138
	v_xor_b32_e32 v151, 16, v161
	v_add_u32_e32 v157, 64, v157
	v_cmp_lt_i32_e32 vcc, v151, v157
	s_nop 1
	v_cndmask_b32_e32 v151, v161, v151, vcc
	v_lshlrev_b32_e32 v151, 2, v151
	v_mov_b32_e32 v151, v138
	s_nop 1
	v_permlane16_swap_b32 v151, v138
	s_waitcnt lgkmcnt(0)
	v_add_f32_e32 v138, v138, v151
	v_xor_b32_e32 v151, 32, v161
	v_cmp_lt_i32_e32 vcc, v151, v157
	s_nop 1
	v_cndmask_b32_e32 v151, v161, v151, vcc
	v_lshlrev_b32_e32 v151, 2, v151
	v_mov_b32_e32 v151, v138
	s_nop 1
	v_permlane32_swap_b32 v151, v138
	s_and_saveexec_b64 s[60:61], s[4:5]
	s_cbranch_execz .LBB0_212
	v_ashrrev_i32_e32 v157, 31, v156
	v_lshlrev_b64 v[156:157], 6, v[156:157]
	s_waitcnt lgkmcnt(0)
	v_add_f32_e32 v138, v138, v151
	v_lshl_add_u64 v[156:157], s[58:59], 0, v[156:157]
	global_store_dword v[156:157], v138, off

.LBB0_213:
	v_add_u32_e32 v156, 0x90, v150
	v_mad_i64_i32 v[164:165], s[60:61], s51, v156, 0
	v_lshl_add_u64 v[168:169], v[164:165], 1, v[154:155]
	v_cvt_pk_bf16_f32 v164, v46, v47
	v_cvt_pk_bf16_f32 v165, v48, v49
	v_cvt_pk_bf16_f32 v166, v38, v39
	v_cvt_pk_bf16_f32 v167, v40, v41
	s_and_b64 vcc, exec, s[6:7]
	global_store_dwordx4 v[168:169], v[164:167], off
	s_nop 1
	v_cvt_pk_bf16_f32 v164, v42, v43
	v_cvt_pk_bf16_f32 v165, v44, v45
	v_cvt_pk_bf16_f32 v166, v34, v35
	v_cvt_pk_bf16_f32 v167, v36, v37
	global_store_dwordx4 v[168:169], v[164:167], off offset:256
	s_cbranch_vccnz .LBB0_217
	s_waitcnt lgkmcnt(0)
	v_mul_f32_e32 v151, v47, v47
	v_mul_f32_e32 v157, v49, v49
	v_fmac_f32_e32 v151, v46, v46
	v_fmac_f32_e32 v157, v48, v48
	v_add_f32_e32 v151, v151, v157
	v_mul_f32_e32 v157, v39, v39
	v_fmac_f32_e32 v157, v38, v38
	v_add_f32_e32 v151, v157, v151
	v_mul_f32_e32 v157, v43, v43
	v_mul_f32_e32 v163, v45, v45
	v_mul_f32_e32 v138, v41, v41
	v_fmac_f32_e32 v157, v42, v42
	v_fmac_f32_e32 v163, v44, v44
	v_fmac_f32_e32 v138, v40, v40
	v_add_f32_e32 v157, v157, v163
	v_mul_f32_e32 v163, v35, v35
	v_add_f32_e32 v138, v138, v151
	v_mul_f32_e32 v151, v37, v37
	v_fmac_f32_e32 v163, v34, v34
	v_fmac_f32_e32 v151, v36, v36
	v_add_f32_e32 v157, v163, v157
	v_add_f32_e32 v151, v151, v157
	v_and_b32_e32 v157, 64, v161
	v_add_f32_e32 v138, v151, v138
	v_xor_b32_e32 v151, 16, v161
	v_add_u32_e32 v157, 64, v157
	v_cmp_lt_i32_e32 vcc, v151, v157
	s_nop 1
	v_cndmask_b32_e32 v151, v161, v151, vcc
	v_lshlrev_b32_e32 v151, 2, v151
	v_mov_b32_e32 v151, v138
	s_nop 1
	v_permlane16_swap_b32 v151, v138
	s_waitcnt lgkmcnt(0)
	v_add_f32_e32 v138, v138, v151
	v_xor_b32_e32 v151, 32, v161
	v_cmp_lt_i32_e32 vcc, v151, v157
	s_nop 1
	v_cndmask_b32_e32 v151, v161, v151, vcc
	v_lshlrev_b32_e32 v151, 2, v151
	v_mov_b32_e32 v151, v138
	s_nop 1
	v_permlane32_swap_b32 v151, v138
	s_and_saveexec_b64 s[60:61], s[4:5]
	s_cbranch_execz .LBB0_216
	v_ashrrev_i32_e32 v157, 31, v156
	v_lshlrev_b64 v[156:157], 6, v[156:157]
	s_waitcnt lgkmcnt(0)
	v_add_f32_e32 v138, v138, v151
	v_lshl_add_u64 v[156:157], s[58:59], 0, v[156:157]
	global_store_dword v[156:157], v138, off

.LBB0_217:
	v_add_u32_e32 v156, 0xa0, v150
	v_mad_i64_i32 v[164:165], s[60:61], s51, v156, 0
	v_lshl_add_u64 v[168:169], v[164:165], 1, v[154:155]
	v_cvt_pk_bf16_f32 v164, v30, v31
	v_cvt_pk_bf16_f32 v165, v32, v33
	v_cvt_pk_bf16_f32 v166, v22, v23
	v_cvt_pk_bf16_f32 v167, v24, v25
	s_and_b64 vcc, exec, s[6:7]
	global_store_dwordx4 v[168:169], v[164:167], off
	s_nop 1
	v_cvt_pk_bf16_f32 v164, v26, v27
	v_cvt_pk_bf16_f32 v165, v28, v29
	v_cvt_pk_bf16_f32 v166, v18, v19
	v_cvt_pk_bf16_f32 v167, v20, v21
	global_store_dwordx4 v[168:169], v[164:167], off offset:256
	s_cbranch_vccnz .LBB0_221
	s_waitcnt lgkmcnt(0)
	v_mul_f32_e32 v151, v31, v31
	v_mul_f32_e32 v157, v33, v33
	v_fmac_f32_e32 v151, v30, v30
	v_fmac_f32_e32 v157, v32, v32
	v_add_f32_e32 v151, v151, v157
	v_mul_f32_e32 v157, v23, v23
	v_fmac_f32_e32 v157, v22, v22
	v_add_f32_e32 v151, v157, v151
	v_mul_f32_e32 v157, v27, v27
	v_mul_f32_e32 v163, v29, v29
	v_mul_f32_e32 v138, v25, v25
	v_fmac_f32_e32 v157, v26, v26
	v_fmac_f32_e32 v163, v28, v28
	v_fmac_f32_e32 v138, v24, v24
	v_add_f32_e32 v157, v157, v163
	v_mul_f32_e32 v163, v19, v19
	v_add_f32_e32 v138, v138, v151
	v_mul_f32_e32 v151, v21, v21
	v_fmac_f32_e32 v163, v18, v18
	v_fmac_f32_e32 v151, v20, v20
	v_add_f32_e32 v157, v163, v157
	v_add_f32_e32 v151, v151, v157
	v_and_b32_e32 v157, 64, v161
	v_add_f32_e32 v138, v151, v138
	v_xor_b32_e32 v151, 16, v161
	v_add_u32_e32 v157, 64, v157
	v_cmp_lt_i32_e32 vcc, v151, v157
	s_nop 1
	v_cndmask_b32_e32 v151, v161, v151, vcc
	v_lshlrev_b32_e32 v151, 2, v151
	v_mov_b32_e32 v151, v138
	s_nop 1
	v_permlane16_swap_b32 v151, v138
	s_waitcnt lgkmcnt(0)
	v_add_f32_e32 v138, v138, v151
	v_xor_b32_e32 v151, 32, v161
	v_cmp_lt_i32_e32 vcc, v151, v157
	s_nop 1
	v_cndmask_b32_e32 v151, v161, v151, vcc
	v_lshlrev_b32_e32 v151, 2, v151
	v_mov_b32_e32 v151, v138
	s_nop 1
	v_permlane32_swap_b32 v151, v138
	s_and_saveexec_b64 s[60:61], s[4:5]
	s_cbranch_execz .LBB0_220
	v_ashrrev_i32_e32 v157, 31, v156
	v_lshlrev_b64 v[156:157], 6, v[156:157]
	s_waitcnt lgkmcnt(0)
	v_add_f32_e32 v138, v138, v151
	v_lshl_add_u64 v[156:157], s[58:59], 0, v[156:157]
	global_store_dword v[156:157], v138, off

.LBB0_221:
	v_add_u32_e32 v156, 0xb0, v150
	v_mad_i64_i32 v[164:165], s[60:61], s51, v156, 0
	v_lshl_add_u64 v[154:155], v[164:165], 1, v[154:155]
	v_cvt_pk_bf16_f32 v164, v14, v15
	v_cvt_pk_bf16_f32 v165, v16, v17
	v_cvt_pk_bf16_f32 v166, v6, v7
	v_cvt_pk_bf16_f32 v167, v8, v9
	s_and_b64 vcc, exec, s[6:7]
	global_store_dwordx4 v[154:155], v[164:167], off
	s_nop 1
	v_cvt_pk_bf16_f32 v164, v10, v11
	v_cvt_pk_bf16_f32 v165, v12, v13
	v_cvt_pk_bf16_f32 v166, v2, v3
	v_cvt_pk_bf16_f32 v167, v4, v5
	global_store_dwordx4 v[154:155], v[164:167], off offset:256
	s_cbranch_vccnz .LBB0_225
	s_waitcnt lgkmcnt(0)
	v_mul_f32_e32 v151, v15, v15
	v_mul_f32_e32 v154, v17, v17
	v_fmac_f32_e32 v151, v14, v14
	v_fmac_f32_e32 v154, v16, v16
	v_add_f32_e32 v151, v151, v154
	v_mul_f32_e32 v154, v7, v7
	v_fmac_f32_e32 v154, v6, v6
	v_add_f32_e32 v151, v154, v151
	v_mul_f32_e32 v154, v11, v11
	v_mul_f32_e32 v155, v13, v13
	v_mul_f32_e32 v138, v9, v9
	v_fmac_f32_e32 v154, v10, v10
	v_fmac_f32_e32 v155, v12, v12
	v_fmac_f32_e32 v138, v8, v8
	v_add_f32_e32 v154, v154, v155
	v_mul_f32_e32 v155, v3, v3
	v_add_f32_e32 v138, v138, v151
	v_mul_f32_e32 v151, v5, v5
	v_fmac_f32_e32 v155, v2, v2
	v_fmac_f32_e32 v151, v4, v4
	v_add_f32_e32 v154, v155, v154
	v_add_f32_e32 v151, v151, v154
	v_and_b32_e32 v154, 64, v161
	v_add_f32_e32 v138, v151, v138
	v_xor_b32_e32 v151, 16, v161
	v_add_u32_e32 v154, 64, v154
	v_cmp_lt_i32_e32 vcc, v151, v154
	s_nop 1
	v_cndmask_b32_e32 v151, v161, v151, vcc
	v_lshlrev_b32_e32 v151, 2, v151
	v_mov_b32_e32 v151, v138
	s_nop 1
	v_permlane16_swap_b32 v151, v138
	s_waitcnt lgkmcnt(0)
	v_add_f32_e32 v138, v138, v151
	v_xor_b32_e32 v151, 32, v161
	v_cmp_lt_i32_e32 vcc, v151, v154
	s_nop 1
	v_cndmask_b32_e32 v151, v161, v151, vcc
	v_lshlrev_b32_e32 v151, 2, v151
	v_mov_b32_e32 v151, v138
	s_nop 1
	v_permlane32_swap_b32 v151, v138
	s_and_saveexec_b64 s[6:7], s[4:5]
	s_cbranch_execz .LBB0_224
	v_ashrrev_i32_e32 v157, 31, v156
	v_lshlrev_b64 v[154:155], 6, v[156:157]
	s_waitcnt lgkmcnt(0)
	v_add_f32_e32 v138, v138, v151
	v_lshl_add_u64 v[154:155], s[58:59], 0, v[154:155]
	global_store_dword v[154:155], v138, off

.LBB0_331:
	s_and_b64 vcc, exec, s[48:49]
	s_cbranch_vccz .LBB0_366
	s_cmp_eq_u32 s79, 4
	s_cselect_b64 s[50:51], -1, 0
	s_lshl_b32 s8, s77, 2
	s_ashr_i32 s9, s8, 31
	v_lshl_or_b32 v156, s77, 8, v162
	s_lshl_b64 s[8:9], s[8:9], 2
	v_ashrrev_i32_e32 v157, 31, v156
	s_add_u32 s48, s67, s8
	v_lshl_add_u64 v[156:157], v[156:157], 1, v[154:155]
	s_addc_u32 s49, s68, s9
	v_mad_i64_i32 v[158:159], s[8:9], s78, v152, 0
	s_cmp_lg_u32 s79, 4
	v_lshl_add_u64 v[158:159], v[158:159], 1, v[156:157]
	v_cvt_pk_bf16_f32 v166, v122, v123
	v_cvt_pk_bf16_f32 v167, v124, v125
	v_cvt_pk_bf16_f32 v168, v118, v119
	v_cvt_pk_bf16_f32 v169, v120, v121
	global_store_dwordx4 v[158:159], v[166:169], off
	s_nop 1
	v_cvt_pk_bf16_f32 v166, v126, v127
	v_cvt_pk_bf16_f32 v167, v128, v129
	v_cvt_pk_bf16_f32 v168, v114, v115
	v_cvt_pk_bf16_f32 v169, v116, v117
	global_store_dwordx4 v[158:159], v[166:169], off offset:256
	s_cbranch_scc1 .LBB0_336
	v_mul_f32_e32 v141, v123, v123
	v_mul_f32_e32 v146, v125, v125
	v_fmac_f32_e32 v141, v122, v122
	v_fmac_f32_e32 v146, v124, v124
	v_add_f32_e32 v141, v141, v146
	v_mul_f32_e32 v146, v119, v119
	v_fmac_f32_e32 v146, v118, v118
	v_add_f32_e32 v141, v146, v141
	v_mul_f32_e32 v146, v127, v127
	v_mul_f32_e32 v153, v129, v129
	v_mul_f32_e32 v138, v121, v121
	v_fmac_f32_e32 v146, v126, v126
	v_fmac_f32_e32 v153, v128, v128
	v_fmac_f32_e32 v138, v120, v120
	v_add_f32_e32 v146, v146, v153
	v_mul_f32_e32 v153, v115, v115
	v_add_f32_e32 v138, v138, v141
	v_mul_f32_e32 v141, v117, v117
	v_fmac_f32_e32 v153, v114, v114
	v_fmac_f32_e32 v141, v116, v116
	v_add_f32_e32 v146, v153, v146
	v_add_f32_e32 v141, v141, v146
	v_and_b32_e32 v146, 64, v164
	v_add_f32_e32 v138, v141, v138
	v_xor_b32_e32 v141, 16, v164
	v_add_u32_e32 v146, 64, v146
	v_cmp_lt_i32_e32 vcc, v141, v146
	s_nop 1
	v_cndmask_b32_e32 v141, v164, v141, vcc
	v_lshlrev_b32_e32 v141, 2, v141
	v_mov_b32_e32 v141, v138
	s_nop 1
	v_permlane16_swap_b32 v141, v138
	s_waitcnt lgkmcnt(0)
	v_add_f32_e32 v138, v138, v141
	v_xor_b32_e32 v141, 32, v164
	v_cmp_lt_i32_e32 vcc, v141, v146
	s_nop 1
	v_cndmask_b32_e32 v141, v164, v141, vcc
	v_lshlrev_b32_e32 v141, 2, v141
	v_mov_b32_e32 v141, v138
	s_nop 1
	v_permlane32_swap_b32 v141, v138
	s_and_saveexec_b64 s[8:9], s[4:5]
	s_cbranch_execz .LBB0_335
	v_ashrrev_i32_e32 v153, 31, v152
	v_lshlrev_b64 v[158:159], 6, v[152:153]
	v_lshl_add_u64 v[158:159], s[48:49], 0, v[158:159]
	s_waitcnt lgkmcnt(0)
	v_add_f32_e32 v138, v138, v141
	global_store_dword v[158:159], v138, off

.LBB0_336:
	v_or_b32_e32 v158, 16, v152
	v_mad_i64_i32 v[166:167], s[8:9], s78, v158, 0
	v_cndmask_b32_e64 v138, 0, 1, s[50:51]
	v_lshl_add_u64 v[170:171], v[166:167], 1, v[156:157]
	v_cvt_pk_bf16_f32 v166, v110, v111
	v_cvt_pk_bf16_f32 v167, v112, v113
	v_cvt_pk_bf16_f32 v168, v102, v103
	v_cvt_pk_bf16_f32 v169, v104, v105
	v_cmp_ne_u32_e64 s[8:9], 1, v138
	s_andn2_b64 vcc, exec, s[50:51]
	global_store_dwordx4 v[170:171], v[166:169], off
	s_nop 1
	v_cvt_pk_bf16_f32 v166, v106, v107
	v_cvt_pk_bf16_f32 v167, v108, v109
	v_cvt_pk_bf16_f32 v168, v98, v99
	v_cvt_pk_bf16_f32 v169, v100, v101
	global_store_dwordx4 v[170:171], v[166:169], off offset:256
	s_cbranch_vccnz .LBB0_340
	s_waitcnt lgkmcnt(0)
	v_mul_f32_e32 v141, v111, v111
	v_mul_f32_e32 v146, v113, v113
	v_fmac_f32_e32 v141, v110, v110
	v_fmac_f32_e32 v146, v112, v112
	v_add_f32_e32 v141, v141, v146
	v_mul_f32_e32 v146, v103, v103
	v_fmac_f32_e32 v146, v102, v102
	v_add_f32_e32 v141, v146, v141
	v_mul_f32_e32 v146, v107, v107
	v_mul_f32_e32 v153, v109, v109
	v_mul_f32_e32 v138, v105, v105
	v_fmac_f32_e32 v146, v106, v106
	v_fmac_f32_e32 v153, v108, v108
	v_fmac_f32_e32 v138, v104, v104
	v_add_f32_e32 v146, v146, v153
	v_mul_f32_e32 v153, v99, v99
	v_add_f32_e32 v138, v138, v141
	v_mul_f32_e32 v141, v101, v101
	v_fmac_f32_e32 v153, v98, v98
	v_fmac_f32_e32 v141, v100, v100
	v_add_f32_e32 v146, v153, v146
	v_add_f32_e32 v141, v141, v146
	v_and_b32_e32 v146, 64, v164
	v_add_f32_e32 v138, v141, v138
	v_xor_b32_e32 v141, 16, v164
	v_add_u32_e32 v146, 64, v146
	v_cmp_lt_i32_e32 vcc, v141, v146
	s_nop 1
	v_cndmask_b32_e32 v141, v164, v141, vcc
	v_lshlrev_b32_e32 v141, 2, v141
	v_mov_b32_e32 v141, v138
	s_nop 1
	v_permlane16_swap_b32 v141, v138
	s_waitcnt lgkmcnt(0)
	v_add_f32_e32 v138, v138, v141
	v_xor_b32_e32 v141, 32, v164
	v_cmp_lt_i32_e32 vcc, v141, v146
	s_nop 1
	v_cndmask_b32_e32 v141, v164, v141, vcc
	v_lshlrev_b32_e32 v141, 2, v141
	v_mov_b32_e32 v141, v138
	s_nop 1
	v_permlane32_swap_b32 v141, v138
	s_and_saveexec_b64 s[50:51], s[4:5]
	s_cbranch_execz .LBB0_339
	v_ashrrev_i32_e32 v159, 31, v158
	v_lshlrev_b64 v[158:159], 6, v[158:159]
	v_lshl_add_u64 v[158:159], s[48:49], 0, v[158:159]
	s_waitcnt lgkmcnt(0)
	v_add_f32_e32 v138, v138, v141
	global_store_dword v[158:159], v138, off

.LBB0_340:
	v_or_b32_e32 v158, 32, v152
	v_mad_i64_i32 v[166:167], s[50:51], s78, v158, 0
	v_lshl_add_u64 v[170:171], v[166:167], 1, v[156:157]
	v_cvt_pk_bf16_f32 v166, v94, v95
	v_cvt_pk_bf16_f32 v167, v96, v97
	v_cvt_pk_bf16_f32 v168, v86, v87
	v_cvt_pk_bf16_f32 v169, v88, v89
	s_and_b64 vcc, exec, s[8:9]
	global_store_dwordx4 v[170:171], v[166:169], off
	s_nop 1
	v_cvt_pk_bf16_f32 v166, v90, v91
	v_cvt_pk_bf16_f32 v167, v92, v93
	v_cvt_pk_bf16_f32 v168, v82, v83
	v_cvt_pk_bf16_f32 v169, v84, v85
	global_store_dwordx4 v[170:171], v[166:169], off offset:256
	s_cbranch_vccnz .LBB0_344
	s_waitcnt lgkmcnt(0)
	v_mul_f32_e32 v141, v95, v95
	v_mul_f32_e32 v146, v97, v97
	v_fmac_f32_e32 v141, v94, v94
	v_fmac_f32_e32 v146, v96, v96
	v_add_f32_e32 v141, v141, v146
	v_mul_f32_e32 v146, v87, v87
	v_fmac_f32_e32 v146, v86, v86
	v_add_f32_e32 v141, v146, v141
	v_mul_f32_e32 v146, v91, v91
	v_mul_f32_e32 v153, v93, v93
	v_mul_f32_e32 v138, v89, v89
	v_fmac_f32_e32 v146, v90, v90
	v_fmac_f32_e32 v153, v92, v92
	v_fmac_f32_e32 v138, v88, v88
	v_add_f32_e32 v146, v146, v153
	v_mul_f32_e32 v153, v83, v83
	v_add_f32_e32 v138, v138, v141
	v_mul_f32_e32 v141, v85, v85
	v_fmac_f32_e32 v153, v82, v82
	v_fmac_f32_e32 v141, v84, v84
	v_add_f32_e32 v146, v153, v146
	v_add_f32_e32 v141, v141, v146
	v_and_b32_e32 v146, 64, v164
	v_add_f32_e32 v138, v141, v138
	v_xor_b32_e32 v141, 16, v164
	v_add_u32_e32 v146, 64, v146
	v_cmp_lt_i32_e32 vcc, v141, v146
	s_nop 1
	v_cndmask_b32_e32 v141, v164, v141, vcc
	v_lshlrev_b32_e32 v141, 2, v141
	v_mov_b32_e32 v141, v138
	s_nop 1
	v_permlane16_swap_b32 v141, v138
	s_waitcnt lgkmcnt(0)
	v_add_f32_e32 v138, v138, v141
	v_xor_b32_e32 v141, 32, v164
	v_cmp_lt_i32_e32 vcc, v141, v146
	s_nop 1
	v_cndmask_b32_e32 v141, v164, v141, vcc
	v_lshlrev_b32_e32 v141, 2, v141
	v_mov_b32_e32 v141, v138
	s_nop 1
	v_permlane32_swap_b32 v141, v138
	s_and_saveexec_b64 s[50:51], s[4:5]
	s_cbranch_execz .LBB0_343
	v_ashrrev_i32_e32 v159, 31, v158
	v_lshlrev_b64 v[158:159], 6, v[158:159]
	v_lshl_add_u64 v[158:159], s[48:49], 0, v[158:159]
	s_waitcnt lgkmcnt(0)
	v_add_f32_e32 v138, v138, v141
	global_store_dword v[158:159], v138, off

.LBB0_344:
	v_or_b32_e32 v158, 48, v152
	v_mad_i64_i32 v[166:167], s[50:51], s78, v158, 0
	v_lshl_add_u64 v[170:171], v[166:167], 1, v[156:157]
	v_cvt_pk_bf16_f32 v166, v78, v79
	v_cvt_pk_bf16_f32 v167, v80, v81
	v_cvt_pk_bf16_f32 v168, v70, v71
	v_cvt_pk_bf16_f32 v169, v72, v73
	s_and_b64 vcc, exec, s[8:9]
	global_store_dwordx4 v[170:171], v[166:169], off
	s_nop 1
	v_cvt_pk_bf16_f32 v166, v74, v75
	v_cvt_pk_bf16_f32 v167, v76, v77
	v_cvt_pk_bf16_f32 v168, v66, v67
	v_cvt_pk_bf16_f32 v169, v68, v69
	global_store_dwordx4 v[170:171], v[166:169], off offset:256
	s_cbranch_vccnz .LBB0_348
	s_waitcnt lgkmcnt(0)
	v_mul_f32_e32 v141, v79, v79
	v_mul_f32_e32 v146, v81, v81
	v_fmac_f32_e32 v141, v78, v78
	v_fmac_f32_e32 v146, v80, v80
	v_add_f32_e32 v141, v141, v146
	v_mul_f32_e32 v146, v71, v71
	v_fmac_f32_e32 v146, v70, v70
	v_add_f32_e32 v141, v146, v141
	v_mul_f32_e32 v146, v75, v75
	v_mul_f32_e32 v153, v77, v77
	v_mul_f32_e32 v138, v73, v73
	v_fmac_f32_e32 v146, v74, v74
	v_fmac_f32_e32 v153, v76, v76
	v_fmac_f32_e32 v138, v72, v72
	v_add_f32_e32 v146, v146, v153
	v_mul_f32_e32 v153, v67, v67
	v_add_f32_e32 v138, v138, v141
	v_mul_f32_e32 v141, v69, v69
	v_fmac_f32_e32 v153, v66, v66
	v_fmac_f32_e32 v141, v68, v68
	v_add_f32_e32 v146, v153, v146
	v_add_f32_e32 v141, v141, v146
	v_and_b32_e32 v146, 64, v164
	v_add_f32_e32 v138, v141, v138
	v_xor_b32_e32 v141, 16, v164
	v_add_u32_e32 v146, 64, v146
	v_cmp_lt_i32_e32 vcc, v141, v146
	s_nop 1
	v_cndmask_b32_e32 v141, v164, v141, vcc
	v_lshlrev_b32_e32 v141, 2, v141
	v_mov_b32_e32 v141, v138
	s_nop 1
	v_permlane16_swap_b32 v141, v138
	s_waitcnt lgkmcnt(0)
	v_add_f32_e32 v138, v138, v141
	v_xor_b32_e32 v141, 32, v164
	v_cmp_lt_i32_e32 vcc, v141, v146
	s_nop 1
	v_cndmask_b32_e32 v141, v164, v141, vcc
	v_lshlrev_b32_e32 v141, 2, v141
	v_mov_b32_e32 v141, v138
	s_nop 1
	v_permlane32_swap_b32 v141, v138
	s_and_saveexec_b64 s[50:51], s[4:5]
	s_cbranch_execz .LBB0_347
	v_ashrrev_i32_e32 v159, 31, v158
	v_lshlrev_b64 v[158:159], 6, v[158:159]
	v_lshl_add_u64 v[158:159], s[48:49], 0, v[158:159]
	s_waitcnt lgkmcnt(0)
	v_add_f32_e32 v138, v138, v141
	global_store_dword v[158:159], v138, off

.LBB0_348:
	v_add_u32_e32 v158, 0x80, v152
	v_mad_i64_i32 v[166:167], s[50:51], s78, v158, 0
	v_lshl_add_u64 v[170:171], v[166:167], 1, v[156:157]
	v_cvt_pk_bf16_f32 v166, v62, v63
	v_cvt_pk_bf16_f32 v167, v64, v65
	v_cvt_pk_bf16_f32 v168, v54, v55
	v_cvt_pk_bf16_f32 v169, v56, v57
	s_and_b64 vcc, exec, s[8:9]
	global_store_dwordx4 v[170:171], v[166:169], off
	s_nop 1
	v_cvt_pk_bf16_f32 v166, v58, v59
	v_cvt_pk_bf16_f32 v167, v60, v61
	v_cvt_pk_bf16_f32 v168, v50, v51
	v_cvt_pk_bf16_f32 v169, v52, v53
	global_store_dwordx4 v[170:171], v[166:169], off offset:256
	s_cbranch_vccnz .LBB0_352
	s_waitcnt lgkmcnt(0)
	v_mul_f32_e32 v141, v63, v63
	v_mul_f32_e32 v146, v65, v65
	v_fmac_f32_e32 v141, v62, v62
	v_fmac_f32_e32 v146, v64, v64
	v_add_f32_e32 v141, v141, v146
	v_mul_f32_e32 v146, v55, v55
	v_fmac_f32_e32 v146, v54, v54
	v_add_f32_e32 v141, v146, v141
	v_mul_f32_e32 v146, v59, v59
	v_mul_f32_e32 v153, v61, v61
	v_mul_f32_e32 v138, v57, v57
	v_fmac_f32_e32 v146, v58, v58
	v_fmac_f32_e32 v153, v60, v60
	v_fmac_f32_e32 v138, v56, v56
	v_add_f32_e32 v146, v146, v153
	v_mul_f32_e32 v153, v51, v51
	v_add_f32_e32 v138, v138, v141
	v_mul_f32_e32 v141, v53, v53
	v_fmac_f32_e32 v153, v50, v50
	v_fmac_f32_e32 v141, v52, v52
	v_add_f32_e32 v146, v153, v146
	v_add_f32_e32 v141, v141, v146
	v_and_b32_e32 v146, 64, v164
	v_add_f32_e32 v138, v141, v138
	v_xor_b32_e32 v141, 16, v164
	v_add_u32_e32 v146, 64, v146
	v_cmp_lt_i32_e32 vcc, v141, v146
	s_nop 1
	v_cndmask_b32_e32 v141, v164, v141, vcc
	v_lshlrev_b32_e32 v141, 2, v141
	v_mov_b32_e32 v141, v138
	s_nop 1
	v_permlane16_swap_b32 v141, v138
	s_waitcnt lgkmcnt(0)
	v_add_f32_e32 v138, v138, v141
	v_xor_b32_e32 v141, 32, v164
	v_cmp_lt_i32_e32 vcc, v141, v146
	s_nop 1
	v_cndmask_b32_e32 v141, v164, v141, vcc
	v_lshlrev_b32_e32 v141, 2, v141
	v_mov_b32_e32 v141, v138
	s_nop 1
	v_permlane32_swap_b32 v141, v138
	s_and_saveexec_b64 s[50:51], s[4:5]
	s_cbranch_execz .LBB0_351
	v_ashrrev_i32_e32 v159, 31, v158
	v_lshlrev_b64 v[158:159], 6, v[158:159]
	v_lshl_add_u64 v[158:159], s[48:49], 0, v[158:159]
	s_waitcnt lgkmcnt(0)
	v_add_f32_e32 v138, v138, v141
	global_store_dword v[158:159], v138, off

.LBB0_352:
	v_add_u32_e32 v158, 0x90, v152
	v_mad_i64_i32 v[166:167], s[50:51], s78, v158, 0
	v_lshl_add_u64 v[170:171], v[166:167], 1, v[156:157]
	v_cvt_pk_bf16_f32 v166, v46, v47
	v_cvt_pk_bf16_f32 v167, v48, v49
	v_cvt_pk_bf16_f32 v168, v38, v39
	v_cvt_pk_bf16_f32 v169, v40, v41
	s_and_b64 vcc, exec, s[8:9]
	global_store_dwordx4 v[170:171], v[166:169], off
	s_nop 1
	v_cvt_pk_bf16_f32 v166, v42, v43
	v_cvt_pk_bf16_f32 v167, v44, v45
	v_cvt_pk_bf16_f32 v168, v34, v35
	v_cvt_pk_bf16_f32 v169, v36, v37
	global_store_dwordx4 v[170:171], v[166:169], off offset:256
	s_cbranch_vccnz .LBB0_356
	s_waitcnt lgkmcnt(0)
	v_mul_f32_e32 v141, v47, v47
	v_mul_f32_e32 v146, v49, v49
	v_fmac_f32_e32 v141, v46, v46
	v_fmac_f32_e32 v146, v48, v48
	v_add_f32_e32 v141, v141, v146
	v_mul_f32_e32 v146, v39, v39
	v_fmac_f32_e32 v146, v38, v38
	v_add_f32_e32 v141, v146, v141
	v_mul_f32_e32 v146, v43, v43
	v_mul_f32_e32 v153, v45, v45
	v_mul_f32_e32 v138, v41, v41
	v_fmac_f32_e32 v146, v42, v42
	v_fmac_f32_e32 v153, v44, v44
	v_fmac_f32_e32 v138, v40, v40
	v_add_f32_e32 v146, v146, v153
	v_mul_f32_e32 v153, v35, v35
	v_add_f32_e32 v138, v138, v141
	v_mul_f32_e32 v141, v37, v37
	v_fmac_f32_e32 v153, v34, v34
	v_fmac_f32_e32 v141, v36, v36
	v_add_f32_e32 v146, v153, v146
	v_add_f32_e32 v141, v141, v146
	v_and_b32_e32 v146, 64, v164
	v_add_f32_e32 v138, v141, v138
	v_xor_b32_e32 v141, 16, v164
	v_add_u32_e32 v146, 64, v146
	v_cmp_lt_i32_e32 vcc, v141, v146
	s_nop 1
	v_cndmask_b32_e32 v141, v164, v141, vcc
	v_lshlrev_b32_e32 v141, 2, v141
	v_mov_b32_e32 v141, v138
	s_nop 1
	v_permlane16_swap_b32 v141, v138
	s_waitcnt lgkmcnt(0)
	v_add_f32_e32 v138, v138, v141
	v_xor_b32_e32 v141, 32, v164
	v_cmp_lt_i32_e32 vcc, v141, v146
	s_nop 1
	v_cndmask_b32_e32 v141, v164, v141, vcc
	v_lshlrev_b32_e32 v141, 2, v141
	v_mov_b32_e32 v141, v138
	s_nop 1
	v_permlane32_swap_b32 v141, v138
	s_and_saveexec_b64 s[50:51], s[4:5]
	s_cbranch_execz .LBB0_355
	v_ashrrev_i32_e32 v159, 31, v158
	v_lshlrev_b64 v[158:159], 6, v[158:159]
	v_lshl_add_u64 v[158:159], s[48:49], 0, v[158:159]
	s_waitcnt lgkmcnt(0)
	v_add_f32_e32 v138, v138, v141
	global_store_dword v[158:159], v138, off

.LBB0_356:
	v_add_u32_e32 v158, 0xa0, v152
	v_mad_i64_i32 v[166:167], s[50:51], s78, v158, 0
	v_lshl_add_u64 v[170:171], v[166:167], 1, v[156:157]
	v_cvt_pk_bf16_f32 v166, v30, v31
	v_cvt_pk_bf16_f32 v167, v32, v33
	v_cvt_pk_bf16_f32 v168, v22, v23
	v_cvt_pk_bf16_f32 v169, v24, v25
	s_and_b64 vcc, exec, s[8:9]
	global_store_dwordx4 v[170:171], v[166:169], off
	s_nop 1
	v_cvt_pk_bf16_f32 v166, v26, v27
	v_cvt_pk_bf16_f32 v167, v28, v29
	v_cvt_pk_bf16_f32 v168, v18, v19
	v_cvt_pk_bf16_f32 v169, v20, v21
	global_store_dwordx4 v[170:171], v[166:169], off offset:256
	s_cbranch_vccnz .LBB0_360
	s_waitcnt lgkmcnt(0)
	v_mul_f32_e32 v141, v31, v31
	v_mul_f32_e32 v146, v33, v33
	v_fmac_f32_e32 v141, v30, v30
	v_fmac_f32_e32 v146, v32, v32
	v_add_f32_e32 v141, v141, v146
	v_mul_f32_e32 v146, v23, v23
	v_fmac_f32_e32 v146, v22, v22
	v_add_f32_e32 v141, v146, v141
	v_mul_f32_e32 v146, v27, v27
	v_mul_f32_e32 v153, v29, v29
	v_mul_f32_e32 v138, v25, v25
	v_fmac_f32_e32 v146, v26, v26
	v_fmac_f32_e32 v153, v28, v28
	v_fmac_f32_e32 v138, v24, v24
	v_add_f32_e32 v146, v146, v153
	v_mul_f32_e32 v153, v19, v19
	v_add_f32_e32 v138, v138, v141
	v_mul_f32_e32 v141, v21, v21
	v_fmac_f32_e32 v153, v18, v18
	v_fmac_f32_e32 v141, v20, v20
	v_add_f32_e32 v146, v153, v146
	v_add_f32_e32 v141, v141, v146
	v_and_b32_e32 v146, 64, v164
	v_add_f32_e32 v138, v141, v138
	v_xor_b32_e32 v141, 16, v164
	v_add_u32_e32 v146, 64, v146
	v_cmp_lt_i32_e32 vcc, v141, v146
	s_nop 1
	v_cndmask_b32_e32 v141, v164, v141, vcc
	v_lshlrev_b32_e32 v141, 2, v141
	v_mov_b32_e32 v141, v138
	s_nop 1
	v_permlane16_swap_b32 v141, v138
	s_waitcnt lgkmcnt(0)
	v_add_f32_e32 v138, v138, v141
	v_xor_b32_e32 v141, 32, v164
	v_cmp_lt_i32_e32 vcc, v141, v146
	s_nop 1
	v_cndmask_b32_e32 v141, v164, v141, vcc
	v_lshlrev_b32_e32 v141, 2, v141
	v_mov_b32_e32 v141, v138
	s_nop 1
	v_permlane32_swap_b32 v141, v138
	s_and_saveexec_b64 s[50:51], s[4:5]
	s_cbranch_execz .LBB0_359
	v_ashrrev_i32_e32 v159, 31, v158
	v_lshlrev_b64 v[158:159], 6, v[158:159]
	v_lshl_add_u64 v[158:159], s[48:49], 0, v[158:159]
	s_waitcnt lgkmcnt(0)
	v_add_f32_e32 v138, v138, v141
	global_store_dword v[158:159], v138, off

.LBB0_360:
	v_add_u32_e32 v158, 0xb0, v152
	v_mad_i64_i32 v[166:167], s[50:51], s78, v158, 0
	v_lshl_add_u64 v[156:157], v[166:167], 1, v[156:157]
	v_cvt_pk_bf16_f32 v166, v14, v15
	v_cvt_pk_bf16_f32 v167, v16, v17
	v_cvt_pk_bf16_f32 v168, v6, v7
	v_cvt_pk_bf16_f32 v169, v8, v9
	s_and_b64 vcc, exec, s[8:9]
	global_store_dwordx4 v[156:157], v[166:169], off
	s_nop 1
	v_cvt_pk_bf16_f32 v166, v10, v11
	v_cvt_pk_bf16_f32 v167, v12, v13
	v_cvt_pk_bf16_f32 v168, v2, v3
	v_cvt_pk_bf16_f32 v169, v4, v5
	global_store_dwordx4 v[156:157], v[166:169], off offset:256
	s_cbranch_vccnz .LBB0_364
	s_waitcnt lgkmcnt(0)
	v_mul_f32_e32 v141, v15, v15
	v_mul_f32_e32 v146, v17, v17
	v_fmac_f32_e32 v141, v14, v14
	v_fmac_f32_e32 v146, v16, v16
	v_add_f32_e32 v141, v141, v146
	v_mul_f32_e32 v146, v7, v7
	v_fmac_f32_e32 v146, v6, v6
	v_add_f32_e32 v141, v146, v141
	v_mul_f32_e32 v146, v11, v11
	v_mul_f32_e32 v153, v13, v13
	v_mul_f32_e32 v138, v9, v9
	v_fmac_f32_e32 v146, v10, v10
	v_fmac_f32_e32 v153, v12, v12
	v_fmac_f32_e32 v138, v8, v8
	v_add_f32_e32 v146, v146, v153
	v_mul_f32_e32 v153, v3, v3
	v_add_f32_e32 v138, v138, v141
	v_mul_f32_e32 v141, v5, v5
	v_fmac_f32_e32 v153, v2, v2
	v_fmac_f32_e32 v141, v4, v4
	v_add_f32_e32 v146, v153, v146
	v_add_f32_e32 v141, v141, v146
	v_and_b32_e32 v146, 64, v164
	v_add_f32_e32 v138, v141, v138
	v_xor_b32_e32 v141, 16, v164
	v_add_u32_e32 v146, 64, v146
	v_cmp_lt_i32_e32 vcc, v141, v146
	s_nop 1
	v_cndmask_b32_e32 v141, v164, v141, vcc
	v_lshlrev_b32_e32 v141, 2, v141
	v_mov_b32_e32 v141, v138
	s_nop 1
	v_permlane16_swap_b32 v141, v138
	s_waitcnt lgkmcnt(0)
	v_add_f32_e32 v138, v138, v141
	v_xor_b32_e32 v141, 32, v164
	v_cmp_lt_i32_e32 vcc, v141, v146
	s_nop 1
	v_cndmask_b32_e32 v141, v164, v141, vcc
	v_lshlrev_b32_e32 v141, 2, v141
	v_mov_b32_e32 v141, v138
	s_nop 1
	v_permlane32_swap_b32 v141, v138
	s_and_saveexec_b64 s[8:9], s[4:5]
	s_cbranch_execz .LBB0_363
	v_ashrrev_i32_e32 v159, 31, v158
	v_lshlrev_b64 v[156:157], 6, v[158:159]
	v_lshl_add_u64 v[156:157], s[48:49], 0, v[156:157]
	s_waitcnt lgkmcnt(0)
	v_add_f32_e32 v138, v138, v141
	global_store_dword v[156:157], v138, off

.LBB0_520:
	s_and_b64 vcc, exec, s[50:51]
	s_cbranch_vccz .LBB0_555
	s_cmp_eq_u32 s47, 4
	s_cselect_b64 s[56:57], -1, 0
	s_lshl_b32 s6, s48, 2
	s_ashr_i32 s7, s6, 31
	v_lshl_or_b32 v156, s48, 8, v162
	s_lshl_b64 s[6:7], s[6:7], 2
	v_ashrrev_i32_e32 v157, 31, v156
	s_add_u32 s50, s68, s6
	v_lshl_add_u64 v[156:157], v[156:157], 1, v[154:155]
	s_addc_u32 s51, s69, s7
	v_mad_i64_i32 v[158:159], s[6:7], s45, v152, 0
	s_cmp_lg_u32 s47, 4
	v_lshl_add_u64 v[158:159], v[158:159], 1, v[156:157]
	v_cvt_pk_bf16_f32 v166, v122, v123
	v_cvt_pk_bf16_f32 v167, v124, v125
	v_cvt_pk_bf16_f32 v168, v118, v119
	v_cvt_pk_bf16_f32 v169, v120, v121
	global_store_dwordx4 v[158:159], v[166:169], off
	s_nop 1
	v_cvt_pk_bf16_f32 v166, v126, v127
	v_cvt_pk_bf16_f32 v167, v128, v129
	v_cvt_pk_bf16_f32 v168, v114, v115
	v_cvt_pk_bf16_f32 v169, v116, v117
	global_store_dwordx4 v[158:159], v[166:169], off offset:256
	s_cbranch_scc1 .LBB0_525
	v_mul_f32_e32 v141, v123, v123
	v_mul_f32_e32 v146, v125, v125
	v_fmac_f32_e32 v141, v122, v122
	v_fmac_f32_e32 v146, v124, v124
	v_add_f32_e32 v141, v141, v146
	v_mul_f32_e32 v146, v119, v119
	v_fmac_f32_e32 v146, v118, v118
	v_add_f32_e32 v141, v146, v141
	v_mul_f32_e32 v146, v127, v127
	v_mul_f32_e32 v153, v129, v129
	v_mul_f32_e32 v138, v121, v121
	v_fmac_f32_e32 v146, v126, v126
	v_fmac_f32_e32 v153, v128, v128
	v_fmac_f32_e32 v138, v120, v120
	v_add_f32_e32 v146, v146, v153
	v_mul_f32_e32 v153, v115, v115
	v_add_f32_e32 v138, v138, v141
	v_mul_f32_e32 v141, v117, v117
	v_fmac_f32_e32 v153, v114, v114
	v_fmac_f32_e32 v141, v116, v116
	v_add_f32_e32 v146, v153, v146
	v_add_f32_e32 v141, v141, v146
	v_and_b32_e32 v146, 64, v164
	v_add_f32_e32 v138, v141, v138
	v_xor_b32_e32 v141, 16, v164
	v_add_u32_e32 v146, 64, v146
	v_cmp_lt_i32_e32 vcc, v141, v146
	s_nop 1
	v_cndmask_b32_e32 v141, v164, v141, vcc
	v_lshlrev_b32_e32 v141, 2, v141
	v_mov_b32_e32 v141, v138
	s_nop 1
	v_permlane16_swap_b32 v141, v138
	s_waitcnt lgkmcnt(0)
	v_add_f32_e32 v138, v138, v141
	v_xor_b32_e32 v141, 32, v164
	v_cmp_lt_i32_e32 vcc, v141, v146
	s_nop 1
	v_cndmask_b32_e32 v141, v164, v141, vcc
	v_lshlrev_b32_e32 v141, 2, v141
	v_mov_b32_e32 v141, v138
	s_nop 1
	v_permlane32_swap_b32 v141, v138
	s_and_saveexec_b64 s[6:7], s[4:5]
	s_cbranch_execz .LBB0_524
	v_ashrrev_i32_e32 v153, 31, v152
	v_lshlrev_b64 v[158:159], 6, v[152:153]
	v_lshl_add_u64 v[158:159], s[50:51], 0, v[158:159]
	s_waitcnt lgkmcnt(0)
	v_add_f32_e32 v138, v138, v141
	global_store_dword v[158:159], v138, off

.LBB0_525:
	v_or_b32_e32 v158, 16, v152
	v_mad_i64_i32 v[166:167], s[6:7], s45, v158, 0
	v_cndmask_b32_e64 v138, 0, 1, s[56:57]
	v_lshl_add_u64 v[170:171], v[166:167], 1, v[156:157]
	v_cvt_pk_bf16_f32 v166, v110, v111
	v_cvt_pk_bf16_f32 v167, v112, v113
	v_cvt_pk_bf16_f32 v168, v102, v103
	v_cvt_pk_bf16_f32 v169, v104, v105
	v_cmp_ne_u32_e64 s[6:7], 1, v138
	s_andn2_b64 vcc, exec, s[56:57]
	global_store_dwordx4 v[170:171], v[166:169], off
	s_nop 1
	v_cvt_pk_bf16_f32 v166, v106, v107
	v_cvt_pk_bf16_f32 v167, v108, v109
	v_cvt_pk_bf16_f32 v168, v98, v99
	v_cvt_pk_bf16_f32 v169, v100, v101
	global_store_dwordx4 v[170:171], v[166:169], off offset:256
	s_cbranch_vccnz .LBB0_529
	s_waitcnt lgkmcnt(0)
	v_mul_f32_e32 v141, v111, v111
	v_mul_f32_e32 v146, v113, v113
	v_fmac_f32_e32 v141, v110, v110
	v_fmac_f32_e32 v146, v112, v112
	v_add_f32_e32 v141, v141, v146
	v_mul_f32_e32 v146, v103, v103
	v_fmac_f32_e32 v146, v102, v102
	v_add_f32_e32 v141, v146, v141
	v_mul_f32_e32 v146, v107, v107
	v_mul_f32_e32 v153, v109, v109
	v_mul_f32_e32 v138, v105, v105
	v_fmac_f32_e32 v146, v106, v106
	v_fmac_f32_e32 v153, v108, v108
	v_fmac_f32_e32 v138, v104, v104
	v_add_f32_e32 v146, v146, v153
	v_mul_f32_e32 v153, v99, v99
	v_add_f32_e32 v138, v138, v141
	v_mul_f32_e32 v141, v101, v101
	v_fmac_f32_e32 v153, v98, v98
	v_fmac_f32_e32 v141, v100, v100
	v_add_f32_e32 v146, v153, v146
	v_add_f32_e32 v141, v141, v146
	v_and_b32_e32 v146, 64, v164
	v_add_f32_e32 v138, v141, v138
	v_xor_b32_e32 v141, 16, v164
	v_add_u32_e32 v146, 64, v146
	v_cmp_lt_i32_e32 vcc, v141, v146
	s_nop 1
	v_cndmask_b32_e32 v141, v164, v141, vcc
	v_lshlrev_b32_e32 v141, 2, v141
	v_mov_b32_e32 v141, v138
	s_nop 1
	v_permlane16_swap_b32 v141, v138
	s_waitcnt lgkmcnt(0)
	v_add_f32_e32 v138, v138, v141
	v_xor_b32_e32 v141, 32, v164
	v_cmp_lt_i32_e32 vcc, v141, v146
	s_nop 1
	v_cndmask_b32_e32 v141, v164, v141, vcc
	v_lshlrev_b32_e32 v141, 2, v141
	v_mov_b32_e32 v141, v138
	s_nop 1
	v_permlane32_swap_b32 v141, v138
	s_and_saveexec_b64 s[56:57], s[4:5]
	s_cbranch_execz .LBB0_528
	v_ashrrev_i32_e32 v159, 31, v158
	v_lshlrev_b64 v[158:159], 6, v[158:159]
	v_lshl_add_u64 v[158:159], s[50:51], 0, v[158:159]
	s_waitcnt lgkmcnt(0)
	v_add_f32_e32 v138, v138, v141
	global_store_dword v[158:159], v138, off

.LBB0_529:
	v_or_b32_e32 v158, 32, v152
	v_mad_i64_i32 v[166:167], s[56:57], s45, v158, 0
	v_lshl_add_u64 v[170:171], v[166:167], 1, v[156:157]
	v_cvt_pk_bf16_f32 v166, v94, v95
	v_cvt_pk_bf16_f32 v167, v96, v97
	v_cvt_pk_bf16_f32 v168, v86, v87
	v_cvt_pk_bf16_f32 v169, v88, v89
	s_and_b64 vcc, exec, s[6:7]
	global_store_dwordx4 v[170:171], v[166:169], off
	s_nop 1
	v_cvt_pk_bf16_f32 v166, v90, v91
	v_cvt_pk_bf16_f32 v167, v92, v93
	v_cvt_pk_bf16_f32 v168, v82, v83
	v_cvt_pk_bf16_f32 v169, v84, v85
	global_store_dwordx4 v[170:171], v[166:169], off offset:256
	s_cbranch_vccnz .LBB0_533
	s_waitcnt lgkmcnt(0)
	v_mul_f32_e32 v141, v95, v95
	v_mul_f32_e32 v146, v97, v97
	v_fmac_f32_e32 v141, v94, v94
	v_fmac_f32_e32 v146, v96, v96
	v_add_f32_e32 v141, v141, v146
	v_mul_f32_e32 v146, v87, v87
	v_fmac_f32_e32 v146, v86, v86
	v_add_f32_e32 v141, v146, v141
	v_mul_f32_e32 v146, v91, v91
	v_mul_f32_e32 v153, v93, v93
	v_mul_f32_e32 v138, v89, v89
	v_fmac_f32_e32 v146, v90, v90
	v_fmac_f32_e32 v153, v92, v92
	v_fmac_f32_e32 v138, v88, v88
	v_add_f32_e32 v146, v146, v153
	v_mul_f32_e32 v153, v83, v83
	v_add_f32_e32 v138, v138, v141
	v_mul_f32_e32 v141, v85, v85
	v_fmac_f32_e32 v153, v82, v82
	v_fmac_f32_e32 v141, v84, v84
	v_add_f32_e32 v146, v153, v146
	v_add_f32_e32 v141, v141, v146
	v_and_b32_e32 v146, 64, v164
	v_add_f32_e32 v138, v141, v138
	v_xor_b32_e32 v141, 16, v164
	v_add_u32_e32 v146, 64, v146
	v_cmp_lt_i32_e32 vcc, v141, v146
	s_nop 1
	v_cndmask_b32_e32 v141, v164, v141, vcc
	v_lshlrev_b32_e32 v141, 2, v141
	v_mov_b32_e32 v141, v138
	s_nop 1
	v_permlane16_swap_b32 v141, v138
	s_waitcnt lgkmcnt(0)
	v_add_f32_e32 v138, v138, v141
	v_xor_b32_e32 v141, 32, v164
	v_cmp_lt_i32_e32 vcc, v141, v146
	s_nop 1
	v_cndmask_b32_e32 v141, v164, v141, vcc
	v_lshlrev_b32_e32 v141, 2, v141
	v_mov_b32_e32 v141, v138
	s_nop 1
	v_permlane32_swap_b32 v141, v138
	s_and_saveexec_b64 s[56:57], s[4:5]
	s_cbranch_execz .LBB0_532
	v_ashrrev_i32_e32 v159, 31, v158
	v_lshlrev_b64 v[158:159], 6, v[158:159]
	v_lshl_add_u64 v[158:159], s[50:51], 0, v[158:159]
	s_waitcnt lgkmcnt(0)
	v_add_f32_e32 v138, v138, v141
	global_store_dword v[158:159], v138, off

.LBB0_533:
	v_or_b32_e32 v158, 48, v152
	v_mad_i64_i32 v[166:167], s[56:57], s45, v158, 0
	v_lshl_add_u64 v[170:171], v[166:167], 1, v[156:157]
	v_cvt_pk_bf16_f32 v166, v78, v79
	v_cvt_pk_bf16_f32 v167, v80, v81
	v_cvt_pk_bf16_f32 v168, v70, v71
	v_cvt_pk_bf16_f32 v169, v72, v73
	s_and_b64 vcc, exec, s[6:7]
	global_store_dwordx4 v[170:171], v[166:169], off
	s_nop 1
	v_cvt_pk_bf16_f32 v166, v74, v75
	v_cvt_pk_bf16_f32 v167, v76, v77
	v_cvt_pk_bf16_f32 v168, v66, v67
	v_cvt_pk_bf16_f32 v169, v68, v69
	global_store_dwordx4 v[170:171], v[166:169], off offset:256
	s_cbranch_vccnz .LBB0_537
	s_waitcnt lgkmcnt(0)
	v_mul_f32_e32 v141, v79, v79
	v_mul_f32_e32 v146, v81, v81
	v_fmac_f32_e32 v141, v78, v78
	v_fmac_f32_e32 v146, v80, v80
	v_add_f32_e32 v141, v141, v146
	v_mul_f32_e32 v146, v71, v71
	v_fmac_f32_e32 v146, v70, v70
	v_add_f32_e32 v141, v146, v141
	v_mul_f32_e32 v146, v75, v75
	v_mul_f32_e32 v153, v77, v77
	v_mul_f32_e32 v138, v73, v73
	v_fmac_f32_e32 v146, v74, v74
	v_fmac_f32_e32 v153, v76, v76
	v_fmac_f32_e32 v138, v72, v72
	v_add_f32_e32 v146, v146, v153
	v_mul_f32_e32 v153, v67, v67
	v_add_f32_e32 v138, v138, v141
	v_mul_f32_e32 v141, v69, v69
	v_fmac_f32_e32 v153, v66, v66
	v_fmac_f32_e32 v141, v68, v68
	v_add_f32_e32 v146, v153, v146
	v_add_f32_e32 v141, v141, v146
	v_and_b32_e32 v146, 64, v164
	v_add_f32_e32 v138, v141, v138
	v_xor_b32_e32 v141, 16, v164
	v_add_u32_e32 v146, 64, v146
	v_cmp_lt_i32_e32 vcc, v141, v146
	s_nop 1
	v_cndmask_b32_e32 v141, v164, v141, vcc
	v_lshlrev_b32_e32 v141, 2, v141
	v_mov_b32_e32 v141, v138
	s_nop 1
	v_permlane16_swap_b32 v141, v138
	s_waitcnt lgkmcnt(0)
	v_add_f32_e32 v138, v138, v141
	v_xor_b32_e32 v141, 32, v164
	v_cmp_lt_i32_e32 vcc, v141, v146
	s_nop 1
	v_cndmask_b32_e32 v141, v164, v141, vcc
	v_lshlrev_b32_e32 v141, 2, v141
	v_mov_b32_e32 v141, v138
	s_nop 1
	v_permlane32_swap_b32 v141, v138
	s_and_saveexec_b64 s[56:57], s[4:5]
	s_cbranch_execz .LBB0_536
	v_ashrrev_i32_e32 v159, 31, v158
	v_lshlrev_b64 v[158:159], 6, v[158:159]
	v_lshl_add_u64 v[158:159], s[50:51], 0, v[158:159]
	s_waitcnt lgkmcnt(0)
	v_add_f32_e32 v138, v138, v141
	global_store_dword v[158:159], v138, off

.LBB0_537:
	v_add_u32_e32 v158, 0x80, v152
	v_mad_i64_i32 v[166:167], s[56:57], s45, v158, 0
	v_lshl_add_u64 v[170:171], v[166:167], 1, v[156:157]
	v_cvt_pk_bf16_f32 v166, v62, v63
	v_cvt_pk_bf16_f32 v167, v64, v65
	v_cvt_pk_bf16_f32 v168, v54, v55
	v_cvt_pk_bf16_f32 v169, v56, v57
	s_and_b64 vcc, exec, s[6:7]
	global_store_dwordx4 v[170:171], v[166:169], off
	s_nop 1
	v_cvt_pk_bf16_f32 v166, v58, v59
	v_cvt_pk_bf16_f32 v167, v60, v61
	v_cvt_pk_bf16_f32 v168, v50, v51
	v_cvt_pk_bf16_f32 v169, v52, v53
	global_store_dwordx4 v[170:171], v[166:169], off offset:256
	s_cbranch_vccnz .LBB0_541
	s_waitcnt lgkmcnt(0)
	v_mul_f32_e32 v141, v63, v63
	v_mul_f32_e32 v146, v65, v65
	v_fmac_f32_e32 v141, v62, v62
	v_fmac_f32_e32 v146, v64, v64
	v_add_f32_e32 v141, v141, v146
	v_mul_f32_e32 v146, v55, v55
	v_fmac_f32_e32 v146, v54, v54
	v_add_f32_e32 v141, v146, v141
	v_mul_f32_e32 v146, v59, v59
	v_mul_f32_e32 v153, v61, v61
	v_mul_f32_e32 v138, v57, v57
	v_fmac_f32_e32 v146, v58, v58
	v_fmac_f32_e32 v153, v60, v60
	v_fmac_f32_e32 v138, v56, v56
	v_add_f32_e32 v146, v146, v153
	v_mul_f32_e32 v153, v51, v51
	v_add_f32_e32 v138, v138, v141
	v_mul_f32_e32 v141, v53, v53
	v_fmac_f32_e32 v153, v50, v50
	v_fmac_f32_e32 v141, v52, v52
	v_add_f32_e32 v146, v153, v146
	v_add_f32_e32 v141, v141, v146
	v_and_b32_e32 v146, 64, v164
	v_add_f32_e32 v138, v141, v138
	v_xor_b32_e32 v141, 16, v164
	v_add_u32_e32 v146, 64, v146
	v_cmp_lt_i32_e32 vcc, v141, v146
	s_nop 1
	v_cndmask_b32_e32 v141, v164, v141, vcc
	v_lshlrev_b32_e32 v141, 2, v141
	v_mov_b32_e32 v141, v138
	s_nop 1
	v_permlane16_swap_b32 v141, v138
	s_waitcnt lgkmcnt(0)
	v_add_f32_e32 v138, v138, v141
	v_xor_b32_e32 v141, 32, v164
	v_cmp_lt_i32_e32 vcc, v141, v146
	s_nop 1
	v_cndmask_b32_e32 v141, v164, v141, vcc
	v_lshlrev_b32_e32 v141, 2, v141
	v_mov_b32_e32 v141, v138
	s_nop 1
	v_permlane32_swap_b32 v141, v138
	s_and_saveexec_b64 s[56:57], s[4:5]
	s_cbranch_execz .LBB0_540
	v_ashrrev_i32_e32 v159, 31, v158
	v_lshlrev_b64 v[158:159], 6, v[158:159]
	v_lshl_add_u64 v[158:159], s[50:51], 0, v[158:159]
	s_waitcnt lgkmcnt(0)
	v_add_f32_e32 v138, v138, v141
	global_store_dword v[158:159], v138, off

.LBB0_541:
	v_add_u32_e32 v158, 0x90, v152
	v_mad_i64_i32 v[166:167], s[56:57], s45, v158, 0
	v_lshl_add_u64 v[170:171], v[166:167], 1, v[156:157]
	v_cvt_pk_bf16_f32 v166, v46, v47
	v_cvt_pk_bf16_f32 v167, v48, v49
	v_cvt_pk_bf16_f32 v168, v38, v39
	v_cvt_pk_bf16_f32 v169, v40, v41
	s_and_b64 vcc, exec, s[6:7]
	global_store_dwordx4 v[170:171], v[166:169], off
	s_nop 1
	v_cvt_pk_bf16_f32 v166, v42, v43
	v_cvt_pk_bf16_f32 v167, v44, v45
	v_cvt_pk_bf16_f32 v168, v34, v35
	v_cvt_pk_bf16_f32 v169, v36, v37
	global_store_dwordx4 v[170:171], v[166:169], off offset:256
	s_cbranch_vccnz .LBB0_545
	s_waitcnt lgkmcnt(0)
	v_mul_f32_e32 v141, v47, v47
	v_mul_f32_e32 v146, v49, v49
	v_fmac_f32_e32 v141, v46, v46
	v_fmac_f32_e32 v146, v48, v48
	v_add_f32_e32 v141, v141, v146
	v_mul_f32_e32 v146, v39, v39
	v_fmac_f32_e32 v146, v38, v38
	v_add_f32_e32 v141, v146, v141
	v_mul_f32_e32 v146, v43, v43
	v_mul_f32_e32 v153, v45, v45
	v_mul_f32_e32 v138, v41, v41
	v_fmac_f32_e32 v146, v42, v42
	v_fmac_f32_e32 v153, v44, v44
	v_fmac_f32_e32 v138, v40, v40
	v_add_f32_e32 v146, v146, v153
	v_mul_f32_e32 v153, v35, v35
	v_add_f32_e32 v138, v138, v141
	v_mul_f32_e32 v141, v37, v37
	v_fmac_f32_e32 v153, v34, v34
	v_fmac_f32_e32 v141, v36, v36
	v_add_f32_e32 v146, v153, v146
	v_add_f32_e32 v141, v141, v146
	v_and_b32_e32 v146, 64, v164
	v_add_f32_e32 v138, v141, v138
	v_xor_b32_e32 v141, 16, v164
	v_add_u32_e32 v146, 64, v146
	v_cmp_lt_i32_e32 vcc, v141, v146
	s_nop 1
	v_cndmask_b32_e32 v141, v164, v141, vcc
	v_lshlrev_b32_e32 v141, 2, v141
	v_mov_b32_e32 v141, v138
	s_nop 1
	v_permlane16_swap_b32 v141, v138
	s_waitcnt lgkmcnt(0)
	v_add_f32_e32 v138, v138, v141
	v_xor_b32_e32 v141, 32, v164
	v_cmp_lt_i32_e32 vcc, v141, v146
	s_nop 1
	v_cndmask_b32_e32 v141, v164, v141, vcc
	v_lshlrev_b32_e32 v141, 2, v141
	v_mov_b32_e32 v141, v138
	s_nop 1
	v_permlane32_swap_b32 v141, v138
	s_and_saveexec_b64 s[56:57], s[4:5]
	s_cbranch_execz .LBB0_544
	v_ashrrev_i32_e32 v159, 31, v158
	v_lshlrev_b64 v[158:159], 6, v[158:159]
	v_lshl_add_u64 v[158:159], s[50:51], 0, v[158:159]
	s_waitcnt lgkmcnt(0)
	v_add_f32_e32 v138, v138, v141
	global_store_dword v[158:159], v138, off

.LBB0_545:
	v_add_u32_e32 v158, 0xa0, v152
	v_mad_i64_i32 v[166:167], s[56:57], s45, v158, 0
	v_lshl_add_u64 v[170:171], v[166:167], 1, v[156:157]
	v_cvt_pk_bf16_f32 v166, v30, v31
	v_cvt_pk_bf16_f32 v167, v32, v33
	v_cvt_pk_bf16_f32 v168, v22, v23
	v_cvt_pk_bf16_f32 v169, v24, v25
	s_and_b64 vcc, exec, s[6:7]
	global_store_dwordx4 v[170:171], v[166:169], off
	s_nop 1
	v_cvt_pk_bf16_f32 v166, v26, v27
	v_cvt_pk_bf16_f32 v167, v28, v29
	v_cvt_pk_bf16_f32 v168, v18, v19
	v_cvt_pk_bf16_f32 v169, v20, v21
	global_store_dwordx4 v[170:171], v[166:169], off offset:256
	s_cbranch_vccnz .LBB0_549
	s_waitcnt lgkmcnt(0)
	v_mul_f32_e32 v141, v31, v31
	v_mul_f32_e32 v146, v33, v33
	v_fmac_f32_e32 v141, v30, v30
	v_fmac_f32_e32 v146, v32, v32
	v_add_f32_e32 v141, v141, v146
	v_mul_f32_e32 v146, v23, v23
	v_fmac_f32_e32 v146, v22, v22
	v_add_f32_e32 v141, v146, v141
	v_mul_f32_e32 v146, v27, v27
	v_mul_f32_e32 v153, v29, v29
	v_mul_f32_e32 v138, v25, v25
	v_fmac_f32_e32 v146, v26, v26
	v_fmac_f32_e32 v153, v28, v28
	v_fmac_f32_e32 v138, v24, v24
	v_add_f32_e32 v146, v146, v153
	v_mul_f32_e32 v153, v19, v19
	v_add_f32_e32 v138, v138, v141
	v_mul_f32_e32 v141, v21, v21
	v_fmac_f32_e32 v153, v18, v18
	v_fmac_f32_e32 v141, v20, v20
	v_add_f32_e32 v146, v153, v146
	v_add_f32_e32 v141, v141, v146
	v_and_b32_e32 v146, 64, v164
	v_add_f32_e32 v138, v141, v138
	v_xor_b32_e32 v141, 16, v164
	v_add_u32_e32 v146, 64, v146
	v_cmp_lt_i32_e32 vcc, v141, v146
	s_nop 1
	v_cndmask_b32_e32 v141, v164, v141, vcc
	v_lshlrev_b32_e32 v141, 2, v141
	v_mov_b32_e32 v141, v138
	s_nop 1
	v_permlane16_swap_b32 v141, v138
	s_waitcnt lgkmcnt(0)
	v_add_f32_e32 v138, v138, v141
	v_xor_b32_e32 v141, 32, v164
	v_cmp_lt_i32_e32 vcc, v141, v146
	s_nop 1
	v_cndmask_b32_e32 v141, v164, v141, vcc
	v_lshlrev_b32_e32 v141, 2, v141
	v_mov_b32_e32 v141, v138
	s_nop 1
	v_permlane32_swap_b32 v141, v138
	s_and_saveexec_b64 s[56:57], s[4:5]
	s_cbranch_execz .LBB0_548
	v_ashrrev_i32_e32 v159, 31, v158
	v_lshlrev_b64 v[158:159], 6, v[158:159]
	v_lshl_add_u64 v[158:159], s[50:51], 0, v[158:159]
	s_waitcnt lgkmcnt(0)
	v_add_f32_e32 v138, v138, v141
	global_store_dword v[158:159], v138, off

.LBB0_549:
	v_add_u32_e32 v158, 0xb0, v152
	v_mad_i64_i32 v[166:167], s[56:57], s45, v158, 0
	v_lshl_add_u64 v[156:157], v[166:167], 1, v[156:157]
	v_cvt_pk_bf16_f32 v166, v14, v15
	v_cvt_pk_bf16_f32 v167, v16, v17
	v_cvt_pk_bf16_f32 v168, v6, v7
	v_cvt_pk_bf16_f32 v169, v8, v9
	s_and_b64 vcc, exec, s[6:7]
	global_store_dwordx4 v[156:157], v[166:169], off
	s_nop 1
	v_cvt_pk_bf16_f32 v166, v10, v11
	v_cvt_pk_bf16_f32 v167, v12, v13
	v_cvt_pk_bf16_f32 v168, v2, v3
	v_cvt_pk_bf16_f32 v169, v4, v5
	global_store_dwordx4 v[156:157], v[166:169], off offset:256
	s_cbranch_vccnz .LBB0_553
	s_waitcnt lgkmcnt(0)
	v_mul_f32_e32 v141, v15, v15
	v_mul_f32_e32 v146, v17, v17
	v_fmac_f32_e32 v141, v14, v14
	v_fmac_f32_e32 v146, v16, v16
	v_add_f32_e32 v141, v141, v146
	v_mul_f32_e32 v146, v7, v7
	v_fmac_f32_e32 v146, v6, v6
	v_add_f32_e32 v141, v146, v141
	v_mul_f32_e32 v146, v11, v11
	v_mul_f32_e32 v153, v13, v13
	v_mul_f32_e32 v138, v9, v9
	v_fmac_f32_e32 v146, v10, v10
	v_fmac_f32_e32 v153, v12, v12
	v_fmac_f32_e32 v138, v8, v8
	v_add_f32_e32 v146, v146, v153
	v_mul_f32_e32 v153, v3, v3
	v_add_f32_e32 v138, v138, v141
	v_mul_f32_e32 v141, v5, v5
	v_fmac_f32_e32 v153, v2, v2
	v_fmac_f32_e32 v141, v4, v4
	v_add_f32_e32 v146, v153, v146
	v_add_f32_e32 v141, v141, v146
	v_and_b32_e32 v146, 64, v164
	v_add_f32_e32 v138, v141, v138
	v_xor_b32_e32 v141, 16, v164
	v_add_u32_e32 v146, 64, v146
	v_cmp_lt_i32_e32 vcc, v141, v146
	s_nop 1
	v_cndmask_b32_e32 v141, v164, v141, vcc
	v_lshlrev_b32_e32 v141, 2, v141
	v_mov_b32_e32 v141, v138
	s_nop 1
	v_permlane16_swap_b32 v141, v138
	s_waitcnt lgkmcnt(0)
	v_add_f32_e32 v138, v138, v141
	v_xor_b32_e32 v141, 32, v164
	v_cmp_lt_i32_e32 vcc, v141, v146
	s_nop 1
	v_cndmask_b32_e32 v141, v164, v141, vcc
	v_lshlrev_b32_e32 v141, 2, v141
	v_mov_b32_e32 v141, v138
	s_nop 1
	v_permlane32_swap_b32 v141, v138
	s_and_saveexec_b64 s[6:7], s[4:5]
	s_cbranch_execz .LBB0_552
	v_ashrrev_i32_e32 v159, 31, v158
	v_lshlrev_b64 v[156:157], 6, v[158:159]
	v_lshl_add_u64 v[156:157], s[50:51], 0, v[156:157]
	s_waitcnt lgkmcnt(0)
	v_add_f32_e32 v138, v138, v141
	global_store_dword v[156:157], v138, off

.LBB0_789:
	s_and_b64 vcc, exec, s[50:51]
	s_cbranch_vccz .LBB0_824
	s_cmp_eq_u32 s47, 4
	s_cselect_b64 s[56:57], -1, 0
	s_lshl_b32 s6, s48, 2
	s_ashr_i32 s7, s6, 31
	v_lshl_or_b32 v154, s48, 8, v159
	s_lshl_b64 s[6:7], s[6:7], 2
	v_ashrrev_i32_e32 v155, 31, v154
	s_add_u32 s50, s68, s6
	v_lshl_add_u64 v[154:155], v[154:155], 1, v[152:153]
	s_addc_u32 s51, s69, s7
	v_mad_i64_i32 v[156:157], s[6:7], s45, v150, 0
	s_cmp_lg_u32 s47, 4
	v_lshl_add_u64 v[156:157], v[156:157], 1, v[154:155]
	v_cvt_pk_bf16_f32 v164, v122, v123
	v_cvt_pk_bf16_f32 v165, v124, v125
	v_cvt_pk_bf16_f32 v166, v118, v119
	v_cvt_pk_bf16_f32 v167, v120, v121
	global_store_dwordx4 v[156:157], v[164:167], off
	s_nop 1
	v_cvt_pk_bf16_f32 v164, v126, v127
	v_cvt_pk_bf16_f32 v165, v128, v129
	v_cvt_pk_bf16_f32 v166, v114, v115
	v_cvt_pk_bf16_f32 v167, v116, v117
	global_store_dwordx4 v[156:157], v[164:167], off offset:256
	s_cbranch_scc1 .LBB0_794
	v_mul_f32_e32 v151, v123, v123
	v_mul_f32_e32 v156, v125, v125
	v_fmac_f32_e32 v151, v122, v122
	v_fmac_f32_e32 v156, v124, v124
	v_add_f32_e32 v151, v151, v156
	v_mul_f32_e32 v156, v119, v119
	v_fmac_f32_e32 v156, v118, v118
	v_add_f32_e32 v151, v156, v151
	v_mul_f32_e32 v156, v127, v127
	v_mul_f32_e32 v157, v129, v129
	v_mul_f32_e32 v138, v121, v121
	v_fmac_f32_e32 v156, v126, v126
	v_fmac_f32_e32 v157, v128, v128
	v_fmac_f32_e32 v138, v120, v120
	v_add_f32_e32 v156, v156, v157
	v_mul_f32_e32 v157, v115, v115
	v_add_f32_e32 v138, v138, v151
	v_mul_f32_e32 v151, v117, v117
	v_fmac_f32_e32 v157, v114, v114
	v_fmac_f32_e32 v151, v116, v116
	v_add_f32_e32 v156, v157, v156
	v_add_f32_e32 v151, v151, v156
	v_and_b32_e32 v156, 64, v161
	v_add_f32_e32 v138, v151, v138
	v_xor_b32_e32 v151, 16, v161
	v_add_u32_e32 v156, 64, v156
	v_cmp_lt_i32_e32 vcc, v151, v156
	s_nop 1
	v_cndmask_b32_e32 v151, v161, v151, vcc
	v_lshlrev_b32_e32 v151, 2, v151
	v_mov_b32_e32 v151, v138
	s_nop 1
	v_permlane16_swap_b32 v151, v138
	s_waitcnt lgkmcnt(0)
	v_add_f32_e32 v138, v138, v151
	v_xor_b32_e32 v151, 32, v161
	v_cmp_lt_i32_e32 vcc, v151, v156
	s_nop 1
	v_cndmask_b32_e32 v151, v161, v151, vcc
	v_lshlrev_b32_e32 v151, 2, v151
	v_mov_b32_e32 v156, v138
	s_nop 1
	v_permlane32_swap_b32 v156, v138
	s_and_saveexec_b64 s[6:7], s[4:5]
	s_cbranch_execz .LBB0_793
	v_ashrrev_i32_e32 v151, 31, v150
	s_waitcnt lgkmcnt(0)
	v_add_f32_e32 v138, v138, v156
	v_lshlrev_b64 v[156:157], 6, v[150:151]
	v_lshl_add_u64 v[156:157], s[50:51], 0, v[156:157]
	global_store_dword v[156:157], v138, off

.LBB0_794:
	s_waitcnt lgkmcnt(0)
	v_or_b32_e32 v156, 16, v150
	v_mad_i64_i32 v[164:165], s[6:7], s45, v156, 0
	v_cndmask_b32_e64 v138, 0, 1, s[56:57]
	v_lshl_add_u64 v[168:169], v[164:165], 1, v[154:155]
	v_cvt_pk_bf16_f32 v164, v110, v111
	v_cvt_pk_bf16_f32 v165, v112, v113
	v_cvt_pk_bf16_f32 v166, v102, v103
	v_cvt_pk_bf16_f32 v167, v104, v105
	v_cmp_ne_u32_e64 s[6:7], 1, v138
	s_andn2_b64 vcc, exec, s[56:57]
	global_store_dwordx4 v[168:169], v[164:167], off
	s_nop 1
	v_cvt_pk_bf16_f32 v164, v106, v107
	v_cvt_pk_bf16_f32 v165, v108, v109
	v_cvt_pk_bf16_f32 v166, v98, v99
	v_cvt_pk_bf16_f32 v167, v100, v101
	global_store_dwordx4 v[168:169], v[164:167], off offset:256
	s_cbranch_vccnz .LBB0_798
	v_mul_f32_e32 v151, v111, v111
	v_mul_f32_e32 v157, v113, v113
	v_fmac_f32_e32 v151, v110, v110
	v_fmac_f32_e32 v157, v112, v112
	v_add_f32_e32 v151, v151, v157
	v_mul_f32_e32 v157, v103, v103
	v_fmac_f32_e32 v157, v102, v102
	v_add_f32_e32 v151, v157, v151
	v_mul_f32_e32 v157, v107, v107
	v_mul_f32_e32 v163, v109, v109
	v_mul_f32_e32 v138, v105, v105
	v_fmac_f32_e32 v157, v106, v106
	v_fmac_f32_e32 v163, v108, v108
	v_fmac_f32_e32 v138, v104, v104
	v_add_f32_e32 v157, v157, v163
	v_mul_f32_e32 v163, v99, v99
	v_add_f32_e32 v138, v138, v151
	v_mul_f32_e32 v151, v101, v101
	v_fmac_f32_e32 v163, v98, v98
	v_fmac_f32_e32 v151, v100, v100
	v_add_f32_e32 v157, v163, v157
	v_add_f32_e32 v151, v151, v157
	v_and_b32_e32 v157, 64, v161
	v_add_f32_e32 v138, v151, v138
	v_xor_b32_e32 v151, 16, v161
	v_add_u32_e32 v157, 64, v157
	v_cmp_lt_i32_e32 vcc, v151, v157
	s_nop 1
	v_cndmask_b32_e32 v151, v161, v151, vcc
	v_lshlrev_b32_e32 v151, 2, v151
	v_mov_b32_e32 v151, v138
	s_nop 1
	v_permlane16_swap_b32 v151, v138
	s_waitcnt lgkmcnt(0)
	v_add_f32_e32 v138, v138, v151
	v_xor_b32_e32 v151, 32, v161
	v_cmp_lt_i32_e32 vcc, v151, v157
	s_nop 1
	v_cndmask_b32_e32 v151, v161, v151, vcc
	v_lshlrev_b32_e32 v151, 2, v151
	v_mov_b32_e32 v151, v138
	s_nop 1
	v_permlane32_swap_b32 v151, v138
	s_and_saveexec_b64 s[56:57], s[4:5]
	s_cbranch_execz .LBB0_797
	v_ashrrev_i32_e32 v157, 31, v156
	v_lshlrev_b64 v[156:157], 6, v[156:157]
	s_waitcnt lgkmcnt(0)
	v_add_f32_e32 v138, v138, v151
	v_lshl_add_u64 v[156:157], s[50:51], 0, v[156:157]
	global_store_dword v[156:157], v138, off

.LBB0_798:
	v_or_b32_e32 v156, 32, v150
	v_mad_i64_i32 v[164:165], s[56:57], s45, v156, 0
	v_lshl_add_u64 v[168:169], v[164:165], 1, v[154:155]
	v_cvt_pk_bf16_f32 v164, v94, v95
	v_cvt_pk_bf16_f32 v165, v96, v97
	v_cvt_pk_bf16_f32 v166, v86, v87
	v_cvt_pk_bf16_f32 v167, v88, v89
	s_and_b64 vcc, exec, s[6:7]
	global_store_dwordx4 v[168:169], v[164:167], off
	s_nop 1
	v_cvt_pk_bf16_f32 v164, v90, v91
	v_cvt_pk_bf16_f32 v165, v92, v93
	v_cvt_pk_bf16_f32 v166, v82, v83
	v_cvt_pk_bf16_f32 v167, v84, v85
	global_store_dwordx4 v[168:169], v[164:167], off offset:256
	s_cbranch_vccnz .LBB0_802
	s_waitcnt lgkmcnt(0)
	v_mul_f32_e32 v151, v95, v95
	v_mul_f32_e32 v157, v97, v97
	v_fmac_f32_e32 v151, v94, v94
	v_fmac_f32_e32 v157, v96, v96
	v_add_f32_e32 v151, v151, v157
	v_mul_f32_e32 v157, v87, v87
	v_fmac_f32_e32 v157, v86, v86
	v_add_f32_e32 v151, v157, v151
	v_mul_f32_e32 v157, v91, v91
	v_mul_f32_e32 v163, v93, v93
	v_mul_f32_e32 v138, v89, v89
	v_fmac_f32_e32 v157, v90, v90
	v_fmac_f32_e32 v163, v92, v92
	v_fmac_f32_e32 v138, v88, v88
	v_add_f32_e32 v157, v157, v163
	v_mul_f32_e32 v163, v83, v83
	v_add_f32_e32 v138, v138, v151
	v_mul_f32_e32 v151, v85, v85
	v_fmac_f32_e32 v163, v82, v82
	v_fmac_f32_e32 v151, v84, v84
	v_add_f32_e32 v157, v163, v157
	v_add_f32_e32 v151, v151, v157
	v_and_b32_e32 v157, 64, v161
	v_add_f32_e32 v138, v151, v138
	v_xor_b32_e32 v151, 16, v161
	v_add_u32_e32 v157, 64, v157
	v_cmp_lt_i32_e32 vcc, v151, v157
	s_nop 1
	v_cndmask_b32_e32 v151, v161, v151, vcc
	v_lshlrev_b32_e32 v151, 2, v151
	v_mov_b32_e32 v151, v138
	s_nop 1
	v_permlane16_swap_b32 v151, v138
	s_waitcnt lgkmcnt(0)
	v_add_f32_e32 v138, v138, v151
	v_xor_b32_e32 v151, 32, v161
	v_cmp_lt_i32_e32 vcc, v151, v157
	s_nop 1
	v_cndmask_b32_e32 v151, v161, v151, vcc
	v_lshlrev_b32_e32 v151, 2, v151
	v_mov_b32_e32 v151, v138
	s_nop 1
	v_permlane32_swap_b32 v151, v138
	s_and_saveexec_b64 s[56:57], s[4:5]
	s_cbranch_execz .LBB0_801
	v_ashrrev_i32_e32 v157, 31, v156
	v_lshlrev_b64 v[156:157], 6, v[156:157]
	s_waitcnt lgkmcnt(0)
	v_add_f32_e32 v138, v138, v151
	v_lshl_add_u64 v[156:157], s[50:51], 0, v[156:157]
	global_store_dword v[156:157], v138, off

.LBB0_802:
	v_or_b32_e32 v156, 48, v150
	v_mad_i64_i32 v[164:165], s[56:57], s45, v156, 0
	v_lshl_add_u64 v[168:169], v[164:165], 1, v[154:155]
	v_cvt_pk_bf16_f32 v164, v78, v79
	v_cvt_pk_bf16_f32 v165, v80, v81
	v_cvt_pk_bf16_f32 v166, v70, v71
	v_cvt_pk_bf16_f32 v167, v72, v73
	s_and_b64 vcc, exec, s[6:7]
	global_store_dwordx4 v[168:169], v[164:167], off
	s_nop 1
	v_cvt_pk_bf16_f32 v164, v74, v75
	v_cvt_pk_bf16_f32 v165, v76, v77
	v_cvt_pk_bf16_f32 v166, v66, v67
	v_cvt_pk_bf16_f32 v167, v68, v69
	global_store_dwordx4 v[168:169], v[164:167], off offset:256
	s_cbranch_vccnz .LBB0_806
	s_waitcnt lgkmcnt(0)
	v_mul_f32_e32 v151, v79, v79
	v_mul_f32_e32 v157, v81, v81
	v_fmac_f32_e32 v151, v78, v78
	v_fmac_f32_e32 v157, v80, v80
	v_add_f32_e32 v151, v151, v157
	v_mul_f32_e32 v157, v71, v71
	v_fmac_f32_e32 v157, v70, v70
	v_add_f32_e32 v151, v157, v151
	v_mul_f32_e32 v157, v75, v75
	v_mul_f32_e32 v163, v77, v77
	v_mul_f32_e32 v138, v73, v73
	v_fmac_f32_e32 v157, v74, v74
	v_fmac_f32_e32 v163, v76, v76
	v_fmac_f32_e32 v138, v72, v72
	v_add_f32_e32 v157, v157, v163
	v_mul_f32_e32 v163, v67, v67
	v_add_f32_e32 v138, v138, v151
	v_mul_f32_e32 v151, v69, v69
	v_fmac_f32_e32 v163, v66, v66
	v_fmac_f32_e32 v151, v68, v68
	v_add_f32_e32 v157, v163, v157
	v_add_f32_e32 v151, v151, v157
	v_and_b32_e32 v157, 64, v161
	v_add_f32_e32 v138, v151, v138
	v_xor_b32_e32 v151, 16, v161
	v_add_u32_e32 v157, 64, v157
	v_cmp_lt_i32_e32 vcc, v151, v157
	s_nop 1
	v_cndmask_b32_e32 v151, v161, v151, vcc
	v_lshlrev_b32_e32 v151, 2, v151
	v_mov_b32_e32 v151, v138
	s_nop 1
	v_permlane16_swap_b32 v151, v138
	s_waitcnt lgkmcnt(0)
	v_add_f32_e32 v138, v138, v151
	v_xor_b32_e32 v151, 32, v161
	v_cmp_lt_i32_e32 vcc, v151, v157
	s_nop 1
	v_cndmask_b32_e32 v151, v161, v151, vcc
	v_lshlrev_b32_e32 v151, 2, v151
	v_mov_b32_e32 v151, v138
	s_nop 1
	v_permlane32_swap_b32 v151, v138
	s_and_saveexec_b64 s[56:57], s[4:5]
	s_cbranch_execz .LBB0_805
	v_ashrrev_i32_e32 v157, 31, v156
	v_lshlrev_b64 v[156:157], 6, v[156:157]
	s_waitcnt lgkmcnt(0)
	v_add_f32_e32 v138, v138, v151
	v_lshl_add_u64 v[156:157], s[50:51], 0, v[156:157]
	global_store_dword v[156:157], v138, off

.LBB0_806:
	v_add_u32_e32 v156, 0x80, v150
	v_mad_i64_i32 v[164:165], s[56:57], s45, v156, 0
	v_lshl_add_u64 v[168:169], v[164:165], 1, v[154:155]
	v_cvt_pk_bf16_f32 v164, v62, v63
	v_cvt_pk_bf16_f32 v165, v64, v65
	v_cvt_pk_bf16_f32 v166, v54, v55
	v_cvt_pk_bf16_f32 v167, v56, v57
	s_and_b64 vcc, exec, s[6:7]
	global_store_dwordx4 v[168:169], v[164:167], off
	s_nop 1
	v_cvt_pk_bf16_f32 v164, v58, v59
	v_cvt_pk_bf16_f32 v165, v60, v61
	v_cvt_pk_bf16_f32 v166, v50, v51
	v_cvt_pk_bf16_f32 v167, v52, v53
	global_store_dwordx4 v[168:169], v[164:167], off offset:256
	s_cbranch_vccnz .LBB0_810
	s_waitcnt lgkmcnt(0)
	v_mul_f32_e32 v151, v63, v63
	v_mul_f32_e32 v157, v65, v65
	v_fmac_f32_e32 v151, v62, v62
	v_fmac_f32_e32 v157, v64, v64
	v_add_f32_e32 v151, v151, v157
	v_mul_f32_e32 v157, v55, v55
	v_fmac_f32_e32 v157, v54, v54
	v_add_f32_e32 v151, v157, v151
	v_mul_f32_e32 v157, v59, v59
	v_mul_f32_e32 v163, v61, v61
	v_mul_f32_e32 v138, v57, v57
	v_fmac_f32_e32 v157, v58, v58
	v_fmac_f32_e32 v163, v60, v60
	v_fmac_f32_e32 v138, v56, v56
	v_add_f32_e32 v157, v157, v163
	v_mul_f32_e32 v163, v51, v51
	v_add_f32_e32 v138, v138, v151
	v_mul_f32_e32 v151, v53, v53
	v_fmac_f32_e32 v163, v50, v50
	v_fmac_f32_e32 v151, v52, v52
	v_add_f32_e32 v157, v163, v157
	v_add_f32_e32 v151, v151, v157
	v_and_b32_e32 v157, 64, v161
	v_add_f32_e32 v138, v151, v138
	v_xor_b32_e32 v151, 16, v161
	v_add_u32_e32 v157, 64, v157
	v_cmp_lt_i32_e32 vcc, v151, v157
	s_nop 1
	v_cndmask_b32_e32 v151, v161, v151, vcc
	v_lshlrev_b32_e32 v151, 2, v151
	v_mov_b32_e32 v151, v138
	s_nop 1
	v_permlane16_swap_b32 v151, v138
	s_waitcnt lgkmcnt(0)
	v_add_f32_e32 v138, v138, v151
	v_xor_b32_e32 v151, 32, v161
	v_cmp_lt_i32_e32 vcc, v151, v157
	s_nop 1
	v_cndmask_b32_e32 v151, v161, v151, vcc
	v_lshlrev_b32_e32 v151, 2, v151
	v_mov_b32_e32 v151, v138
	s_nop 1
	v_permlane32_swap_b32 v151, v138
	s_and_saveexec_b64 s[56:57], s[4:5]
	s_cbranch_execz .LBB0_809
	v_ashrrev_i32_e32 v157, 31, v156
	v_lshlrev_b64 v[156:157], 6, v[156:157]
	s_waitcnt lgkmcnt(0)
	v_add_f32_e32 v138, v138, v151
	v_lshl_add_u64 v[156:157], s[50:51], 0, v[156:157]
	global_store_dword v[156:157], v138, off

.LBB0_810:
	v_add_u32_e32 v156, 0x90, v150
	v_mad_i64_i32 v[164:165], s[56:57], s45, v156, 0
	v_lshl_add_u64 v[168:169], v[164:165], 1, v[154:155]
	v_cvt_pk_bf16_f32 v164, v46, v47
	v_cvt_pk_bf16_f32 v165, v48, v49
	v_cvt_pk_bf16_f32 v166, v38, v39
	v_cvt_pk_bf16_f32 v167, v40, v41
	s_and_b64 vcc, exec, s[6:7]
	global_store_dwordx4 v[168:169], v[164:167], off
	s_nop 1
	v_cvt_pk_bf16_f32 v164, v42, v43
	v_cvt_pk_bf16_f32 v165, v44, v45
	v_cvt_pk_bf16_f32 v166, v34, v35
	v_cvt_pk_bf16_f32 v167, v36, v37
	global_store_dwordx4 v[168:169], v[164:167], off offset:256
	s_cbranch_vccnz .LBB0_814
	s_waitcnt lgkmcnt(0)
	v_mul_f32_e32 v151, v47, v47
	v_mul_f32_e32 v157, v49, v49
	v_fmac_f32_e32 v151, v46, v46
	v_fmac_f32_e32 v157, v48, v48
	v_add_f32_e32 v151, v151, v157
	v_mul_f32_e32 v157, v39, v39
	v_fmac_f32_e32 v157, v38, v38
	v_add_f32_e32 v151, v157, v151
	v_mul_f32_e32 v157, v43, v43
	v_mul_f32_e32 v163, v45, v45
	v_mul_f32_e32 v138, v41, v41
	v_fmac_f32_e32 v157, v42, v42
	v_fmac_f32_e32 v163, v44, v44
	v_fmac_f32_e32 v138, v40, v40
	v_add_f32_e32 v157, v157, v163
	v_mul_f32_e32 v163, v35, v35
	v_add_f32_e32 v138, v138, v151
	v_mul_f32_e32 v151, v37, v37
	v_fmac_f32_e32 v163, v34, v34
	v_fmac_f32_e32 v151, v36, v36
	v_add_f32_e32 v157, v163, v157
	v_add_f32_e32 v151, v151, v157
	v_and_b32_e32 v157, 64, v161
	v_add_f32_e32 v138, v151, v138
	v_xor_b32_e32 v151, 16, v161
	v_add_u32_e32 v157, 64, v157
	v_cmp_lt_i32_e32 vcc, v151, v157
	s_nop 1
	v_cndmask_b32_e32 v151, v161, v151, vcc
	v_lshlrev_b32_e32 v151, 2, v151
	v_mov_b32_e32 v151, v138
	s_nop 1
	v_permlane16_swap_b32 v151, v138
	s_waitcnt lgkmcnt(0)
	v_add_f32_e32 v138, v138, v151
	v_xor_b32_e32 v151, 32, v161
	v_cmp_lt_i32_e32 vcc, v151, v157
	s_nop 1
	v_cndmask_b32_e32 v151, v161, v151, vcc
	v_lshlrev_b32_e32 v151, 2, v151
	v_mov_b32_e32 v151, v138
	s_nop 1
	v_permlane32_swap_b32 v151, v138
	s_and_saveexec_b64 s[56:57], s[4:5]
	s_cbranch_execz .LBB0_813
	v_ashrrev_i32_e32 v157, 31, v156
	v_lshlrev_b64 v[156:157], 6, v[156:157]
	s_waitcnt lgkmcnt(0)
	v_add_f32_e32 v138, v138, v151
	v_lshl_add_u64 v[156:157], s[50:51], 0, v[156:157]
	global_store_dword v[156:157], v138, off

.LBB0_814:
	v_add_u32_e32 v156, 0xa0, v150
	v_mad_i64_i32 v[164:165], s[56:57], s45, v156, 0
	v_lshl_add_u64 v[168:169], v[164:165], 1, v[154:155]
	v_cvt_pk_bf16_f32 v164, v30, v31
	v_cvt_pk_bf16_f32 v165, v32, v33
	v_cvt_pk_bf16_f32 v166, v22, v23
	v_cvt_pk_bf16_f32 v167, v24, v25
	s_and_b64 vcc, exec, s[6:7]
	global_store_dwordx4 v[168:169], v[164:167], off
	s_nop 1
	v_cvt_pk_bf16_f32 v164, v26, v27
	v_cvt_pk_bf16_f32 v165, v28, v29
	v_cvt_pk_bf16_f32 v166, v18, v19
	v_cvt_pk_bf16_f32 v167, v20, v21
	global_store_dwordx4 v[168:169], v[164:167], off offset:256
	s_cbranch_vccnz .LBB0_818
	s_waitcnt lgkmcnt(0)
	v_mul_f32_e32 v151, v31, v31
	v_mul_f32_e32 v157, v33, v33
	v_fmac_f32_e32 v151, v30, v30
	v_fmac_f32_e32 v157, v32, v32
	v_add_f32_e32 v151, v151, v157
	v_mul_f32_e32 v157, v23, v23
	v_fmac_f32_e32 v157, v22, v22
	v_add_f32_e32 v151, v157, v151
	v_mul_f32_e32 v157, v27, v27
	v_mul_f32_e32 v163, v29, v29
	v_mul_f32_e32 v138, v25, v25
	v_fmac_f32_e32 v157, v26, v26
	v_fmac_f32_e32 v163, v28, v28
	v_fmac_f32_e32 v138, v24, v24
	v_add_f32_e32 v157, v157, v163
	v_mul_f32_e32 v163, v19, v19
	v_add_f32_e32 v138, v138, v151
	v_mul_f32_e32 v151, v21, v21
	v_fmac_f32_e32 v163, v18, v18
	v_fmac_f32_e32 v151, v20, v20
	v_add_f32_e32 v157, v163, v157
	v_add_f32_e32 v151, v151, v157
	v_and_b32_e32 v157, 64, v161
	v_add_f32_e32 v138, v151, v138
	v_xor_b32_e32 v151, 16, v161
	v_add_u32_e32 v157, 64, v157
	v_cmp_lt_i32_e32 vcc, v151, v157
	s_nop 1
	v_cndmask_b32_e32 v151, v161, v151, vcc
	v_lshlrev_b32_e32 v151, 2, v151
	v_mov_b32_e32 v151, v138
	s_nop 1
	v_permlane16_swap_b32 v151, v138
	s_waitcnt lgkmcnt(0)
	v_add_f32_e32 v138, v138, v151
	v_xor_b32_e32 v151, 32, v161
	v_cmp_lt_i32_e32 vcc, v151, v157
	s_nop 1
	v_cndmask_b32_e32 v151, v161, v151, vcc
	v_lshlrev_b32_e32 v151, 2, v151
	v_mov_b32_e32 v151, v138
	s_nop 1
	v_permlane32_swap_b32 v151, v138
	s_and_saveexec_b64 s[56:57], s[4:5]
	s_cbranch_execz .LBB0_817
	v_ashrrev_i32_e32 v157, 31, v156
	v_lshlrev_b64 v[156:157], 6, v[156:157]
	s_waitcnt lgkmcnt(0)
	v_add_f32_e32 v138, v138, v151
	v_lshl_add_u64 v[156:157], s[50:51], 0, v[156:157]
	global_store_dword v[156:157], v138, off

.LBB0_818:
	v_add_u32_e32 v156, 0xb0, v150
	v_mad_i64_i32 v[164:165], s[56:57], s45, v156, 0
	v_lshl_add_u64 v[154:155], v[164:165], 1, v[154:155]
	v_cvt_pk_bf16_f32 v164, v14, v15
	v_cvt_pk_bf16_f32 v165, v16, v17
	v_cvt_pk_bf16_f32 v166, v6, v7
	v_cvt_pk_bf16_f32 v167, v8, v9
	s_and_b64 vcc, exec, s[6:7]
	global_store_dwordx4 v[154:155], v[164:167], off
	s_nop 1
	v_cvt_pk_bf16_f32 v164, v10, v11
	v_cvt_pk_bf16_f32 v165, v12, v13
	v_cvt_pk_bf16_f32 v166, v2, v3
	v_cvt_pk_bf16_f32 v167, v4, v5
	global_store_dwordx4 v[154:155], v[164:167], off offset:256
	s_cbranch_vccnz .LBB0_822
	s_waitcnt lgkmcnt(0)
	v_mul_f32_e32 v151, v15, v15
	v_mul_f32_e32 v154, v17, v17
	v_fmac_f32_e32 v151, v14, v14
	v_fmac_f32_e32 v154, v16, v16
	v_add_f32_e32 v151, v151, v154
	v_mul_f32_e32 v154, v7, v7
	v_fmac_f32_e32 v154, v6, v6
	v_add_f32_e32 v151, v154, v151
	v_mul_f32_e32 v154, v11, v11
	v_mul_f32_e32 v155, v13, v13
	v_mul_f32_e32 v138, v9, v9
	v_fmac_f32_e32 v154, v10, v10
	v_fmac_f32_e32 v155, v12, v12
	v_fmac_f32_e32 v138, v8, v8
	v_add_f32_e32 v154, v154, v155
	v_mul_f32_e32 v155, v3, v3
	v_add_f32_e32 v138, v138, v151
	v_mul_f32_e32 v151, v5, v5
	v_fmac_f32_e32 v155, v2, v2
	v_fmac_f32_e32 v151, v4, v4
	v_add_f32_e32 v154, v155, v154
	v_add_f32_e32 v151, v151, v154
	v_and_b32_e32 v154, 64, v161
	v_add_f32_e32 v138, v151, v138
	v_xor_b32_e32 v151, 16, v161
	v_add_u32_e32 v154, 64, v154
	v_cmp_lt_i32_e32 vcc, v151, v154
	s_nop 1
	v_cndmask_b32_e32 v151, v161, v151, vcc
	v_lshlrev_b32_e32 v151, 2, v151
	v_mov_b32_e32 v151, v138
	s_nop 1
	v_permlane16_swap_b32 v151, v138
	s_waitcnt lgkmcnt(0)
	v_add_f32_e32 v138, v138, v151
	v_xor_b32_e32 v151, 32, v161
	v_cmp_lt_i32_e32 vcc, v151, v154
	s_nop 1
	v_cndmask_b32_e32 v151, v161, v151, vcc
	v_lshlrev_b32_e32 v151, 2, v151
	v_mov_b32_e32 v151, v138
	s_nop 1
	v_permlane32_swap_b32 v151, v138
	s_and_saveexec_b64 s[6:7], s[4:5]
	s_cbranch_execz .LBB0_821
	v_ashrrev_i32_e32 v157, 31, v156
	v_lshlrev_b64 v[154:155], 6, v[156:157]
	s_waitcnt lgkmcnt(0)
	v_add_f32_e32 v138, v138, v151
	v_lshl_add_u64 v[154:155], s[50:51], 0, v[154:155]
	global_store_dword v[154:155], v138, off

.LBB0_970:
	s_and_b64 vcc, exec, s[56:57]
	s_cbranch_vccz .LBB0_1005
	s_cmp_eq_u32 s49, 4
	s_cselect_b64 s[58:59], -1, 0
	s_lshl_b32 s6, s50, 2
	v_lshl_or_b32 v154, s50, 8, v159
	s_ashr_i32 s7, s6, 31
	v_ashrrev_i32_e32 v155, 31, v154
	s_lshl_b64 s[6:7], s[6:7], 2
	v_lshl_add_u64 v[154:155], v[154:155], 1, v[152:153]
	s_or_b64 s[56:57], s[12:13], s[6:7]
	v_mad_i64_i32 v[156:157], s[6:7], s47, v150, 0
	s_cmp_lg_u32 s49, 4
	v_lshl_add_u64 v[156:157], v[156:157], 1, v[154:155]
	v_cvt_pk_bf16_f32 v164, v122, v123
	v_cvt_pk_bf16_f32 v165, v124, v125
	v_cvt_pk_bf16_f32 v166, v118, v119
	v_cvt_pk_bf16_f32 v167, v120, v121
	global_store_dwordx4 v[156:157], v[164:167], off
	s_nop 1
	v_cvt_pk_bf16_f32 v164, v126, v127
	v_cvt_pk_bf16_f32 v165, v128, v129
	v_cvt_pk_bf16_f32 v166, v114, v115
	v_cvt_pk_bf16_f32 v167, v116, v117
	global_store_dwordx4 v[156:157], v[164:167], off offset:256
	s_cbranch_scc1 .LBB0_975
	v_mul_f32_e32 v151, v123, v123
	v_mul_f32_e32 v156, v125, v125
	v_fmac_f32_e32 v151, v122, v122
	v_fmac_f32_e32 v156, v124, v124
	v_add_f32_e32 v151, v151, v156
	v_mul_f32_e32 v156, v119, v119
	v_fmac_f32_e32 v156, v118, v118
	v_add_f32_e32 v151, v156, v151
	v_mul_f32_e32 v156, v127, v127
	v_mul_f32_e32 v157, v129, v129
	v_mul_f32_e32 v138, v121, v121
	v_fmac_f32_e32 v156, v126, v126
	v_fmac_f32_e32 v157, v128, v128
	v_fmac_f32_e32 v138, v120, v120
	v_add_f32_e32 v156, v156, v157
	v_mul_f32_e32 v157, v115, v115
	v_add_f32_e32 v138, v138, v151
	v_mul_f32_e32 v151, v117, v117
	v_fmac_f32_e32 v157, v114, v114
	v_fmac_f32_e32 v151, v116, v116
	v_add_f32_e32 v156, v157, v156
	v_add_f32_e32 v151, v151, v156
	v_and_b32_e32 v156, 64, v161
	v_add_f32_e32 v138, v151, v138
	v_xor_b32_e32 v151, 16, v161
	v_add_u32_e32 v156, 64, v156
	v_cmp_lt_i32_e32 vcc, v151, v156
	s_nop 1
	v_cndmask_b32_e32 v151, v161, v151, vcc
	v_lshlrev_b32_e32 v151, 2, v151
	v_mov_b32_e32 v151, v138
	s_nop 1
	v_permlane16_swap_b32 v151, v138
	s_waitcnt lgkmcnt(0)
	v_add_f32_e32 v138, v138, v151
	v_xor_b32_e32 v151, 32, v161
	v_cmp_lt_i32_e32 vcc, v151, v156
	s_nop 1
	v_cndmask_b32_e32 v151, v161, v151, vcc
	v_lshlrev_b32_e32 v151, 2, v151
	v_mov_b32_e32 v156, v138
	s_nop 1
	v_permlane32_swap_b32 v156, v138
	s_and_saveexec_b64 s[6:7], s[4:5]
	s_cbranch_execz .LBB0_974
	v_ashrrev_i32_e32 v151, 31, v150
	s_waitcnt lgkmcnt(0)
	v_add_f32_e32 v138, v138, v156
	v_lshlrev_b64 v[156:157], 6, v[150:151]
	v_lshl_add_u64 v[156:157], s[56:57], 0, v[156:157]
	global_store_dword v[156:157], v138, off

.LBB0_975:
	s_waitcnt lgkmcnt(0)
	v_or_b32_e32 v156, 16, v150
	v_mad_i64_i32 v[164:165], s[6:7], s47, v156, 0
	v_cndmask_b32_e64 v138, 0, 1, s[58:59]
	v_lshl_add_u64 v[168:169], v[164:165], 1, v[154:155]
	v_cvt_pk_bf16_f32 v164, v110, v111
	v_cvt_pk_bf16_f32 v165, v112, v113
	v_cvt_pk_bf16_f32 v166, v102, v103
	v_cvt_pk_bf16_f32 v167, v104, v105
	v_cmp_ne_u32_e64 s[6:7], 1, v138
	s_andn2_b64 vcc, exec, s[58:59]
	global_store_dwordx4 v[168:169], v[164:167], off
	s_nop 1
	v_cvt_pk_bf16_f32 v164, v106, v107
	v_cvt_pk_bf16_f32 v165, v108, v109
	v_cvt_pk_bf16_f32 v166, v98, v99
	v_cvt_pk_bf16_f32 v167, v100, v101
	global_store_dwordx4 v[168:169], v[164:167], off offset:256
	s_cbranch_vccnz .LBB0_979
	v_mul_f32_e32 v151, v111, v111
	v_mul_f32_e32 v157, v113, v113
	v_fmac_f32_e32 v151, v110, v110
	v_fmac_f32_e32 v157, v112, v112
	v_add_f32_e32 v151, v151, v157
	v_mul_f32_e32 v157, v103, v103
	v_fmac_f32_e32 v157, v102, v102
	v_add_f32_e32 v151, v157, v151
	v_mul_f32_e32 v157, v107, v107
	v_mul_f32_e32 v163, v109, v109
	v_mul_f32_e32 v138, v105, v105
	v_fmac_f32_e32 v157, v106, v106
	v_fmac_f32_e32 v163, v108, v108
	v_fmac_f32_e32 v138, v104, v104
	v_add_f32_e32 v157, v157, v163
	v_mul_f32_e32 v163, v99, v99
	v_add_f32_e32 v138, v138, v151
	v_mul_f32_e32 v151, v101, v101
	v_fmac_f32_e32 v163, v98, v98
	v_fmac_f32_e32 v151, v100, v100
	v_add_f32_e32 v157, v163, v157
	v_add_f32_e32 v151, v151, v157
	v_and_b32_e32 v157, 64, v161
	v_add_f32_e32 v138, v151, v138
	v_xor_b32_e32 v151, 16, v161
	v_add_u32_e32 v157, 64, v157
	v_cmp_lt_i32_e32 vcc, v151, v157
	s_nop 1
	v_cndmask_b32_e32 v151, v161, v151, vcc
	v_lshlrev_b32_e32 v151, 2, v151
	v_mov_b32_e32 v151, v138
	s_nop 1
	v_permlane16_swap_b32 v151, v138
	s_waitcnt lgkmcnt(0)
	v_add_f32_e32 v138, v138, v151
	v_xor_b32_e32 v151, 32, v161
	v_cmp_lt_i32_e32 vcc, v151, v157
	s_nop 1
	v_cndmask_b32_e32 v151, v161, v151, vcc
	v_lshlrev_b32_e32 v151, 2, v151
	v_mov_b32_e32 v151, v138
	s_nop 1
	v_permlane32_swap_b32 v151, v138
	s_and_saveexec_b64 s[58:59], s[4:5]
	s_cbranch_execz .LBB0_978
	v_ashrrev_i32_e32 v157, 31, v156
	v_lshlrev_b64 v[156:157], 6, v[156:157]
	s_waitcnt lgkmcnt(0)
	v_add_f32_e32 v138, v138, v151
	v_lshl_add_u64 v[156:157], s[56:57], 0, v[156:157]
	global_store_dword v[156:157], v138, off

.LBB0_979:
	v_or_b32_e32 v156, 32, v150
	v_mad_i64_i32 v[164:165], s[58:59], s47, v156, 0
	v_lshl_add_u64 v[168:169], v[164:165], 1, v[154:155]
	v_cvt_pk_bf16_f32 v164, v94, v95
	v_cvt_pk_bf16_f32 v165, v96, v97
	v_cvt_pk_bf16_f32 v166, v86, v87
	v_cvt_pk_bf16_f32 v167, v88, v89
	s_and_b64 vcc, exec, s[6:7]
	global_store_dwordx4 v[168:169], v[164:167], off
	s_nop 1
	v_cvt_pk_bf16_f32 v164, v90, v91
	v_cvt_pk_bf16_f32 v165, v92, v93
	v_cvt_pk_bf16_f32 v166, v82, v83
	v_cvt_pk_bf16_f32 v167, v84, v85
	global_store_dwordx4 v[168:169], v[164:167], off offset:256
	s_cbranch_vccnz .LBB0_983
	s_waitcnt lgkmcnt(0)
	v_mul_f32_e32 v151, v95, v95
	v_mul_f32_e32 v157, v97, v97
	v_fmac_f32_e32 v151, v94, v94
	v_fmac_f32_e32 v157, v96, v96
	v_add_f32_e32 v151, v151, v157
	v_mul_f32_e32 v157, v87, v87
	v_fmac_f32_e32 v157, v86, v86
	v_add_f32_e32 v151, v157, v151
	v_mul_f32_e32 v157, v91, v91
	v_mul_f32_e32 v163, v93, v93
	v_mul_f32_e32 v138, v89, v89
	v_fmac_f32_e32 v157, v90, v90
	v_fmac_f32_e32 v163, v92, v92
	v_fmac_f32_e32 v138, v88, v88
	v_add_f32_e32 v157, v157, v163
	v_mul_f32_e32 v163, v83, v83
	v_add_f32_e32 v138, v138, v151
	v_mul_f32_e32 v151, v85, v85
	v_fmac_f32_e32 v163, v82, v82
	v_fmac_f32_e32 v151, v84, v84
	v_add_f32_e32 v157, v163, v157
	v_add_f32_e32 v151, v151, v157
	v_and_b32_e32 v157, 64, v161
	v_add_f32_e32 v138, v151, v138
	v_xor_b32_e32 v151, 16, v161
	v_add_u32_e32 v157, 64, v157
	v_cmp_lt_i32_e32 vcc, v151, v157
	s_nop 1
	v_cndmask_b32_e32 v151, v161, v151, vcc
	v_lshlrev_b32_e32 v151, 2, v151
	v_mov_b32_e32 v151, v138
	s_nop 1
	v_permlane16_swap_b32 v151, v138
	s_waitcnt lgkmcnt(0)
	v_add_f32_e32 v138, v138, v151
	v_xor_b32_e32 v151, 32, v161
	v_cmp_lt_i32_e32 vcc, v151, v157
	s_nop 1
	v_cndmask_b32_e32 v151, v161, v151, vcc
	v_lshlrev_b32_e32 v151, 2, v151
	v_mov_b32_e32 v151, v138
	s_nop 1
	v_permlane32_swap_b32 v151, v138
	s_and_saveexec_b64 s[58:59], s[4:5]
	s_cbranch_execz .LBB0_982
	v_ashrrev_i32_e32 v157, 31, v156
	v_lshlrev_b64 v[156:157], 6, v[156:157]
	s_waitcnt lgkmcnt(0)
	v_add_f32_e32 v138, v138, v151
	v_lshl_add_u64 v[156:157], s[56:57], 0, v[156:157]
	global_store_dword v[156:157], v138, off

.LBB0_983:
	v_or_b32_e32 v156, 48, v150
	v_mad_i64_i32 v[164:165], s[58:59], s47, v156, 0
	v_lshl_add_u64 v[168:169], v[164:165], 1, v[154:155]
	v_cvt_pk_bf16_f32 v164, v78, v79
	v_cvt_pk_bf16_f32 v165, v80, v81
	v_cvt_pk_bf16_f32 v166, v70, v71
	v_cvt_pk_bf16_f32 v167, v72, v73
	s_and_b64 vcc, exec, s[6:7]
	global_store_dwordx4 v[168:169], v[164:167], off
	s_nop 1
	v_cvt_pk_bf16_f32 v164, v74, v75
	v_cvt_pk_bf16_f32 v165, v76, v77
	v_cvt_pk_bf16_f32 v166, v66, v67
	v_cvt_pk_bf16_f32 v167, v68, v69
	global_store_dwordx4 v[168:169], v[164:167], off offset:256
	s_cbranch_vccnz .LBB0_987
	s_waitcnt lgkmcnt(0)
	v_mul_f32_e32 v151, v79, v79
	v_mul_f32_e32 v157, v81, v81
	v_fmac_f32_e32 v151, v78, v78
	v_fmac_f32_e32 v157, v80, v80
	v_add_f32_e32 v151, v151, v157
	v_mul_f32_e32 v157, v71, v71
	v_fmac_f32_e32 v157, v70, v70
	v_add_f32_e32 v151, v157, v151
	v_mul_f32_e32 v157, v75, v75
	v_mul_f32_e32 v163, v77, v77
	v_mul_f32_e32 v138, v73, v73
	v_fmac_f32_e32 v157, v74, v74
	v_fmac_f32_e32 v163, v76, v76
	v_fmac_f32_e32 v138, v72, v72
	v_add_f32_e32 v157, v157, v163
	v_mul_f32_e32 v163, v67, v67
	v_add_f32_e32 v138, v138, v151
	v_mul_f32_e32 v151, v69, v69
	v_fmac_f32_e32 v163, v66, v66
	v_fmac_f32_e32 v151, v68, v68
	v_add_f32_e32 v157, v163, v157
	v_add_f32_e32 v151, v151, v157
	v_and_b32_e32 v157, 64, v161
	v_add_f32_e32 v138, v151, v138
	v_xor_b32_e32 v151, 16, v161
	v_add_u32_e32 v157, 64, v157
	v_cmp_lt_i32_e32 vcc, v151, v157
	s_nop 1
	v_cndmask_b32_e32 v151, v161, v151, vcc
	v_lshlrev_b32_e32 v151, 2, v151
	v_mov_b32_e32 v151, v138
	s_nop 1
	v_permlane16_swap_b32 v151, v138
	s_waitcnt lgkmcnt(0)
	v_add_f32_e32 v138, v138, v151
	v_xor_b32_e32 v151, 32, v161
	v_cmp_lt_i32_e32 vcc, v151, v157
	s_nop 1
	v_cndmask_b32_e32 v151, v161, v151, vcc
	v_lshlrev_b32_e32 v151, 2, v151
	v_mov_b32_e32 v151, v138
	s_nop 1
	v_permlane32_swap_b32 v151, v138
	s_and_saveexec_b64 s[58:59], s[4:5]
	s_cbranch_execz .LBB0_986
	v_ashrrev_i32_e32 v157, 31, v156
	v_lshlrev_b64 v[156:157], 6, v[156:157]
	s_waitcnt lgkmcnt(0)
	v_add_f32_e32 v138, v138, v151
	v_lshl_add_u64 v[156:157], s[56:57], 0, v[156:157]
	global_store_dword v[156:157], v138, off

.LBB0_987:
	v_add_u32_e32 v156, 0x80, v150
	v_mad_i64_i32 v[164:165], s[58:59], s47, v156, 0
	v_lshl_add_u64 v[168:169], v[164:165], 1, v[154:155]
	v_cvt_pk_bf16_f32 v164, v62, v63
	v_cvt_pk_bf16_f32 v165, v64, v65
	v_cvt_pk_bf16_f32 v166, v54, v55
	v_cvt_pk_bf16_f32 v167, v56, v57
	s_and_b64 vcc, exec, s[6:7]
	global_store_dwordx4 v[168:169], v[164:167], off
	s_nop 1
	v_cvt_pk_bf16_f32 v164, v58, v59
	v_cvt_pk_bf16_f32 v165, v60, v61
	v_cvt_pk_bf16_f32 v166, v50, v51
	v_cvt_pk_bf16_f32 v167, v52, v53
	global_store_dwordx4 v[168:169], v[164:167], off offset:256
	s_cbranch_vccnz .LBB0_991
	s_waitcnt lgkmcnt(0)
	v_mul_f32_e32 v151, v63, v63
	v_mul_f32_e32 v157, v65, v65
	v_fmac_f32_e32 v151, v62, v62
	v_fmac_f32_e32 v157, v64, v64
	v_add_f32_e32 v151, v151, v157
	v_mul_f32_e32 v157, v55, v55
	v_fmac_f32_e32 v157, v54, v54
	v_add_f32_e32 v151, v157, v151
	v_mul_f32_e32 v157, v59, v59
	v_mul_f32_e32 v163, v61, v61
	v_mul_f32_e32 v138, v57, v57
	v_fmac_f32_e32 v157, v58, v58
	v_fmac_f32_e32 v163, v60, v60
	v_fmac_f32_e32 v138, v56, v56
	v_add_f32_e32 v157, v157, v163
	v_mul_f32_e32 v163, v51, v51
	v_add_f32_e32 v138, v138, v151
	v_mul_f32_e32 v151, v53, v53
	v_fmac_f32_e32 v163, v50, v50
	v_fmac_f32_e32 v151, v52, v52
	v_add_f32_e32 v157, v163, v157
	v_add_f32_e32 v151, v151, v157
	v_and_b32_e32 v157, 64, v161
	v_add_f32_e32 v138, v151, v138
	v_xor_b32_e32 v151, 16, v161
	v_add_u32_e32 v157, 64, v157
	v_cmp_lt_i32_e32 vcc, v151, v157
	s_nop 1
	v_cndmask_b32_e32 v151, v161, v151, vcc
	v_lshlrev_b32_e32 v151, 2, v151
	v_mov_b32_e32 v151, v138
	s_nop 1
	v_permlane16_swap_b32 v151, v138
	s_waitcnt lgkmcnt(0)
	v_add_f32_e32 v138, v138, v151
	v_xor_b32_e32 v151, 32, v161
	v_cmp_lt_i32_e32 vcc, v151, v157
	s_nop 1
	v_cndmask_b32_e32 v151, v161, v151, vcc
	v_lshlrev_b32_e32 v151, 2, v151
	v_mov_b32_e32 v151, v138
	s_nop 1
	v_permlane32_swap_b32 v151, v138
	s_and_saveexec_b64 s[58:59], s[4:5]
	s_cbranch_execz .LBB0_990
	v_ashrrev_i32_e32 v157, 31, v156
	v_lshlrev_b64 v[156:157], 6, v[156:157]
	s_waitcnt lgkmcnt(0)
	v_add_f32_e32 v138, v138, v151
	v_lshl_add_u64 v[156:157], s[56:57], 0, v[156:157]
	global_store_dword v[156:157], v138, off

.LBB0_991:
	v_add_u32_e32 v156, 0x90, v150
	v_mad_i64_i32 v[164:165], s[58:59], s47, v156, 0
	v_lshl_add_u64 v[168:169], v[164:165], 1, v[154:155]
	v_cvt_pk_bf16_f32 v164, v46, v47
	v_cvt_pk_bf16_f32 v165, v48, v49
	v_cvt_pk_bf16_f32 v166, v38, v39
	v_cvt_pk_bf16_f32 v167, v40, v41
	s_and_b64 vcc, exec, s[6:7]
	global_store_dwordx4 v[168:169], v[164:167], off
	s_nop 1
	v_cvt_pk_bf16_f32 v164, v42, v43
	v_cvt_pk_bf16_f32 v165, v44, v45
	v_cvt_pk_bf16_f32 v166, v34, v35
	v_cvt_pk_bf16_f32 v167, v36, v37
	global_store_dwordx4 v[168:169], v[164:167], off offset:256
	s_cbranch_vccnz .LBB0_995
	s_waitcnt lgkmcnt(0)
	v_mul_f32_e32 v151, v47, v47
	v_mul_f32_e32 v157, v49, v49
	v_fmac_f32_e32 v151, v46, v46
	v_fmac_f32_e32 v157, v48, v48
	v_add_f32_e32 v151, v151, v157
	v_mul_f32_e32 v157, v39, v39
	v_fmac_f32_e32 v157, v38, v38
	v_add_f32_e32 v151, v157, v151
	v_mul_f32_e32 v157, v43, v43
	v_mul_f32_e32 v163, v45, v45
	v_mul_f32_e32 v138, v41, v41
	v_fmac_f32_e32 v157, v42, v42
	v_fmac_f32_e32 v163, v44, v44
	v_fmac_f32_e32 v138, v40, v40
	v_add_f32_e32 v157, v157, v163
	v_mul_f32_e32 v163, v35, v35
	v_add_f32_e32 v138, v138, v151
	v_mul_f32_e32 v151, v37, v37
	v_fmac_f32_e32 v163, v34, v34
	v_fmac_f32_e32 v151, v36, v36
	v_add_f32_e32 v157, v163, v157
	v_add_f32_e32 v151, v151, v157
	v_and_b32_e32 v157, 64, v161
	v_add_f32_e32 v138, v151, v138
	v_xor_b32_e32 v151, 16, v161
	v_add_u32_e32 v157, 64, v157
	v_cmp_lt_i32_e32 vcc, v151, v157
	s_nop 1
	v_cndmask_b32_e32 v151, v161, v151, vcc
	v_lshlrev_b32_e32 v151, 2, v151
	v_mov_b32_e32 v151, v138
	s_nop 1
	v_permlane16_swap_b32 v151, v138
	s_waitcnt lgkmcnt(0)
	v_add_f32_e32 v138, v138, v151
	v_xor_b32_e32 v151, 32, v161
	v_cmp_lt_i32_e32 vcc, v151, v157
	s_nop 1
	v_cndmask_b32_e32 v151, v161, v151, vcc
	v_lshlrev_b32_e32 v151, 2, v151
	v_mov_b32_e32 v151, v138
	s_nop 1
	v_permlane32_swap_b32 v151, v138
	s_and_saveexec_b64 s[58:59], s[4:5]
	s_cbranch_execz .LBB0_994
	v_ashrrev_i32_e32 v157, 31, v156
	v_lshlrev_b64 v[156:157], 6, v[156:157]
	s_waitcnt lgkmcnt(0)
	v_add_f32_e32 v138, v138, v151
	v_lshl_add_u64 v[156:157], s[56:57], 0, v[156:157]
	global_store_dword v[156:157], v138, off

.LBB0_995:
	v_add_u32_e32 v156, 0xa0, v150
	v_mad_i64_i32 v[164:165], s[58:59], s47, v156, 0
	v_lshl_add_u64 v[168:169], v[164:165], 1, v[154:155]
	v_cvt_pk_bf16_f32 v164, v30, v31
	v_cvt_pk_bf16_f32 v165, v32, v33
	v_cvt_pk_bf16_f32 v166, v22, v23
	v_cvt_pk_bf16_f32 v167, v24, v25
	s_and_b64 vcc, exec, s[6:7]
	global_store_dwordx4 v[168:169], v[164:167], off
	s_nop 1
	v_cvt_pk_bf16_f32 v164, v26, v27
	v_cvt_pk_bf16_f32 v165, v28, v29
	v_cvt_pk_bf16_f32 v166, v18, v19
	v_cvt_pk_bf16_f32 v167, v20, v21
	global_store_dwordx4 v[168:169], v[164:167], off offset:256
	s_cbranch_vccnz .LBB0_999
	s_waitcnt lgkmcnt(0)
	v_mul_f32_e32 v151, v31, v31
	v_mul_f32_e32 v157, v33, v33
	v_fmac_f32_e32 v151, v30, v30
	v_fmac_f32_e32 v157, v32, v32
	v_add_f32_e32 v151, v151, v157
	v_mul_f32_e32 v157, v23, v23
	v_fmac_f32_e32 v157, v22, v22
	v_add_f32_e32 v151, v157, v151
	v_mul_f32_e32 v157, v27, v27
	v_mul_f32_e32 v163, v29, v29
	v_mul_f32_e32 v138, v25, v25
	v_fmac_f32_e32 v157, v26, v26
	v_fmac_f32_e32 v163, v28, v28
	v_fmac_f32_e32 v138, v24, v24
	v_add_f32_e32 v157, v157, v163
	v_mul_f32_e32 v163, v19, v19
	v_add_f32_e32 v138, v138, v151
	v_mul_f32_e32 v151, v21, v21
	v_fmac_f32_e32 v163, v18, v18
	v_fmac_f32_e32 v151, v20, v20
	v_add_f32_e32 v157, v163, v157
	v_add_f32_e32 v151, v151, v157
	v_and_b32_e32 v157, 64, v161
	v_add_f32_e32 v138, v151, v138
	v_xor_b32_e32 v151, 16, v161
	v_add_u32_e32 v157, 64, v157
	v_cmp_lt_i32_e32 vcc, v151, v157
	s_nop 1
	v_cndmask_b32_e32 v151, v161, v151, vcc
	v_lshlrev_b32_e32 v151, 2, v151
	v_mov_b32_e32 v151, v138
	s_nop 1
	v_permlane16_swap_b32 v151, v138
	s_waitcnt lgkmcnt(0)
	v_add_f32_e32 v138, v138, v151
	v_xor_b32_e32 v151, 32, v161
	v_cmp_lt_i32_e32 vcc, v151, v157
	s_nop 1
	v_cndmask_b32_e32 v151, v161, v151, vcc
	v_lshlrev_b32_e32 v151, 2, v151
	v_mov_b32_e32 v151, v138
	s_nop 1
	v_permlane32_swap_b32 v151, v138
	s_and_saveexec_b64 s[58:59], s[4:5]
	s_cbranch_execz .LBB0_998
	v_ashrrev_i32_e32 v157, 31, v156
	v_lshlrev_b64 v[156:157], 6, v[156:157]
	s_waitcnt lgkmcnt(0)
	v_add_f32_e32 v138, v138, v151
	v_lshl_add_u64 v[156:157], s[56:57], 0, v[156:157]
	global_store_dword v[156:157], v138, off

.LBB0_999:
	v_add_u32_e32 v156, 0xb0, v150
	v_mad_i64_i32 v[164:165], s[58:59], s47, v156, 0
	v_lshl_add_u64 v[154:155], v[164:165], 1, v[154:155]
	v_cvt_pk_bf16_f32 v164, v14, v15
	v_cvt_pk_bf16_f32 v165, v16, v17
	v_cvt_pk_bf16_f32 v166, v6, v7
	v_cvt_pk_bf16_f32 v167, v8, v9
	s_and_b64 vcc, exec, s[6:7]
	global_store_dwordx4 v[154:155], v[164:167], off
	s_nop 1
	v_cvt_pk_bf16_f32 v164, v10, v11
	v_cvt_pk_bf16_f32 v165, v12, v13
	v_cvt_pk_bf16_f32 v166, v2, v3
	v_cvt_pk_bf16_f32 v167, v4, v5
	global_store_dwordx4 v[154:155], v[164:167], off offset:256
	s_cbranch_vccnz .LBB0_1003
	s_waitcnt lgkmcnt(0)
	v_mul_f32_e32 v151, v15, v15
	v_mul_f32_e32 v154, v17, v17
	v_fmac_f32_e32 v151, v14, v14
	v_fmac_f32_e32 v154, v16, v16
	v_add_f32_e32 v151, v151, v154
	v_mul_f32_e32 v154, v7, v7
	v_fmac_f32_e32 v154, v6, v6
	v_add_f32_e32 v151, v154, v151
	v_mul_f32_e32 v154, v11, v11
	v_mul_f32_e32 v155, v13, v13
	v_mul_f32_e32 v138, v9, v9
	v_fmac_f32_e32 v154, v10, v10
	v_fmac_f32_e32 v155, v12, v12
	v_fmac_f32_e32 v138, v8, v8
	v_add_f32_e32 v154, v154, v155
	v_mul_f32_e32 v155, v3, v3
	v_add_f32_e32 v138, v138, v151
	v_mul_f32_e32 v151, v5, v5
	v_fmac_f32_e32 v155, v2, v2
	v_fmac_f32_e32 v151, v4, v4
	v_add_f32_e32 v154, v155, v154
	v_add_f32_e32 v151, v151, v154
	v_and_b32_e32 v154, 64, v161
	v_add_f32_e32 v138, v151, v138
	v_xor_b32_e32 v151, 16, v161
	v_add_u32_e32 v154, 64, v154
	v_cmp_lt_i32_e32 vcc, v151, v154
	s_nop 1
	v_cndmask_b32_e32 v151, v161, v151, vcc
	v_lshlrev_b32_e32 v151, 2, v151
	v_mov_b32_e32 v151, v138
	s_nop 1
	v_permlane16_swap_b32 v151, v138
	s_waitcnt lgkmcnt(0)
	v_add_f32_e32 v138, v138, v151
	v_xor_b32_e32 v151, 32, v161
	v_cmp_lt_i32_e32 vcc, v151, v154
	s_nop 1
	v_cndmask_b32_e32 v151, v161, v151, vcc
	v_lshlrev_b32_e32 v151, 2, v151
	v_mov_b32_e32 v151, v138
	s_nop 1
	v_permlane32_swap_b32 v151, v138
	s_and_saveexec_b64 s[6:7], s[4:5]
	s_cbranch_execz .LBB0_1002
	v_ashrrev_i32_e32 v157, 31, v156
	v_lshlrev_b64 v[154:155], 6, v[156:157]
	s_waitcnt lgkmcnt(0)
	v_add_f32_e32 v138, v138, v151
	v_lshl_add_u64 v[154:155], s[56:57], 0, v[154:155]
	global_store_dword v[154:155], v138, off

.LBB0_1101:
	s_and_b64 vcc, exec, s[28:29]
	s_cbranch_vccz .LBB0_1136
	s_cmp_eq_u32 s78, 4
	s_cselect_b64 s[44:45], -1, 0
	s_lshl_b32 s6, s76, 2
	s_ashr_i32 s7, s6, 31
	v_lshl_or_b32 v154, s76, 8, v159
	s_lshl_b64 s[6:7], s[6:7], 2
	v_ashrrev_i32_e32 v155, 31, v154
	s_add_u32 s28, s61, s6
	v_lshl_add_u64 v[154:155], v[154:155], 1, v[152:153]
	s_addc_u32 s29, s62, s7
	v_mad_i64_i32 v[156:157], s[6:7], s77, v150, 0
	s_cmp_lg_u32 s78, 4
	v_lshl_add_u64 v[156:157], v[156:157], 1, v[154:155]
	v_cvt_pk_bf16_f32 v164, v122, v123
	v_cvt_pk_bf16_f32 v165, v124, v125
	v_cvt_pk_bf16_f32 v166, v118, v119
	v_cvt_pk_bf16_f32 v167, v120, v121
	global_store_dwordx4 v[156:157], v[164:167], off
	s_nop 1
	v_cvt_pk_bf16_f32 v164, v126, v127
	v_cvt_pk_bf16_f32 v165, v128, v129
	v_cvt_pk_bf16_f32 v166, v114, v115
	v_cvt_pk_bf16_f32 v167, v116, v117
	global_store_dwordx4 v[156:157], v[164:167], off offset:256
	s_cbranch_scc1 .LBB0_1106
	v_mul_f32_e32 v151, v123, v123
	v_mul_f32_e32 v156, v125, v125
	v_fmac_f32_e32 v151, v122, v122
	v_fmac_f32_e32 v156, v124, v124
	v_add_f32_e32 v151, v151, v156
	v_mul_f32_e32 v156, v119, v119
	v_fmac_f32_e32 v156, v118, v118
	v_add_f32_e32 v151, v156, v151
	v_mul_f32_e32 v156, v127, v127
	v_mul_f32_e32 v157, v129, v129
	v_mul_f32_e32 v138, v121, v121
	v_fmac_f32_e32 v156, v126, v126
	v_fmac_f32_e32 v157, v128, v128
	v_fmac_f32_e32 v138, v120, v120
	v_add_f32_e32 v156, v156, v157
	v_mul_f32_e32 v157, v115, v115
	v_add_f32_e32 v138, v138, v151
	v_mul_f32_e32 v151, v117, v117
	v_fmac_f32_e32 v157, v114, v114
	v_fmac_f32_e32 v151, v116, v116
	v_add_f32_e32 v156, v157, v156
	v_add_f32_e32 v151, v151, v156
	v_and_b32_e32 v156, 64, v161
	v_add_f32_e32 v138, v151, v138
	v_xor_b32_e32 v151, 16, v161
	v_add_u32_e32 v156, 64, v156
	v_cmp_lt_i32_e32 vcc, v151, v156
	s_nop 1
	v_cndmask_b32_e32 v151, v161, v151, vcc
	v_lshlrev_b32_e32 v151, 2, v151
	v_mov_b32_e32 v151, v138
	s_nop 1
	v_permlane16_swap_b32 v151, v138
	s_waitcnt lgkmcnt(0)
	v_add_f32_e32 v138, v138, v151
	v_xor_b32_e32 v151, 32, v161
	v_cmp_lt_i32_e32 vcc, v151, v156
	s_nop 1
	v_cndmask_b32_e32 v151, v161, v151, vcc
	v_lshlrev_b32_e32 v151, 2, v151
	v_mov_b32_e32 v156, v138
	s_nop 1
	v_permlane32_swap_b32 v156, v138
	s_and_saveexec_b64 s[6:7], s[4:5]
	s_cbranch_execz .LBB0_1105
	v_ashrrev_i32_e32 v151, 31, v150
	s_waitcnt lgkmcnt(0)
	v_add_f32_e32 v138, v138, v156
	v_lshlrev_b64 v[156:157], 6, v[150:151]
	v_lshl_add_u64 v[156:157], s[28:29], 0, v[156:157]
	global_store_dword v[156:157], v138, off

.LBB0_1106:
	s_waitcnt lgkmcnt(0)
	v_or_b32_e32 v156, 16, v150
	v_mad_i64_i32 v[164:165], s[6:7], s77, v156, 0
	v_cndmask_b32_e64 v138, 0, 1, s[44:45]
	v_lshl_add_u64 v[168:169], v[164:165], 1, v[154:155]
	v_cvt_pk_bf16_f32 v164, v110, v111
	v_cvt_pk_bf16_f32 v165, v112, v113
	v_cvt_pk_bf16_f32 v166, v102, v103
	v_cvt_pk_bf16_f32 v167, v104, v105
	v_cmp_ne_u32_e64 s[6:7], 1, v138
	s_andn2_b64 vcc, exec, s[44:45]
	global_store_dwordx4 v[168:169], v[164:167], off
	s_nop 1
	v_cvt_pk_bf16_f32 v164, v106, v107
	v_cvt_pk_bf16_f32 v165, v108, v109
	v_cvt_pk_bf16_f32 v166, v98, v99
	v_cvt_pk_bf16_f32 v167, v100, v101
	global_store_dwordx4 v[168:169], v[164:167], off offset:256
	s_cbranch_vccnz .LBB0_1110
	v_mul_f32_e32 v151, v111, v111
	v_mul_f32_e32 v157, v113, v113
	v_fmac_f32_e32 v151, v110, v110
	v_fmac_f32_e32 v157, v112, v112
	v_add_f32_e32 v151, v151, v157
	v_mul_f32_e32 v157, v103, v103
	v_fmac_f32_e32 v157, v102, v102
	v_add_f32_e32 v151, v157, v151
	v_mul_f32_e32 v157, v107, v107
	v_mul_f32_e32 v163, v109, v109
	v_mul_f32_e32 v138, v105, v105
	v_fmac_f32_e32 v157, v106, v106
	v_fmac_f32_e32 v163, v108, v108
	v_fmac_f32_e32 v138, v104, v104
	v_add_f32_e32 v157, v157, v163
	v_mul_f32_e32 v163, v99, v99
	v_add_f32_e32 v138, v138, v151
	v_mul_f32_e32 v151, v101, v101
	v_fmac_f32_e32 v163, v98, v98
	v_fmac_f32_e32 v151, v100, v100
	v_add_f32_e32 v157, v163, v157
	v_add_f32_e32 v151, v151, v157
	v_and_b32_e32 v157, 64, v161
	v_add_f32_e32 v138, v151, v138
	v_xor_b32_e32 v151, 16, v161
	v_add_u32_e32 v157, 64, v157
	v_cmp_lt_i32_e32 vcc, v151, v157
	s_nop 1
	v_cndmask_b32_e32 v151, v161, v151, vcc
	v_lshlrev_b32_e32 v151, 2, v151
	v_mov_b32_e32 v151, v138
	s_nop 1
	v_permlane16_swap_b32 v151, v138
	s_waitcnt lgkmcnt(0)
	v_add_f32_e32 v138, v138, v151
	v_xor_b32_e32 v151, 32, v161
	v_cmp_lt_i32_e32 vcc, v151, v157
	s_nop 1
	v_cndmask_b32_e32 v151, v161, v151, vcc
	v_lshlrev_b32_e32 v151, 2, v151
	v_mov_b32_e32 v151, v138
	s_nop 1
	v_permlane32_swap_b32 v151, v138
	s_and_saveexec_b64 s[44:45], s[4:5]
	s_cbranch_execz .LBB0_1109
	v_ashrrev_i32_e32 v157, 31, v156
	v_lshlrev_b64 v[156:157], 6, v[156:157]
	s_waitcnt lgkmcnt(0)
	v_add_f32_e32 v138, v138, v151
	v_lshl_add_u64 v[156:157], s[28:29], 0, v[156:157]
	global_store_dword v[156:157], v138, off

.LBB0_1110:
	v_or_b32_e32 v156, 32, v150
	v_mad_i64_i32 v[164:165], s[44:45], s77, v156, 0
	v_lshl_add_u64 v[168:169], v[164:165], 1, v[154:155]
	v_cvt_pk_bf16_f32 v164, v94, v95
	v_cvt_pk_bf16_f32 v165, v96, v97
	v_cvt_pk_bf16_f32 v166, v86, v87
	v_cvt_pk_bf16_f32 v167, v88, v89
	s_and_b64 vcc, exec, s[6:7]
	global_store_dwordx4 v[168:169], v[164:167], off
	s_nop 1
	v_cvt_pk_bf16_f32 v164, v90, v91
	v_cvt_pk_bf16_f32 v165, v92, v93
	v_cvt_pk_bf16_f32 v166, v82, v83
	v_cvt_pk_bf16_f32 v167, v84, v85
	global_store_dwordx4 v[168:169], v[164:167], off offset:256
	s_cbranch_vccnz .LBB0_1114
	s_waitcnt lgkmcnt(0)
	v_mul_f32_e32 v151, v95, v95
	v_mul_f32_e32 v157, v97, v97
	v_fmac_f32_e32 v151, v94, v94
	v_fmac_f32_e32 v157, v96, v96
	v_add_f32_e32 v151, v151, v157
	v_mul_f32_e32 v157, v87, v87
	v_fmac_f32_e32 v157, v86, v86
	v_add_f32_e32 v151, v157, v151
	v_mul_f32_e32 v157, v91, v91
	v_mul_f32_e32 v163, v93, v93
	v_mul_f32_e32 v138, v89, v89
	v_fmac_f32_e32 v157, v90, v90
	v_fmac_f32_e32 v163, v92, v92
	v_fmac_f32_e32 v138, v88, v88
	v_add_f32_e32 v157, v157, v163
	v_mul_f32_e32 v163, v83, v83
	v_add_f32_e32 v138, v138, v151
	v_mul_f32_e32 v151, v85, v85
	v_fmac_f32_e32 v163, v82, v82
	v_fmac_f32_e32 v151, v84, v84
	v_add_f32_e32 v157, v163, v157
	v_add_f32_e32 v151, v151, v157
	v_and_b32_e32 v157, 64, v161
	v_add_f32_e32 v138, v151, v138
	v_xor_b32_e32 v151, 16, v161
	v_add_u32_e32 v157, 64, v157
	v_cmp_lt_i32_e32 vcc, v151, v157
	s_nop 1
	v_cndmask_b32_e32 v151, v161, v151, vcc
	v_lshlrev_b32_e32 v151, 2, v151
	v_mov_b32_e32 v151, v138
	s_nop 1
	v_permlane16_swap_b32 v151, v138
	s_waitcnt lgkmcnt(0)
	v_add_f32_e32 v138, v138, v151
	v_xor_b32_e32 v151, 32, v161
	v_cmp_lt_i32_e32 vcc, v151, v157
	s_nop 1
	v_cndmask_b32_e32 v151, v161, v151, vcc
	v_lshlrev_b32_e32 v151, 2, v151
	v_mov_b32_e32 v151, v138
	s_nop 1
	v_permlane32_swap_b32 v151, v138
	s_and_saveexec_b64 s[44:45], s[4:5]
	s_cbranch_execz .LBB0_1113
	v_ashrrev_i32_e32 v157, 31, v156
	v_lshlrev_b64 v[156:157], 6, v[156:157]
	s_waitcnt lgkmcnt(0)
	v_add_f32_e32 v138, v138, v151
	v_lshl_add_u64 v[156:157], s[28:29], 0, v[156:157]
	global_store_dword v[156:157], v138, off

.LBB0_1114:
	v_or_b32_e32 v156, 48, v150
	v_mad_i64_i32 v[164:165], s[44:45], s77, v156, 0
	v_lshl_add_u64 v[168:169], v[164:165], 1, v[154:155]
	v_cvt_pk_bf16_f32 v164, v78, v79
	v_cvt_pk_bf16_f32 v165, v80, v81
	v_cvt_pk_bf16_f32 v166, v70, v71
	v_cvt_pk_bf16_f32 v167, v72, v73
	s_and_b64 vcc, exec, s[6:7]
	global_store_dwordx4 v[168:169], v[164:167], off
	s_nop 1
	v_cvt_pk_bf16_f32 v164, v74, v75
	v_cvt_pk_bf16_f32 v165, v76, v77
	v_cvt_pk_bf16_f32 v166, v66, v67
	v_cvt_pk_bf16_f32 v167, v68, v69
	global_store_dwordx4 v[168:169], v[164:167], off offset:256
	s_cbranch_vccnz .LBB0_1118
	s_waitcnt lgkmcnt(0)
	v_mul_f32_e32 v151, v79, v79
	v_mul_f32_e32 v157, v81, v81
	v_fmac_f32_e32 v151, v78, v78
	v_fmac_f32_e32 v157, v80, v80
	v_add_f32_e32 v151, v151, v157
	v_mul_f32_e32 v157, v71, v71
	v_fmac_f32_e32 v157, v70, v70
	v_add_f32_e32 v151, v157, v151
	v_mul_f32_e32 v157, v75, v75
	v_mul_f32_e32 v163, v77, v77
	v_mul_f32_e32 v138, v73, v73
	v_fmac_f32_e32 v157, v74, v74
	v_fmac_f32_e32 v163, v76, v76
	v_fmac_f32_e32 v138, v72, v72
	v_add_f32_e32 v157, v157, v163
	v_mul_f32_e32 v163, v67, v67
	v_add_f32_e32 v138, v138, v151
	v_mul_f32_e32 v151, v69, v69
	v_fmac_f32_e32 v163, v66, v66
	v_fmac_f32_e32 v151, v68, v68
	v_add_f32_e32 v157, v163, v157
	v_add_f32_e32 v151, v151, v157
	v_and_b32_e32 v157, 64, v161
	v_add_f32_e32 v138, v151, v138
	v_xor_b32_e32 v151, 16, v161
	v_add_u32_e32 v157, 64, v157
	v_cmp_lt_i32_e32 vcc, v151, v157
	s_nop 1
	v_cndmask_b32_e32 v151, v161, v151, vcc
	v_lshlrev_b32_e32 v151, 2, v151
	v_mov_b32_e32 v151, v138
	s_nop 1
	v_permlane16_swap_b32 v151, v138
	s_waitcnt lgkmcnt(0)
	v_add_f32_e32 v138, v138, v151
	v_xor_b32_e32 v151, 32, v161
	v_cmp_lt_i32_e32 vcc, v151, v157
	s_nop 1
	v_cndmask_b32_e32 v151, v161, v151, vcc
	v_lshlrev_b32_e32 v151, 2, v151
	v_mov_b32_e32 v151, v138
	s_nop 1
	v_permlane32_swap_b32 v151, v138
	s_and_saveexec_b64 s[44:45], s[4:5]
	s_cbranch_execz .LBB0_1117
	v_ashrrev_i32_e32 v157, 31, v156
	v_lshlrev_b64 v[156:157], 6, v[156:157]
	s_waitcnt lgkmcnt(0)
	v_add_f32_e32 v138, v138, v151
	v_lshl_add_u64 v[156:157], s[28:29], 0, v[156:157]
	global_store_dword v[156:157], v138, off

.LBB0_1118:
	v_add_u32_e32 v156, 0x80, v150
	v_mad_i64_i32 v[164:165], s[44:45], s77, v156, 0
	v_lshl_add_u64 v[168:169], v[164:165], 1, v[154:155]
	v_cvt_pk_bf16_f32 v164, v62, v63
	v_cvt_pk_bf16_f32 v165, v64, v65
	v_cvt_pk_bf16_f32 v166, v54, v55
	v_cvt_pk_bf16_f32 v167, v56, v57
	s_and_b64 vcc, exec, s[6:7]
	global_store_dwordx4 v[168:169], v[164:167], off
	s_nop 1
	v_cvt_pk_bf16_f32 v164, v58, v59
	v_cvt_pk_bf16_f32 v165, v60, v61
	v_cvt_pk_bf16_f32 v166, v50, v51
	v_cvt_pk_bf16_f32 v167, v52, v53
	global_store_dwordx4 v[168:169], v[164:167], off offset:256
	s_cbranch_vccnz .LBB0_1122
	s_waitcnt lgkmcnt(0)
	v_mul_f32_e32 v151, v63, v63
	v_mul_f32_e32 v157, v65, v65
	v_fmac_f32_e32 v151, v62, v62
	v_fmac_f32_e32 v157, v64, v64
	v_add_f32_e32 v151, v151, v157
	v_mul_f32_e32 v157, v55, v55
	v_fmac_f32_e32 v157, v54, v54
	v_add_f32_e32 v151, v157, v151
	v_mul_f32_e32 v157, v59, v59
	v_mul_f32_e32 v163, v61, v61
	v_mul_f32_e32 v138, v57, v57
	v_fmac_f32_e32 v157, v58, v58
	v_fmac_f32_e32 v163, v60, v60
	v_fmac_f32_e32 v138, v56, v56
	v_add_f32_e32 v157, v157, v163
	v_mul_f32_e32 v163, v51, v51
	v_add_f32_e32 v138, v138, v151
	v_mul_f32_e32 v151, v53, v53
	v_fmac_f32_e32 v163, v50, v50
	v_fmac_f32_e32 v151, v52, v52
	v_add_f32_e32 v157, v163, v157
	v_add_f32_e32 v151, v151, v157
	v_and_b32_e32 v157, 64, v161
	v_add_f32_e32 v138, v151, v138
	v_xor_b32_e32 v151, 16, v161
	v_add_u32_e32 v157, 64, v157
	v_cmp_lt_i32_e32 vcc, v151, v157
	s_nop 1
	v_cndmask_b32_e32 v151, v161, v151, vcc
	v_lshlrev_b32_e32 v151, 2, v151
	v_mov_b32_e32 v151, v138
	s_nop 1
	v_permlane16_swap_b32 v151, v138
	s_waitcnt lgkmcnt(0)
	v_add_f32_e32 v138, v138, v151
	v_xor_b32_e32 v151, 32, v161
	v_cmp_lt_i32_e32 vcc, v151, v157
	s_nop 1
	v_cndmask_b32_e32 v151, v161, v151, vcc
	v_lshlrev_b32_e32 v151, 2, v151
	v_mov_b32_e32 v151, v138
	s_nop 1
	v_permlane32_swap_b32 v151, v138
	s_and_saveexec_b64 s[44:45], s[4:5]
	s_cbranch_execz .LBB0_1121
	v_ashrrev_i32_e32 v157, 31, v156
	v_lshlrev_b64 v[156:157], 6, v[156:157]
	s_waitcnt lgkmcnt(0)
	v_add_f32_e32 v138, v138, v151
	v_lshl_add_u64 v[156:157], s[28:29], 0, v[156:157]
	global_store_dword v[156:157], v138, off

.LBB0_1122:
	v_add_u32_e32 v156, 0x90, v150
	v_mad_i64_i32 v[164:165], s[44:45], s77, v156, 0
	v_lshl_add_u64 v[168:169], v[164:165], 1, v[154:155]
	v_cvt_pk_bf16_f32 v164, v46, v47
	v_cvt_pk_bf16_f32 v165, v48, v49
	v_cvt_pk_bf16_f32 v166, v38, v39
	v_cvt_pk_bf16_f32 v167, v40, v41
	s_and_b64 vcc, exec, s[6:7]
	global_store_dwordx4 v[168:169], v[164:167], off
	s_nop 1
	v_cvt_pk_bf16_f32 v164, v42, v43
	v_cvt_pk_bf16_f32 v165, v44, v45
	v_cvt_pk_bf16_f32 v166, v34, v35
	v_cvt_pk_bf16_f32 v167, v36, v37
	global_store_dwordx4 v[168:169], v[164:167], off offset:256
	s_cbranch_vccnz .LBB0_1126
	s_waitcnt lgkmcnt(0)
	v_mul_f32_e32 v151, v47, v47
	v_mul_f32_e32 v157, v49, v49
	v_fmac_f32_e32 v151, v46, v46
	v_fmac_f32_e32 v157, v48, v48
	v_add_f32_e32 v151, v151, v157
	v_mul_f32_e32 v157, v39, v39
	v_fmac_f32_e32 v157, v38, v38
	v_add_f32_e32 v151, v157, v151
	v_mul_f32_e32 v157, v43, v43
	v_mul_f32_e32 v163, v45, v45
	v_mul_f32_e32 v138, v41, v41
	v_fmac_f32_e32 v157, v42, v42
	v_fmac_f32_e32 v163, v44, v44
	v_fmac_f32_e32 v138, v40, v40
	v_add_f32_e32 v157, v157, v163
	v_mul_f32_e32 v163, v35, v35
	v_add_f32_e32 v138, v138, v151
	v_mul_f32_e32 v151, v37, v37
	v_fmac_f32_e32 v163, v34, v34
	v_fmac_f32_e32 v151, v36, v36
	v_add_f32_e32 v157, v163, v157
	v_add_f32_e32 v151, v151, v157
	v_and_b32_e32 v157, 64, v161
	v_add_f32_e32 v138, v151, v138
	v_xor_b32_e32 v151, 16, v161
	v_add_u32_e32 v157, 64, v157
	v_cmp_lt_i32_e32 vcc, v151, v157
	s_nop 1
	v_cndmask_b32_e32 v151, v161, v151, vcc
	v_lshlrev_b32_e32 v151, 2, v151
	v_mov_b32_e32 v151, v138
	s_nop 1
	v_permlane16_swap_b32 v151, v138
	s_waitcnt lgkmcnt(0)
	v_add_f32_e32 v138, v138, v151
	v_xor_b32_e32 v151, 32, v161
	v_cmp_lt_i32_e32 vcc, v151, v157
	s_nop 1
	v_cndmask_b32_e32 v151, v161, v151, vcc
	v_lshlrev_b32_e32 v151, 2, v151
	v_mov_b32_e32 v151, v138
	s_nop 1
	v_permlane32_swap_b32 v151, v138
	s_and_saveexec_b64 s[44:45], s[4:5]
	s_cbranch_execz .LBB0_1125
	v_ashrrev_i32_e32 v157, 31, v156
	v_lshlrev_b64 v[156:157], 6, v[156:157]
	s_waitcnt lgkmcnt(0)
	v_add_f32_e32 v138, v138, v151
	v_lshl_add_u64 v[156:157], s[28:29], 0, v[156:157]
	global_store_dword v[156:157], v138, off

.LBB0_1126:
	v_add_u32_e32 v156, 0xa0, v150
	v_mad_i64_i32 v[164:165], s[44:45], s77, v156, 0
	v_lshl_add_u64 v[168:169], v[164:165], 1, v[154:155]
	v_cvt_pk_bf16_f32 v164, v30, v31
	v_cvt_pk_bf16_f32 v165, v32, v33
	v_cvt_pk_bf16_f32 v166, v22, v23
	v_cvt_pk_bf16_f32 v167, v24, v25
	s_and_b64 vcc, exec, s[6:7]
	global_store_dwordx4 v[168:169], v[164:167], off
	s_nop 1
	v_cvt_pk_bf16_f32 v164, v26, v27
	v_cvt_pk_bf16_f32 v165, v28, v29
	v_cvt_pk_bf16_f32 v166, v18, v19
	v_cvt_pk_bf16_f32 v167, v20, v21
	global_store_dwordx4 v[168:169], v[164:167], off offset:256
	s_cbranch_vccnz .LBB0_1130
	s_waitcnt lgkmcnt(0)
	v_mul_f32_e32 v151, v31, v31
	v_mul_f32_e32 v157, v33, v33
	v_fmac_f32_e32 v151, v30, v30
	v_fmac_f32_e32 v157, v32, v32
	v_add_f32_e32 v151, v151, v157
	v_mul_f32_e32 v157, v23, v23
	v_fmac_f32_e32 v157, v22, v22
	v_add_f32_e32 v151, v157, v151
	v_mul_f32_e32 v157, v27, v27
	v_mul_f32_e32 v163, v29, v29
	v_mul_f32_e32 v138, v25, v25
	v_fmac_f32_e32 v157, v26, v26
	v_fmac_f32_e32 v163, v28, v28
	v_fmac_f32_e32 v138, v24, v24
	v_add_f32_e32 v157, v157, v163
	v_mul_f32_e32 v163, v19, v19
	v_add_f32_e32 v138, v138, v151
	v_mul_f32_e32 v151, v21, v21
	v_fmac_f32_e32 v163, v18, v18
	v_fmac_f32_e32 v151, v20, v20
	v_add_f32_e32 v157, v163, v157
	v_add_f32_e32 v151, v151, v157
	v_and_b32_e32 v157, 64, v161
	v_add_f32_e32 v138, v151, v138
	v_xor_b32_e32 v151, 16, v161
	v_add_u32_e32 v157, 64, v157
	v_cmp_lt_i32_e32 vcc, v151, v157
	s_nop 1
	v_cndmask_b32_e32 v151, v161, v151, vcc
	v_lshlrev_b32_e32 v151, 2, v151
	v_mov_b32_e32 v151, v138
	s_nop 1
	v_permlane16_swap_b32 v151, v138
	s_waitcnt lgkmcnt(0)
	v_add_f32_e32 v138, v138, v151
	v_xor_b32_e32 v151, 32, v161
	v_cmp_lt_i32_e32 vcc, v151, v157
	s_nop 1
	v_cndmask_b32_e32 v151, v161, v151, vcc
	v_lshlrev_b32_e32 v151, 2, v151
	v_mov_b32_e32 v151, v138
	s_nop 1
	v_permlane32_swap_b32 v151, v138
	s_and_saveexec_b64 s[44:45], s[4:5]
	s_cbranch_execz .LBB0_1129
	v_ashrrev_i32_e32 v157, 31, v156
	v_lshlrev_b64 v[156:157], 6, v[156:157]
	s_waitcnt lgkmcnt(0)
	v_add_f32_e32 v138, v138, v151
	v_lshl_add_u64 v[156:157], s[28:29], 0, v[156:157]
	global_store_dword v[156:157], v138, off

.LBB0_1130:
	v_add_u32_e32 v156, 0xb0, v150
	v_mad_i64_i32 v[164:165], s[44:45], s77, v156, 0
	v_lshl_add_u64 v[154:155], v[164:165], 1, v[154:155]
	v_cvt_pk_bf16_f32 v164, v14, v15
	v_cvt_pk_bf16_f32 v165, v16, v17
	v_cvt_pk_bf16_f32 v166, v6, v7
	v_cvt_pk_bf16_f32 v167, v8, v9
	s_and_b64 vcc, exec, s[6:7]
	global_store_dwordx4 v[154:155], v[164:167], off
	s_nop 1
	v_cvt_pk_bf16_f32 v164, v10, v11
	v_cvt_pk_bf16_f32 v165, v12, v13
	v_cvt_pk_bf16_f32 v166, v2, v3
	v_cvt_pk_bf16_f32 v167, v4, v5
	global_store_dwordx4 v[154:155], v[164:167], off offset:256
	s_cbranch_vccnz .LBB0_1134
	s_waitcnt lgkmcnt(0)
	v_mul_f32_e32 v151, v15, v15
	v_mul_f32_e32 v154, v17, v17
	v_fmac_f32_e32 v151, v14, v14
	v_fmac_f32_e32 v154, v16, v16
	v_add_f32_e32 v151, v151, v154
	v_mul_f32_e32 v154, v7, v7
	v_fmac_f32_e32 v154, v6, v6
	v_add_f32_e32 v151, v154, v151
	v_mul_f32_e32 v154, v11, v11
	v_mul_f32_e32 v155, v13, v13
	v_mul_f32_e32 v138, v9, v9
	v_fmac_f32_e32 v154, v10, v10
	v_fmac_f32_e32 v155, v12, v12
	v_fmac_f32_e32 v138, v8, v8
	v_add_f32_e32 v154, v154, v155
	v_mul_f32_e32 v155, v3, v3
	v_add_f32_e32 v138, v138, v151
	v_mul_f32_e32 v151, v5, v5
	v_fmac_f32_e32 v155, v2, v2
	v_fmac_f32_e32 v151, v4, v4
	v_add_f32_e32 v154, v155, v154
	v_add_f32_e32 v151, v151, v154
	v_and_b32_e32 v154, 64, v161
	v_add_f32_e32 v138, v151, v138
	v_xor_b32_e32 v151, 16, v161
	v_add_u32_e32 v154, 64, v154
	v_cmp_lt_i32_e32 vcc, v151, v154
	s_nop 1
	v_cndmask_b32_e32 v151, v161, v151, vcc
	v_lshlrev_b32_e32 v151, 2, v151
	v_mov_b32_e32 v151, v138
	s_nop 1
	v_permlane16_swap_b32 v151, v138
	s_waitcnt lgkmcnt(0)
	v_add_f32_e32 v138, v138, v151
	v_xor_b32_e32 v151, 32, v161
	v_cmp_lt_i32_e32 vcc, v151, v154
	s_nop 1
	v_cndmask_b32_e32 v151, v161, v151, vcc
	v_lshlrev_b32_e32 v151, 2, v151
	v_mov_b32_e32 v151, v138
	s_nop 1
	v_permlane32_swap_b32 v151, v138
	s_and_saveexec_b64 s[6:7], s[4:5]
	s_cbranch_execz .LBB0_1133
	v_ashrrev_i32_e32 v157, 31, v156
	v_lshlrev_b64 v[154:155], 6, v[156:157]
	s_waitcnt lgkmcnt(0)
	v_add_f32_e32 v138, v138, v151
	v_lshl_add_u64 v[154:155], s[28:29], 0, v[154:155]
	global_store_dword v[154:155], v138, off

.LBB0_1594:
	s_and_b64 vcc, exec, s[56:57]
	s_cbranch_vccz .LBB0_1629
	s_cmp_eq_u32 s49, 4
	s_cselect_b64 s[58:59], -1, 0
	s_lshl_b32 s6, s50, 2
	v_lshl_or_b32 v156, s50, 8, v162
	s_ashr_i32 s7, s6, 31
	v_ashrrev_i32_e32 v157, 31, v156
	s_lshl_b64 s[6:7], s[6:7], 2
	v_lshl_add_u64 v[156:157], v[156:157], 1, v[154:155]
	s_or_b64 s[56:57], s[12:13], s[6:7]
	v_mad_i64_i32 v[158:159], s[6:7], s47, v152, 0
	s_cmp_lg_u32 s49, 4
	v_lshl_add_u64 v[158:159], v[158:159], 1, v[156:157]
	v_cvt_pk_bf16_f32 v166, v122, v123
	v_cvt_pk_bf16_f32 v167, v124, v125
	v_cvt_pk_bf16_f32 v168, v118, v119
	v_cvt_pk_bf16_f32 v169, v120, v121
	global_store_dwordx4 v[158:159], v[166:169], off
	s_nop 1
	v_cvt_pk_bf16_f32 v166, v126, v127
	v_cvt_pk_bf16_f32 v167, v128, v129
	v_cvt_pk_bf16_f32 v168, v114, v115
	v_cvt_pk_bf16_f32 v169, v116, v117
	global_store_dwordx4 v[158:159], v[166:169], off offset:256
	s_cbranch_scc1 .LBB0_1599
	v_mul_f32_e32 v141, v123, v123
	v_mul_f32_e32 v146, v125, v125
	v_fmac_f32_e32 v141, v122, v122
	v_fmac_f32_e32 v146, v124, v124
	v_add_f32_e32 v141, v141, v146
	v_mul_f32_e32 v146, v119, v119
	v_fmac_f32_e32 v146, v118, v118
	v_add_f32_e32 v141, v146, v141
	v_mul_f32_e32 v146, v127, v127
	v_mul_f32_e32 v153, v129, v129
	v_mul_f32_e32 v138, v121, v121
	v_fmac_f32_e32 v146, v126, v126
	v_fmac_f32_e32 v153, v128, v128
	v_fmac_f32_e32 v138, v120, v120
	v_add_f32_e32 v146, v146, v153
	v_mul_f32_e32 v153, v115, v115
	v_add_f32_e32 v138, v138, v141
	v_mul_f32_e32 v141, v117, v117
	v_fmac_f32_e32 v153, v114, v114
	v_fmac_f32_e32 v141, v116, v116
	v_add_f32_e32 v146, v153, v146
	v_add_f32_e32 v141, v141, v146
	v_and_b32_e32 v146, 64, v164
	v_add_f32_e32 v138, v141, v138
	v_xor_b32_e32 v141, 16, v164
	v_add_u32_e32 v146, 64, v146
	v_cmp_lt_i32_e32 vcc, v141, v146
	s_nop 1
	v_cndmask_b32_e32 v141, v164, v141, vcc
	v_lshlrev_b32_e32 v141, 2, v141
	v_mov_b32_e32 v141, v138
	s_nop 1
	v_permlane16_swap_b32 v141, v138
	s_waitcnt lgkmcnt(0)
	v_add_f32_e32 v138, v138, v141
	v_xor_b32_e32 v141, 32, v164
	v_cmp_lt_i32_e32 vcc, v141, v146
	s_nop 1
	v_cndmask_b32_e32 v141, v164, v141, vcc
	v_lshlrev_b32_e32 v141, 2, v141
	v_mov_b32_e32 v141, v138
	s_nop 1
	v_permlane32_swap_b32 v141, v138
	s_and_saveexec_b64 s[6:7], s[4:5]
	s_cbranch_execz .LBB0_1598
	v_ashrrev_i32_e32 v153, 31, v152
	v_lshlrev_b64 v[158:159], 6, v[152:153]
	v_lshl_add_u64 v[158:159], s[56:57], 0, v[158:159]
	s_waitcnt lgkmcnt(0)
	v_add_f32_e32 v138, v138, v141
	global_store_dword v[158:159], v138, off

.LBB0_1599:
	v_or_b32_e32 v158, 16, v152
	v_mad_i64_i32 v[166:167], s[6:7], s47, v158, 0
	v_cndmask_b32_e64 v138, 0, 1, s[58:59]
	v_lshl_add_u64 v[170:171], v[166:167], 1, v[156:157]
	v_cvt_pk_bf16_f32 v166, v110, v111
	v_cvt_pk_bf16_f32 v167, v112, v113
	v_cvt_pk_bf16_f32 v168, v102, v103
	v_cvt_pk_bf16_f32 v169, v104, v105
	v_cmp_ne_u32_e64 s[6:7], 1, v138
	s_andn2_b64 vcc, exec, s[58:59]
	global_store_dwordx4 v[170:171], v[166:169], off
	s_nop 1
	v_cvt_pk_bf16_f32 v166, v106, v107
	v_cvt_pk_bf16_f32 v167, v108, v109
	v_cvt_pk_bf16_f32 v168, v98, v99
	v_cvt_pk_bf16_f32 v169, v100, v101
	global_store_dwordx4 v[170:171], v[166:169], off offset:256
	s_cbranch_vccnz .LBB0_1603
	s_waitcnt lgkmcnt(0)
	v_mul_f32_e32 v141, v111, v111
	v_mul_f32_e32 v146, v113, v113
	v_fmac_f32_e32 v141, v110, v110
	v_fmac_f32_e32 v146, v112, v112
	v_add_f32_e32 v141, v141, v146
	v_mul_f32_e32 v146, v103, v103
	v_fmac_f32_e32 v146, v102, v102
	v_add_f32_e32 v141, v146, v141
	v_mul_f32_e32 v146, v107, v107
	v_mul_f32_e32 v153, v109, v109
	v_mul_f32_e32 v138, v105, v105
	v_fmac_f32_e32 v146, v106, v106
	v_fmac_f32_e32 v153, v108, v108
	v_fmac_f32_e32 v138, v104, v104
	v_add_f32_e32 v146, v146, v153
	v_mul_f32_e32 v153, v99, v99
	v_add_f32_e32 v138, v138, v141
	v_mul_f32_e32 v141, v101, v101
	v_fmac_f32_e32 v153, v98, v98
	v_fmac_f32_e32 v141, v100, v100
	v_add_f32_e32 v146, v153, v146
	v_add_f32_e32 v141, v141, v146
	v_and_b32_e32 v146, 64, v164
	v_add_f32_e32 v138, v141, v138
	v_xor_b32_e32 v141, 16, v164
	v_add_u32_e32 v146, 64, v146
	v_cmp_lt_i32_e32 vcc, v141, v146
	s_nop 1
	v_cndmask_b32_e32 v141, v164, v141, vcc
	v_lshlrev_b32_e32 v141, 2, v141
	v_mov_b32_e32 v141, v138
	s_nop 1
	v_permlane16_swap_b32 v141, v138
	s_waitcnt lgkmcnt(0)
	v_add_f32_e32 v138, v138, v141
	v_xor_b32_e32 v141, 32, v164
	v_cmp_lt_i32_e32 vcc, v141, v146
	s_nop 1
	v_cndmask_b32_e32 v141, v164, v141, vcc
	v_lshlrev_b32_e32 v141, 2, v141
	v_mov_b32_e32 v141, v138
	s_nop 1
	v_permlane32_swap_b32 v141, v138
	s_and_saveexec_b64 s[58:59], s[4:5]
	s_cbranch_execz .LBB0_1602
	v_ashrrev_i32_e32 v159, 31, v158
	v_lshlrev_b64 v[158:159], 6, v[158:159]
	v_lshl_add_u64 v[158:159], s[56:57], 0, v[158:159]
	s_waitcnt lgkmcnt(0)
	v_add_f32_e32 v138, v138, v141
	global_store_dword v[158:159], v138, off

.LBB0_1603:
	v_or_b32_e32 v158, 32, v152
	v_mad_i64_i32 v[166:167], s[58:59], s47, v158, 0
	v_lshl_add_u64 v[170:171], v[166:167], 1, v[156:157]
	v_cvt_pk_bf16_f32 v166, v94, v95
	v_cvt_pk_bf16_f32 v167, v96, v97
	v_cvt_pk_bf16_f32 v168, v86, v87
	v_cvt_pk_bf16_f32 v169, v88, v89
	s_and_b64 vcc, exec, s[6:7]
	global_store_dwordx4 v[170:171], v[166:169], off
	s_nop 1
	v_cvt_pk_bf16_f32 v166, v90, v91
	v_cvt_pk_bf16_f32 v167, v92, v93
	v_cvt_pk_bf16_f32 v168, v82, v83
	v_cvt_pk_bf16_f32 v169, v84, v85
	global_store_dwordx4 v[170:171], v[166:169], off offset:256
	s_cbranch_vccnz .LBB0_1607
	s_waitcnt lgkmcnt(0)
	v_mul_f32_e32 v141, v95, v95
	v_mul_f32_e32 v146, v97, v97
	v_fmac_f32_e32 v141, v94, v94
	v_fmac_f32_e32 v146, v96, v96
	v_add_f32_e32 v141, v141, v146
	v_mul_f32_e32 v146, v87, v87
	v_fmac_f32_e32 v146, v86, v86
	v_add_f32_e32 v141, v146, v141
	v_mul_f32_e32 v146, v91, v91
	v_mul_f32_e32 v153, v93, v93
	v_mul_f32_e32 v138, v89, v89
	v_fmac_f32_e32 v146, v90, v90
	v_fmac_f32_e32 v153, v92, v92
	v_fmac_f32_e32 v138, v88, v88
	v_add_f32_e32 v146, v146, v153
	v_mul_f32_e32 v153, v83, v83
	v_add_f32_e32 v138, v138, v141
	v_mul_f32_e32 v141, v85, v85
	v_fmac_f32_e32 v153, v82, v82
	v_fmac_f32_e32 v141, v84, v84
	v_add_f32_e32 v146, v153, v146
	v_add_f32_e32 v141, v141, v146
	v_and_b32_e32 v146, 64, v164
	v_add_f32_e32 v138, v141, v138
	v_xor_b32_e32 v141, 16, v164
	v_add_u32_e32 v146, 64, v146
	v_cmp_lt_i32_e32 vcc, v141, v146
	s_nop 1
	v_cndmask_b32_e32 v141, v164, v141, vcc
	v_lshlrev_b32_e32 v141, 2, v141
	v_mov_b32_e32 v141, v138
	s_nop 1
	v_permlane16_swap_b32 v141, v138
	s_waitcnt lgkmcnt(0)
	v_add_f32_e32 v138, v138, v141
	v_xor_b32_e32 v141, 32, v164
	v_cmp_lt_i32_e32 vcc, v141, v146
	s_nop 1
	v_cndmask_b32_e32 v141, v164, v141, vcc
	v_lshlrev_b32_e32 v141, 2, v141
	v_mov_b32_e32 v141, v138
	s_nop 1
	v_permlane32_swap_b32 v141, v138
	s_and_saveexec_b64 s[58:59], s[4:5]
	s_cbranch_execz .LBB0_1606
	v_ashrrev_i32_e32 v159, 31, v158
	v_lshlrev_b64 v[158:159], 6, v[158:159]
	v_lshl_add_u64 v[158:159], s[56:57], 0, v[158:159]
	s_waitcnt lgkmcnt(0)
	v_add_f32_e32 v138, v138, v141
	global_store_dword v[158:159], v138, off

.LBB0_1607:
	v_or_b32_e32 v158, 48, v152
	v_mad_i64_i32 v[166:167], s[58:59], s47, v158, 0
	v_lshl_add_u64 v[170:171], v[166:167], 1, v[156:157]
	v_cvt_pk_bf16_f32 v166, v78, v79
	v_cvt_pk_bf16_f32 v167, v80, v81
	v_cvt_pk_bf16_f32 v168, v70, v71
	v_cvt_pk_bf16_f32 v169, v72, v73
	s_and_b64 vcc, exec, s[6:7]
	global_store_dwordx4 v[170:171], v[166:169], off
	s_nop 1
	v_cvt_pk_bf16_f32 v166, v74, v75
	v_cvt_pk_bf16_f32 v167, v76, v77
	v_cvt_pk_bf16_f32 v168, v66, v67
	v_cvt_pk_bf16_f32 v169, v68, v69
	global_store_dwordx4 v[170:171], v[166:169], off offset:256
	s_cbranch_vccnz .LBB0_1611
	s_waitcnt lgkmcnt(0)
	v_mul_f32_e32 v141, v79, v79
	v_mul_f32_e32 v146, v81, v81
	v_fmac_f32_e32 v141, v78, v78
	v_fmac_f32_e32 v146, v80, v80
	v_add_f32_e32 v141, v141, v146
	v_mul_f32_e32 v146, v71, v71
	v_fmac_f32_e32 v146, v70, v70
	v_add_f32_e32 v141, v146, v141
	v_mul_f32_e32 v146, v75, v75
	v_mul_f32_e32 v153, v77, v77
	v_mul_f32_e32 v138, v73, v73
	v_fmac_f32_e32 v146, v74, v74
	v_fmac_f32_e32 v153, v76, v76
	v_fmac_f32_e32 v138, v72, v72
	v_add_f32_e32 v146, v146, v153
	v_mul_f32_e32 v153, v67, v67
	v_add_f32_e32 v138, v138, v141
	v_mul_f32_e32 v141, v69, v69
	v_fmac_f32_e32 v153, v66, v66
	v_fmac_f32_e32 v141, v68, v68
	v_add_f32_e32 v146, v153, v146
	v_add_f32_e32 v141, v141, v146
	v_and_b32_e32 v146, 64, v164
	v_add_f32_e32 v138, v141, v138
	v_xor_b32_e32 v141, 16, v164
	v_add_u32_e32 v146, 64, v146
	v_cmp_lt_i32_e32 vcc, v141, v146
	s_nop 1
	v_cndmask_b32_e32 v141, v164, v141, vcc
	v_lshlrev_b32_e32 v141, 2, v141
	v_mov_b32_e32 v141, v138
	s_nop 1
	v_permlane16_swap_b32 v141, v138
	s_waitcnt lgkmcnt(0)
	v_add_f32_e32 v138, v138, v141
	v_xor_b32_e32 v141, 32, v164
	v_cmp_lt_i32_e32 vcc, v141, v146
	s_nop 1
	v_cndmask_b32_e32 v141, v164, v141, vcc
	v_lshlrev_b32_e32 v141, 2, v141
	v_mov_b32_e32 v141, v138
	s_nop 1
	v_permlane32_swap_b32 v141, v138
	s_and_saveexec_b64 s[58:59], s[4:5]
	s_cbranch_execz .LBB0_1610
	v_ashrrev_i32_e32 v159, 31, v158
	v_lshlrev_b64 v[158:159], 6, v[158:159]
	v_lshl_add_u64 v[158:159], s[56:57], 0, v[158:159]
	s_waitcnt lgkmcnt(0)
	v_add_f32_e32 v138, v138, v141
	global_store_dword v[158:159], v138, off

.LBB0_1611:
	v_add_u32_e32 v158, 0x80, v152
	v_mad_i64_i32 v[166:167], s[58:59], s47, v158, 0
	v_lshl_add_u64 v[170:171], v[166:167], 1, v[156:157]
	v_cvt_pk_bf16_f32 v166, v62, v63
	v_cvt_pk_bf16_f32 v167, v64, v65
	v_cvt_pk_bf16_f32 v168, v54, v55
	v_cvt_pk_bf16_f32 v169, v56, v57
	s_and_b64 vcc, exec, s[6:7]
	global_store_dwordx4 v[170:171], v[166:169], off
	s_nop 1
	v_cvt_pk_bf16_f32 v166, v58, v59
	v_cvt_pk_bf16_f32 v167, v60, v61
	v_cvt_pk_bf16_f32 v168, v50, v51
	v_cvt_pk_bf16_f32 v169, v52, v53
	global_store_dwordx4 v[170:171], v[166:169], off offset:256
	s_cbranch_vccnz .LBB0_1615
	s_waitcnt lgkmcnt(0)
	v_mul_f32_e32 v141, v63, v63
	v_mul_f32_e32 v146, v65, v65
	v_fmac_f32_e32 v141, v62, v62
	v_fmac_f32_e32 v146, v64, v64
	v_add_f32_e32 v141, v141, v146
	v_mul_f32_e32 v146, v55, v55
	v_fmac_f32_e32 v146, v54, v54
	v_add_f32_e32 v141, v146, v141
	v_mul_f32_e32 v146, v59, v59
	v_mul_f32_e32 v153, v61, v61
	v_mul_f32_e32 v138, v57, v57
	v_fmac_f32_e32 v146, v58, v58
	v_fmac_f32_e32 v153, v60, v60
	v_fmac_f32_e32 v138, v56, v56
	v_add_f32_e32 v146, v146, v153
	v_mul_f32_e32 v153, v51, v51
	v_add_f32_e32 v138, v138, v141
	v_mul_f32_e32 v141, v53, v53
	v_fmac_f32_e32 v153, v50, v50
	v_fmac_f32_e32 v141, v52, v52
	v_add_f32_e32 v146, v153, v146
	v_add_f32_e32 v141, v141, v146
	v_and_b32_e32 v146, 64, v164
	v_add_f32_e32 v138, v141, v138
	v_xor_b32_e32 v141, 16, v164
	v_add_u32_e32 v146, 64, v146
	v_cmp_lt_i32_e32 vcc, v141, v146
	s_nop 1
	v_cndmask_b32_e32 v141, v164, v141, vcc
	v_lshlrev_b32_e32 v141, 2, v141
	v_mov_b32_e32 v141, v138
	s_nop 1
	v_permlane16_swap_b32 v141, v138
	s_waitcnt lgkmcnt(0)
	v_add_f32_e32 v138, v138, v141
	v_xor_b32_e32 v141, 32, v164
	v_cmp_lt_i32_e32 vcc, v141, v146
	s_nop 1
	v_cndmask_b32_e32 v141, v164, v141, vcc
	v_lshlrev_b32_e32 v141, 2, v141
	v_mov_b32_e32 v141, v138
	s_nop 1
	v_permlane32_swap_b32 v141, v138
	s_and_saveexec_b64 s[58:59], s[4:5]
	s_cbranch_execz .LBB0_1614
	v_ashrrev_i32_e32 v159, 31, v158
	v_lshlrev_b64 v[158:159], 6, v[158:159]
	v_lshl_add_u64 v[158:159], s[56:57], 0, v[158:159]
	s_waitcnt lgkmcnt(0)
	v_add_f32_e32 v138, v138, v141
	global_store_dword v[158:159], v138, off

.LBB0_1615:
	v_add_u32_e32 v158, 0x90, v152
	v_mad_i64_i32 v[166:167], s[58:59], s47, v158, 0
	v_lshl_add_u64 v[170:171], v[166:167], 1, v[156:157]
	v_cvt_pk_bf16_f32 v166, v46, v47
	v_cvt_pk_bf16_f32 v167, v48, v49
	v_cvt_pk_bf16_f32 v168, v38, v39
	v_cvt_pk_bf16_f32 v169, v40, v41
	s_and_b64 vcc, exec, s[6:7]
	global_store_dwordx4 v[170:171], v[166:169], off
	s_nop 1
	v_cvt_pk_bf16_f32 v166, v42, v43
	v_cvt_pk_bf16_f32 v167, v44, v45
	v_cvt_pk_bf16_f32 v168, v34, v35
	v_cvt_pk_bf16_f32 v169, v36, v37
	global_store_dwordx4 v[170:171], v[166:169], off offset:256
	s_cbranch_vccnz .LBB0_1619
	s_waitcnt lgkmcnt(0)
	v_mul_f32_e32 v141, v47, v47
	v_mul_f32_e32 v146, v49, v49
	v_fmac_f32_e32 v141, v46, v46
	v_fmac_f32_e32 v146, v48, v48
	v_add_f32_e32 v141, v141, v146
	v_mul_f32_e32 v146, v39, v39
	v_fmac_f32_e32 v146, v38, v38
	v_add_f32_e32 v141, v146, v141
	v_mul_f32_e32 v146, v43, v43
	v_mul_f32_e32 v153, v45, v45
	v_mul_f32_e32 v138, v41, v41
	v_fmac_f32_e32 v146, v42, v42
	v_fmac_f32_e32 v153, v44, v44
	v_fmac_f32_e32 v138, v40, v40
	v_add_f32_e32 v146, v146, v153
	v_mul_f32_e32 v153, v35, v35
	v_add_f32_e32 v138, v138, v141
	v_mul_f32_e32 v141, v37, v37
	v_fmac_f32_e32 v153, v34, v34
	v_fmac_f32_e32 v141, v36, v36
	v_add_f32_e32 v146, v153, v146
	v_add_f32_e32 v141, v141, v146
	v_and_b32_e32 v146, 64, v164
	v_add_f32_e32 v138, v141, v138
	v_xor_b32_e32 v141, 16, v164
	v_add_u32_e32 v146, 64, v146
	v_cmp_lt_i32_e32 vcc, v141, v146
	s_nop 1
	v_cndmask_b32_e32 v141, v164, v141, vcc
	v_lshlrev_b32_e32 v141, 2, v141
	v_mov_b32_e32 v141, v138
	s_nop 1
	v_permlane16_swap_b32 v141, v138
	s_waitcnt lgkmcnt(0)
	v_add_f32_e32 v138, v138, v141
	v_xor_b32_e32 v141, 32, v164
	v_cmp_lt_i32_e32 vcc, v141, v146
	s_nop 1
	v_cndmask_b32_e32 v141, v164, v141, vcc
	v_lshlrev_b32_e32 v141, 2, v141
	v_mov_b32_e32 v141, v138
	s_nop 1
	v_permlane32_swap_b32 v141, v138
	s_and_saveexec_b64 s[58:59], s[4:5]
	s_cbranch_execz .LBB0_1618
	v_ashrrev_i32_e32 v159, 31, v158
	v_lshlrev_b64 v[158:159], 6, v[158:159]
	v_lshl_add_u64 v[158:159], s[56:57], 0, v[158:159]
	s_waitcnt lgkmcnt(0)
	v_add_f32_e32 v138, v138, v141
	global_store_dword v[158:159], v138, off

.LBB0_1619:
	v_add_u32_e32 v158, 0xa0, v152
	v_mad_i64_i32 v[166:167], s[58:59], s47, v158, 0
	v_lshl_add_u64 v[170:171], v[166:167], 1, v[156:157]
	v_cvt_pk_bf16_f32 v166, v30, v31
	v_cvt_pk_bf16_f32 v167, v32, v33
	v_cvt_pk_bf16_f32 v168, v22, v23
	v_cvt_pk_bf16_f32 v169, v24, v25
	s_and_b64 vcc, exec, s[6:7]
	global_store_dwordx4 v[170:171], v[166:169], off
	s_nop 1
	v_cvt_pk_bf16_f32 v166, v26, v27
	v_cvt_pk_bf16_f32 v167, v28, v29
	v_cvt_pk_bf16_f32 v168, v18, v19
	v_cvt_pk_bf16_f32 v169, v20, v21
	global_store_dwordx4 v[170:171], v[166:169], off offset:256
	s_cbranch_vccnz .LBB0_1623
	s_waitcnt lgkmcnt(0)
	v_mul_f32_e32 v141, v31, v31
	v_mul_f32_e32 v146, v33, v33
	v_fmac_f32_e32 v141, v30, v30
	v_fmac_f32_e32 v146, v32, v32
	v_add_f32_e32 v141, v141, v146
	v_mul_f32_e32 v146, v23, v23
	v_fmac_f32_e32 v146, v22, v22
	v_add_f32_e32 v141, v146, v141
	v_mul_f32_e32 v146, v27, v27
	v_mul_f32_e32 v153, v29, v29
	v_mul_f32_e32 v138, v25, v25
	v_fmac_f32_e32 v146, v26, v26
	v_fmac_f32_e32 v153, v28, v28
	v_fmac_f32_e32 v138, v24, v24
	v_add_f32_e32 v146, v146, v153
	v_mul_f32_e32 v153, v19, v19
	v_add_f32_e32 v138, v138, v141
	v_mul_f32_e32 v141, v21, v21
	v_fmac_f32_e32 v153, v18, v18
	v_fmac_f32_e32 v141, v20, v20
	v_add_f32_e32 v146, v153, v146
	v_add_f32_e32 v141, v141, v146
	v_and_b32_e32 v146, 64, v164
	v_add_f32_e32 v138, v141, v138
	v_xor_b32_e32 v141, 16, v164
	v_add_u32_e32 v146, 64, v146
	v_cmp_lt_i32_e32 vcc, v141, v146
	s_nop 1
	v_cndmask_b32_e32 v141, v164, v141, vcc
	v_lshlrev_b32_e32 v141, 2, v141
	v_mov_b32_e32 v141, v138
	s_nop 1
	v_permlane16_swap_b32 v141, v138
	s_waitcnt lgkmcnt(0)
	v_add_f32_e32 v138, v138, v141
	v_xor_b32_e32 v141, 32, v164
	v_cmp_lt_i32_e32 vcc, v141, v146
	s_nop 1
	v_cndmask_b32_e32 v141, v164, v141, vcc
	v_lshlrev_b32_e32 v141, 2, v141
	v_mov_b32_e32 v141, v138
	s_nop 1
	v_permlane32_swap_b32 v141, v138
	s_and_saveexec_b64 s[58:59], s[4:5]
	s_cbranch_execz .LBB0_1622
	v_ashrrev_i32_e32 v159, 31, v158
	v_lshlrev_b64 v[158:159], 6, v[158:159]
	v_lshl_add_u64 v[158:159], s[56:57], 0, v[158:159]
	s_waitcnt lgkmcnt(0)
	v_add_f32_e32 v138, v138, v141
	global_store_dword v[158:159], v138, off

.LBB0_1623:
	v_add_u32_e32 v158, 0xb0, v152
	v_mad_i64_i32 v[166:167], s[58:59], s47, v158, 0
	v_lshl_add_u64 v[156:157], v[166:167], 1, v[156:157]
	v_cvt_pk_bf16_f32 v166, v14, v15
	v_cvt_pk_bf16_f32 v167, v16, v17
	v_cvt_pk_bf16_f32 v168, v6, v7
	v_cvt_pk_bf16_f32 v169, v8, v9
	s_and_b64 vcc, exec, s[6:7]
	global_store_dwordx4 v[156:157], v[166:169], off
	s_nop 1
	v_cvt_pk_bf16_f32 v166, v10, v11
	v_cvt_pk_bf16_f32 v167, v12, v13
	v_cvt_pk_bf16_f32 v168, v2, v3
	v_cvt_pk_bf16_f32 v169, v4, v5
	global_store_dwordx4 v[156:157], v[166:169], off offset:256
	s_cbranch_vccnz .LBB0_1627
	s_waitcnt lgkmcnt(0)
	v_mul_f32_e32 v141, v15, v15
	v_mul_f32_e32 v146, v17, v17
	v_fmac_f32_e32 v141, v14, v14
	v_fmac_f32_e32 v146, v16, v16
	v_add_f32_e32 v141, v141, v146
	v_mul_f32_e32 v146, v7, v7
	v_fmac_f32_e32 v146, v6, v6
	v_add_f32_e32 v141, v146, v141
	v_mul_f32_e32 v146, v11, v11
	v_mul_f32_e32 v153, v13, v13
	v_mul_f32_e32 v138, v9, v9
	v_fmac_f32_e32 v146, v10, v10
	v_fmac_f32_e32 v153, v12, v12
	v_fmac_f32_e32 v138, v8, v8
	v_add_f32_e32 v146, v146, v153
	v_mul_f32_e32 v153, v3, v3
	v_add_f32_e32 v138, v138, v141
	v_mul_f32_e32 v141, v5, v5
	v_fmac_f32_e32 v153, v2, v2
	v_fmac_f32_e32 v141, v4, v4
	v_add_f32_e32 v146, v153, v146
	v_add_f32_e32 v141, v141, v146
	v_and_b32_e32 v146, 64, v164
	v_add_f32_e32 v138, v141, v138
	v_xor_b32_e32 v141, 16, v164
	v_add_u32_e32 v146, 64, v146
	v_cmp_lt_i32_e32 vcc, v141, v146
	s_nop 1
	v_cndmask_b32_e32 v141, v164, v141, vcc
	v_lshlrev_b32_e32 v141, 2, v141
	v_mov_b32_e32 v141, v138
	s_nop 1
	v_permlane16_swap_b32 v141, v138
	s_waitcnt lgkmcnt(0)
	v_add_f32_e32 v138, v138, v141
	v_xor_b32_e32 v141, 32, v164
	v_cmp_lt_i32_e32 vcc, v141, v146
	s_nop 1
	v_cndmask_b32_e32 v141, v164, v141, vcc
	v_lshlrev_b32_e32 v141, 2, v141
	v_mov_b32_e32 v141, v138
	s_nop 1
	v_permlane32_swap_b32 v141, v138
	s_and_saveexec_b64 s[6:7], s[4:5]
	s_cbranch_execz .LBB0_1626
	v_ashrrev_i32_e32 v159, 31, v158
	v_lshlrev_b64 v[156:157], 6, v[158:159]
	v_lshl_add_u64 v[156:157], s[56:57], 0, v[156:157]
	s_waitcnt lgkmcnt(0)
	v_add_f32_e32 v138, v138, v141
	global_store_dword v[156:157], v138, off

.LBB0_1784:
	s_and_b64 vcc, exec, s[48:49]
	s_cbranch_vccz .LBB0_1819
	s_cmp_eq_u32 s45, 4
	s_cselect_b64 s[50:51], -1, 0
	s_lshl_b32 s4, s46, 2
	s_ashr_i32 s5, s4, 31
	v_lshl_or_b32 v154, s46, 8, v159
	s_lshl_b64 s[4:5], s[4:5], 2
	v_ashrrev_i32_e32 v155, 31, v154
	s_add_u32 s48, s66, s4
	v_lshl_add_u64 v[154:155], v[154:155], 1, v[152:153]
	s_addc_u32 s49, s67, s5
	v_mad_i64_i32 v[156:157], s[4:5], s29, v150, 0
	s_cmp_lg_u32 s45, 4
	v_lshl_add_u64 v[156:157], v[156:157], 1, v[154:155]
	v_cvt_pk_bf16_f32 v164, v122, v123
	v_cvt_pk_bf16_f32 v165, v124, v125
	v_cvt_pk_bf16_f32 v166, v118, v119
	v_cvt_pk_bf16_f32 v167, v120, v121
	global_store_dwordx4 v[156:157], v[164:167], off
	s_nop 1
	v_cvt_pk_bf16_f32 v164, v126, v127
	v_cvt_pk_bf16_f32 v165, v128, v129
	v_cvt_pk_bf16_f32 v166, v114, v115
	v_cvt_pk_bf16_f32 v167, v116, v117
	global_store_dwordx4 v[156:157], v[164:167], off offset:256
	s_cbranch_scc1 .LBB0_1789
	v_mul_f32_e32 v151, v123, v123
	v_mul_f32_e32 v156, v125, v125
	v_fmac_f32_e32 v151, v122, v122
	v_fmac_f32_e32 v156, v124, v124
	v_add_f32_e32 v151, v151, v156
	v_mul_f32_e32 v156, v119, v119
	v_fmac_f32_e32 v156, v118, v118
	v_add_f32_e32 v151, v156, v151
	v_mul_f32_e32 v156, v127, v127
	v_mul_f32_e32 v157, v129, v129
	v_mul_f32_e32 v138, v121, v121
	v_fmac_f32_e32 v156, v126, v126
	v_fmac_f32_e32 v157, v128, v128
	v_fmac_f32_e32 v138, v120, v120
	v_add_f32_e32 v156, v156, v157
	v_mul_f32_e32 v157, v115, v115
	v_add_f32_e32 v138, v138, v151
	v_mul_f32_e32 v151, v117, v117
	v_fmac_f32_e32 v157, v114, v114
	v_fmac_f32_e32 v151, v116, v116
	v_add_f32_e32 v156, v157, v156
	v_add_f32_e32 v151, v151, v156
	v_and_b32_e32 v156, 64, v161
	v_add_f32_e32 v138, v151, v138
	v_xor_b32_e32 v151, 16, v161
	v_add_u32_e32 v156, 64, v156
	v_cmp_lt_i32_e32 vcc, v151, v156
	s_nop 1
	v_cndmask_b32_e32 v151, v161, v151, vcc
	v_lshlrev_b32_e32 v151, 2, v151
	v_mov_b32_e32 v151, v138
	s_nop 1
	v_permlane16_swap_b32 v151, v138
	s_waitcnt lgkmcnt(0)
	v_add_f32_e32 v138, v138, v151
	v_xor_b32_e32 v151, 32, v161
	v_cmp_lt_i32_e32 vcc, v151, v156
	s_nop 1
	v_cndmask_b32_e32 v151, v161, v151, vcc
	v_lshlrev_b32_e32 v151, 2, v151
	v_mov_b32_e32 v156, v138
	s_nop 1
	v_permlane32_swap_b32 v156, v138
	s_and_saveexec_b64 s[4:5], s[0:1]
	s_cbranch_execz .LBB0_1788
	v_ashrrev_i32_e32 v151, 31, v150
	s_waitcnt lgkmcnt(0)
	v_add_f32_e32 v138, v138, v156
	v_lshlrev_b64 v[156:157], 6, v[150:151]
	v_lshl_add_u64 v[156:157], s[48:49], 0, v[156:157]
	global_store_dword v[156:157], v138, off

.LBB0_1789:
	s_waitcnt lgkmcnt(0)
	v_or_b32_e32 v156, 16, v150
	v_mad_i64_i32 v[164:165], s[4:5], s29, v156, 0
	v_cndmask_b32_e64 v138, 0, 1, s[50:51]
	v_lshl_add_u64 v[168:169], v[164:165], 1, v[154:155]
	v_cvt_pk_bf16_f32 v164, v110, v111
	v_cvt_pk_bf16_f32 v165, v112, v113
	v_cvt_pk_bf16_f32 v166, v102, v103
	v_cvt_pk_bf16_f32 v167, v104, v105
	v_cmp_ne_u32_e64 s[4:5], 1, v138
	s_andn2_b64 vcc, exec, s[50:51]
	global_store_dwordx4 v[168:169], v[164:167], off
	s_nop 1
	v_cvt_pk_bf16_f32 v164, v106, v107
	v_cvt_pk_bf16_f32 v165, v108, v109
	v_cvt_pk_bf16_f32 v166, v98, v99
	v_cvt_pk_bf16_f32 v167, v100, v101
	global_store_dwordx4 v[168:169], v[164:167], off offset:256
	s_cbranch_vccnz .LBB0_1793
	v_mul_f32_e32 v151, v111, v111
	v_mul_f32_e32 v157, v113, v113
	v_fmac_f32_e32 v151, v110, v110
	v_fmac_f32_e32 v157, v112, v112
	v_add_f32_e32 v151, v151, v157
	v_mul_f32_e32 v157, v103, v103
	v_fmac_f32_e32 v157, v102, v102
	v_add_f32_e32 v151, v157, v151
	v_mul_f32_e32 v157, v107, v107
	v_mul_f32_e32 v163, v109, v109
	v_mul_f32_e32 v138, v105, v105
	v_fmac_f32_e32 v157, v106, v106
	v_fmac_f32_e32 v163, v108, v108
	v_fmac_f32_e32 v138, v104, v104
	v_add_f32_e32 v157, v157, v163
	v_mul_f32_e32 v163, v99, v99
	v_add_f32_e32 v138, v138, v151
	v_mul_f32_e32 v151, v101, v101
	v_fmac_f32_e32 v163, v98, v98
	v_fmac_f32_e32 v151, v100, v100
	v_add_f32_e32 v157, v163, v157
	v_add_f32_e32 v151, v151, v157
	v_and_b32_e32 v157, 64, v161
	v_add_f32_e32 v138, v151, v138
	v_xor_b32_e32 v151, 16, v161
	v_add_u32_e32 v157, 64, v157
	v_cmp_lt_i32_e32 vcc, v151, v157
	s_nop 1
	v_cndmask_b32_e32 v151, v161, v151, vcc
	v_lshlrev_b32_e32 v151, 2, v151
	v_mov_b32_e32 v151, v138
	s_nop 1
	v_permlane16_swap_b32 v151, v138
	s_waitcnt lgkmcnt(0)
	v_add_f32_e32 v138, v138, v151
	v_xor_b32_e32 v151, 32, v161
	v_cmp_lt_i32_e32 vcc, v151, v157
	s_nop 1
	v_cndmask_b32_e32 v151, v161, v151, vcc
	v_lshlrev_b32_e32 v151, 2, v151
	v_mov_b32_e32 v151, v138
	s_nop 1
	v_permlane32_swap_b32 v151, v138
	s_and_saveexec_b64 s[50:51], s[0:1]
	s_cbranch_execz .LBB0_1792
	v_ashrrev_i32_e32 v157, 31, v156
	v_lshlrev_b64 v[156:157], 6, v[156:157]
	s_waitcnt lgkmcnt(0)
	v_add_f32_e32 v138, v138, v151
	v_lshl_add_u64 v[156:157], s[48:49], 0, v[156:157]
	global_store_dword v[156:157], v138, off

.LBB0_1793:
	v_or_b32_e32 v156, 32, v150
	v_mad_i64_i32 v[164:165], s[50:51], s29, v156, 0
	v_lshl_add_u64 v[168:169], v[164:165], 1, v[154:155]
	v_cvt_pk_bf16_f32 v164, v94, v95
	v_cvt_pk_bf16_f32 v165, v96, v97
	v_cvt_pk_bf16_f32 v166, v86, v87
	v_cvt_pk_bf16_f32 v167, v88, v89
	s_and_b64 vcc, exec, s[4:5]
	global_store_dwordx4 v[168:169], v[164:167], off
	s_nop 1
	v_cvt_pk_bf16_f32 v164, v90, v91
	v_cvt_pk_bf16_f32 v165, v92, v93
	v_cvt_pk_bf16_f32 v166, v82, v83
	v_cvt_pk_bf16_f32 v167, v84, v85
	global_store_dwordx4 v[168:169], v[164:167], off offset:256
	s_cbranch_vccnz .LBB0_1797
	s_waitcnt lgkmcnt(0)
	v_mul_f32_e32 v151, v95, v95
	v_mul_f32_e32 v157, v97, v97
	v_fmac_f32_e32 v151, v94, v94
	v_fmac_f32_e32 v157, v96, v96
	v_add_f32_e32 v151, v151, v157
	v_mul_f32_e32 v157, v87, v87
	v_fmac_f32_e32 v157, v86, v86
	v_add_f32_e32 v151, v157, v151
	v_mul_f32_e32 v157, v91, v91
	v_mul_f32_e32 v163, v93, v93
	v_mul_f32_e32 v138, v89, v89
	v_fmac_f32_e32 v157, v90, v90
	v_fmac_f32_e32 v163, v92, v92
	v_fmac_f32_e32 v138, v88, v88
	v_add_f32_e32 v157, v157, v163
	v_mul_f32_e32 v163, v83, v83
	v_add_f32_e32 v138, v138, v151
	v_mul_f32_e32 v151, v85, v85
	v_fmac_f32_e32 v163, v82, v82
	v_fmac_f32_e32 v151, v84, v84
	v_add_f32_e32 v157, v163, v157
	v_add_f32_e32 v151, v151, v157
	v_and_b32_e32 v157, 64, v161
	v_add_f32_e32 v138, v151, v138
	v_xor_b32_e32 v151, 16, v161
	v_add_u32_e32 v157, 64, v157
	v_cmp_lt_i32_e32 vcc, v151, v157
	s_nop 1
	v_cndmask_b32_e32 v151, v161, v151, vcc
	v_lshlrev_b32_e32 v151, 2, v151
	v_mov_b32_e32 v151, v138
	s_nop 1
	v_permlane16_swap_b32 v151, v138
	s_waitcnt lgkmcnt(0)
	v_add_f32_e32 v138, v138, v151
	v_xor_b32_e32 v151, 32, v161
	v_cmp_lt_i32_e32 vcc, v151, v157
	s_nop 1
	v_cndmask_b32_e32 v151, v161, v151, vcc
	v_lshlrev_b32_e32 v151, 2, v151
	v_mov_b32_e32 v151, v138
	s_nop 1
	v_permlane32_swap_b32 v151, v138
	s_and_saveexec_b64 s[50:51], s[0:1]
	s_cbranch_execz .LBB0_1796
	v_ashrrev_i32_e32 v157, 31, v156
	v_lshlrev_b64 v[156:157], 6, v[156:157]
	s_waitcnt lgkmcnt(0)
	v_add_f32_e32 v138, v138, v151
	v_lshl_add_u64 v[156:157], s[48:49], 0, v[156:157]
	global_store_dword v[156:157], v138, off

.LBB0_1797:
	v_or_b32_e32 v156, 48, v150
	v_mad_i64_i32 v[164:165], s[50:51], s29, v156, 0
	v_lshl_add_u64 v[168:169], v[164:165], 1, v[154:155]
	v_cvt_pk_bf16_f32 v164, v78, v79
	v_cvt_pk_bf16_f32 v165, v80, v81
	v_cvt_pk_bf16_f32 v166, v70, v71
	v_cvt_pk_bf16_f32 v167, v72, v73
	s_and_b64 vcc, exec, s[4:5]
	global_store_dwordx4 v[168:169], v[164:167], off
	s_nop 1
	v_cvt_pk_bf16_f32 v164, v74, v75
	v_cvt_pk_bf16_f32 v165, v76, v77
	v_cvt_pk_bf16_f32 v166, v66, v67
	v_cvt_pk_bf16_f32 v167, v68, v69
	global_store_dwordx4 v[168:169], v[164:167], off offset:256
	s_cbranch_vccnz .LBB0_1801
	s_waitcnt lgkmcnt(0)
	v_mul_f32_e32 v151, v79, v79
	v_mul_f32_e32 v157, v81, v81
	v_fmac_f32_e32 v151, v78, v78
	v_fmac_f32_e32 v157, v80, v80
	v_add_f32_e32 v151, v151, v157
	v_mul_f32_e32 v157, v71, v71
	v_fmac_f32_e32 v157, v70, v70
	v_add_f32_e32 v151, v157, v151
	v_mul_f32_e32 v157, v75, v75
	v_mul_f32_e32 v163, v77, v77
	v_mul_f32_e32 v138, v73, v73
	v_fmac_f32_e32 v157, v74, v74
	v_fmac_f32_e32 v163, v76, v76
	v_fmac_f32_e32 v138, v72, v72
	v_add_f32_e32 v157, v157, v163
	v_mul_f32_e32 v163, v67, v67
	v_add_f32_e32 v138, v138, v151
	v_mul_f32_e32 v151, v69, v69
	v_fmac_f32_e32 v163, v66, v66
	v_fmac_f32_e32 v151, v68, v68
	v_add_f32_e32 v157, v163, v157
	v_add_f32_e32 v151, v151, v157
	v_and_b32_e32 v157, 64, v161
	v_add_f32_e32 v138, v151, v138
	v_xor_b32_e32 v151, 16, v161
	v_add_u32_e32 v157, 64, v157
	v_cmp_lt_i32_e32 vcc, v151, v157
	s_nop 1
	v_cndmask_b32_e32 v151, v161, v151, vcc
	v_lshlrev_b32_e32 v151, 2, v151
	v_mov_b32_e32 v151, v138
	s_nop 1
	v_permlane16_swap_b32 v151, v138
	s_waitcnt lgkmcnt(0)
	v_add_f32_e32 v138, v138, v151
	v_xor_b32_e32 v151, 32, v161
	v_cmp_lt_i32_e32 vcc, v151, v157
	s_nop 1
	v_cndmask_b32_e32 v151, v161, v151, vcc
	v_lshlrev_b32_e32 v151, 2, v151
	v_mov_b32_e32 v151, v138
	s_nop 1
	v_permlane32_swap_b32 v151, v138
	s_and_saveexec_b64 s[50:51], s[0:1]
	s_cbranch_execz .LBB0_1800
	v_ashrrev_i32_e32 v157, 31, v156
	v_lshlrev_b64 v[156:157], 6, v[156:157]
	s_waitcnt lgkmcnt(0)
	v_add_f32_e32 v138, v138, v151
	v_lshl_add_u64 v[156:157], s[48:49], 0, v[156:157]
	global_store_dword v[156:157], v138, off

.LBB0_1801:
	v_add_u32_e32 v156, 0x80, v150
	v_mad_i64_i32 v[164:165], s[50:51], s29, v156, 0
	v_lshl_add_u64 v[168:169], v[164:165], 1, v[154:155]
	v_cvt_pk_bf16_f32 v164, v62, v63
	v_cvt_pk_bf16_f32 v165, v64, v65
	v_cvt_pk_bf16_f32 v166, v54, v55
	v_cvt_pk_bf16_f32 v167, v56, v57
	s_and_b64 vcc, exec, s[4:5]
	global_store_dwordx4 v[168:169], v[164:167], off
	s_nop 1
	v_cvt_pk_bf16_f32 v164, v58, v59
	v_cvt_pk_bf16_f32 v165, v60, v61
	v_cvt_pk_bf16_f32 v166, v50, v51
	v_cvt_pk_bf16_f32 v167, v52, v53
	global_store_dwordx4 v[168:169], v[164:167], off offset:256
	s_cbranch_vccnz .LBB0_1805
	s_waitcnt lgkmcnt(0)
	v_mul_f32_e32 v151, v63, v63
	v_mul_f32_e32 v157, v65, v65
	v_fmac_f32_e32 v151, v62, v62
	v_fmac_f32_e32 v157, v64, v64
	v_add_f32_e32 v151, v151, v157
	v_mul_f32_e32 v157, v55, v55
	v_fmac_f32_e32 v157, v54, v54
	v_add_f32_e32 v151, v157, v151
	v_mul_f32_e32 v157, v59, v59
	v_mul_f32_e32 v163, v61, v61
	v_mul_f32_e32 v138, v57, v57
	v_fmac_f32_e32 v157, v58, v58
	v_fmac_f32_e32 v163, v60, v60
	v_fmac_f32_e32 v138, v56, v56
	v_add_f32_e32 v157, v157, v163
	v_mul_f32_e32 v163, v51, v51
	v_add_f32_e32 v138, v138, v151
	v_mul_f32_e32 v151, v53, v53
	v_fmac_f32_e32 v163, v50, v50
	v_fmac_f32_e32 v151, v52, v52
	v_add_f32_e32 v157, v163, v157
	v_add_f32_e32 v151, v151, v157
	v_and_b32_e32 v157, 64, v161
	v_add_f32_e32 v138, v151, v138
	v_xor_b32_e32 v151, 16, v161
	v_add_u32_e32 v157, 64, v157
	v_cmp_lt_i32_e32 vcc, v151, v157
	s_nop 1
	v_cndmask_b32_e32 v151, v161, v151, vcc
	v_lshlrev_b32_e32 v151, 2, v151
	v_mov_b32_e32 v151, v138
	s_nop 1
	v_permlane16_swap_b32 v151, v138
	s_waitcnt lgkmcnt(0)
	v_add_f32_e32 v138, v138, v151
	v_xor_b32_e32 v151, 32, v161
	v_cmp_lt_i32_e32 vcc, v151, v157
	s_nop 1
	v_cndmask_b32_e32 v151, v161, v151, vcc
	v_lshlrev_b32_e32 v151, 2, v151
	v_mov_b32_e32 v151, v138
	s_nop 1
	v_permlane32_swap_b32 v151, v138
	s_and_saveexec_b64 s[50:51], s[0:1]
	s_cbranch_execz .LBB0_1804
	v_ashrrev_i32_e32 v157, 31, v156
	v_lshlrev_b64 v[156:157], 6, v[156:157]
	s_waitcnt lgkmcnt(0)
	v_add_f32_e32 v138, v138, v151
	v_lshl_add_u64 v[156:157], s[48:49], 0, v[156:157]
	global_store_dword v[156:157], v138, off

.LBB0_1805:
	v_add_u32_e32 v156, 0x90, v150
	v_mad_i64_i32 v[164:165], s[50:51], s29, v156, 0
	v_lshl_add_u64 v[168:169], v[164:165], 1, v[154:155]
	v_cvt_pk_bf16_f32 v164, v46, v47
	v_cvt_pk_bf16_f32 v165, v48, v49
	v_cvt_pk_bf16_f32 v166, v38, v39
	v_cvt_pk_bf16_f32 v167, v40, v41
	s_and_b64 vcc, exec, s[4:5]
	global_store_dwordx4 v[168:169], v[164:167], off
	s_nop 1
	v_cvt_pk_bf16_f32 v164, v42, v43
	v_cvt_pk_bf16_f32 v165, v44, v45
	v_cvt_pk_bf16_f32 v166, v34, v35
	v_cvt_pk_bf16_f32 v167, v36, v37
	global_store_dwordx4 v[168:169], v[164:167], off offset:256
	s_cbranch_vccnz .LBB0_1809
	s_waitcnt lgkmcnt(0)
	v_mul_f32_e32 v151, v47, v47
	v_mul_f32_e32 v157, v49, v49
	v_fmac_f32_e32 v151, v46, v46
	v_fmac_f32_e32 v157, v48, v48
	v_add_f32_e32 v151, v151, v157
	v_mul_f32_e32 v157, v39, v39
	v_fmac_f32_e32 v157, v38, v38
	v_add_f32_e32 v151, v157, v151
	v_mul_f32_e32 v157, v43, v43
	v_mul_f32_e32 v163, v45, v45
	v_mul_f32_e32 v138, v41, v41
	v_fmac_f32_e32 v157, v42, v42
	v_fmac_f32_e32 v163, v44, v44
	v_fmac_f32_e32 v138, v40, v40
	v_add_f32_e32 v157, v157, v163
	v_mul_f32_e32 v163, v35, v35
	v_add_f32_e32 v138, v138, v151
	v_mul_f32_e32 v151, v37, v37
	v_fmac_f32_e32 v163, v34, v34
	v_fmac_f32_e32 v151, v36, v36
	v_add_f32_e32 v157, v163, v157
	v_add_f32_e32 v151, v151, v157
	v_and_b32_e32 v157, 64, v161
	v_add_f32_e32 v138, v151, v138
	v_xor_b32_e32 v151, 16, v161
	v_add_u32_e32 v157, 64, v157
	v_cmp_lt_i32_e32 vcc, v151, v157
	s_nop 1
	v_cndmask_b32_e32 v151, v161, v151, vcc
	v_lshlrev_b32_e32 v151, 2, v151
	v_mov_b32_e32 v151, v138
	s_nop 1
	v_permlane16_swap_b32 v151, v138
	s_waitcnt lgkmcnt(0)
	v_add_f32_e32 v138, v138, v151
	v_xor_b32_e32 v151, 32, v161
	v_cmp_lt_i32_e32 vcc, v151, v157
	s_nop 1
	v_cndmask_b32_e32 v151, v161, v151, vcc
	v_lshlrev_b32_e32 v151, 2, v151
	v_mov_b32_e32 v151, v138
	s_nop 1
	v_permlane32_swap_b32 v151, v138
	s_and_saveexec_b64 s[50:51], s[0:1]
	s_cbranch_execz .LBB0_1808
	v_ashrrev_i32_e32 v157, 31, v156
	v_lshlrev_b64 v[156:157], 6, v[156:157]
	s_waitcnt lgkmcnt(0)
	v_add_f32_e32 v138, v138, v151
	v_lshl_add_u64 v[156:157], s[48:49], 0, v[156:157]
	global_store_dword v[156:157], v138, off

.LBB0_1809:
	v_add_u32_e32 v156, 0xa0, v150
	v_mad_i64_i32 v[164:165], s[50:51], s29, v156, 0
	v_lshl_add_u64 v[168:169], v[164:165], 1, v[154:155]
	v_cvt_pk_bf16_f32 v164, v30, v31
	v_cvt_pk_bf16_f32 v165, v32, v33
	v_cvt_pk_bf16_f32 v166, v22, v23
	v_cvt_pk_bf16_f32 v167, v24, v25
	s_and_b64 vcc, exec, s[4:5]
	global_store_dwordx4 v[168:169], v[164:167], off
	s_nop 1
	v_cvt_pk_bf16_f32 v164, v26, v27
	v_cvt_pk_bf16_f32 v165, v28, v29
	v_cvt_pk_bf16_f32 v166, v18, v19
	v_cvt_pk_bf16_f32 v167, v20, v21
	global_store_dwordx4 v[168:169], v[164:167], off offset:256
	s_cbranch_vccnz .LBB0_1813
	s_waitcnt lgkmcnt(0)
	v_mul_f32_e32 v151, v31, v31
	v_mul_f32_e32 v157, v33, v33
	v_fmac_f32_e32 v151, v30, v30
	v_fmac_f32_e32 v157, v32, v32
	v_add_f32_e32 v151, v151, v157
	v_mul_f32_e32 v157, v23, v23
	v_fmac_f32_e32 v157, v22, v22
	v_add_f32_e32 v151, v157, v151
	v_mul_f32_e32 v157, v27, v27
	v_mul_f32_e32 v163, v29, v29
	v_mul_f32_e32 v138, v25, v25
	v_fmac_f32_e32 v157, v26, v26
	v_fmac_f32_e32 v163, v28, v28
	v_fmac_f32_e32 v138, v24, v24
	v_add_f32_e32 v157, v157, v163
	v_mul_f32_e32 v163, v19, v19
	v_add_f32_e32 v138, v138, v151
	v_mul_f32_e32 v151, v21, v21
	v_fmac_f32_e32 v163, v18, v18
	v_fmac_f32_e32 v151, v20, v20
	v_add_f32_e32 v157, v163, v157
	v_add_f32_e32 v151, v151, v157
	v_and_b32_e32 v157, 64, v161
	v_add_f32_e32 v138, v151, v138
	v_xor_b32_e32 v151, 16, v161
	v_add_u32_e32 v157, 64, v157
	v_cmp_lt_i32_e32 vcc, v151, v157
	s_nop 1
	v_cndmask_b32_e32 v151, v161, v151, vcc
	v_lshlrev_b32_e32 v151, 2, v151
	v_mov_b32_e32 v151, v138
	s_nop 1
	v_permlane16_swap_b32 v151, v138
	s_waitcnt lgkmcnt(0)
	v_add_f32_e32 v138, v138, v151
	v_xor_b32_e32 v151, 32, v161
	v_cmp_lt_i32_e32 vcc, v151, v157
	s_nop 1
	v_cndmask_b32_e32 v151, v161, v151, vcc
	v_lshlrev_b32_e32 v151, 2, v151
	v_mov_b32_e32 v151, v138
	s_nop 1
	v_permlane32_swap_b32 v151, v138
	s_and_saveexec_b64 s[50:51], s[0:1]
	s_cbranch_execz .LBB0_1812
	v_ashrrev_i32_e32 v157, 31, v156
	v_lshlrev_b64 v[156:157], 6, v[156:157]
	s_waitcnt lgkmcnt(0)
	v_add_f32_e32 v138, v138, v151
	v_lshl_add_u64 v[156:157], s[48:49], 0, v[156:157]
	global_store_dword v[156:157], v138, off

.LBB0_1813:
	v_add_u32_e32 v156, 0xb0, v150
	v_mad_i64_i32 v[164:165], s[50:51], s29, v156, 0
	v_lshl_add_u64 v[154:155], v[164:165], 1, v[154:155]
	v_cvt_pk_bf16_f32 v164, v14, v15
	v_cvt_pk_bf16_f32 v165, v16, v17
	v_cvt_pk_bf16_f32 v166, v6, v7
	v_cvt_pk_bf16_f32 v167, v8, v9
	s_and_b64 vcc, exec, s[4:5]
	global_store_dwordx4 v[154:155], v[164:167], off
	s_nop 1
	v_cvt_pk_bf16_f32 v164, v10, v11
	v_cvt_pk_bf16_f32 v165, v12, v13
	v_cvt_pk_bf16_f32 v166, v2, v3
	v_cvt_pk_bf16_f32 v167, v4, v5
	global_store_dwordx4 v[154:155], v[164:167], off offset:256
	s_cbranch_vccnz .LBB0_1817
	s_waitcnt lgkmcnt(0)
	v_mul_f32_e32 v151, v15, v15
	v_mul_f32_e32 v154, v17, v17
	v_fmac_f32_e32 v151, v14, v14
	v_fmac_f32_e32 v154, v16, v16
	v_add_f32_e32 v151, v151, v154
	v_mul_f32_e32 v154, v7, v7
	v_fmac_f32_e32 v154, v6, v6
	v_add_f32_e32 v151, v154, v151
	v_mul_f32_e32 v154, v11, v11
	v_mul_f32_e32 v155, v13, v13
	v_mul_f32_e32 v138, v9, v9
	v_fmac_f32_e32 v154, v10, v10
	v_fmac_f32_e32 v155, v12, v12
	v_fmac_f32_e32 v138, v8, v8
	v_add_f32_e32 v154, v154, v155
	v_mul_f32_e32 v155, v3, v3
	v_add_f32_e32 v138, v138, v151
	v_mul_f32_e32 v151, v5, v5
	v_fmac_f32_e32 v155, v2, v2
	v_fmac_f32_e32 v151, v4, v4
	v_add_f32_e32 v154, v155, v154
	v_add_f32_e32 v151, v151, v154
	v_and_b32_e32 v154, 64, v161
	v_add_f32_e32 v138, v151, v138
	v_xor_b32_e32 v151, 16, v161
	v_add_u32_e32 v154, 64, v154
	v_cmp_lt_i32_e32 vcc, v151, v154
	s_nop 1
	v_cndmask_b32_e32 v151, v161, v151, vcc
	v_lshlrev_b32_e32 v151, 2, v151
	v_mov_b32_e32 v151, v138
	s_nop 1
	v_permlane16_swap_b32 v151, v138
	s_waitcnt lgkmcnt(0)
	v_add_f32_e32 v138, v138, v151
	v_xor_b32_e32 v151, 32, v161
	v_cmp_lt_i32_e32 vcc, v151, v154
	s_nop 1
	v_cndmask_b32_e32 v151, v161, v151, vcc
	v_lshlrev_b32_e32 v151, 2, v151
	v_mov_b32_e32 v151, v138
	s_nop 1
	v_permlane32_swap_b32 v151, v138
	s_and_saveexec_b64 s[4:5], s[0:1]
	s_cbranch_execz .LBB0_1816
	v_ashrrev_i32_e32 v157, 31, v156
	v_lshlrev_b64 v[154:155], 6, v[156:157]
	s_waitcnt lgkmcnt(0)
	v_add_f32_e32 v138, v138, v151
	v_lshl_add_u64 v[154:155], s[48:49], 0, v[154:155]
	global_store_dword v[154:155], v138, off

.LBB0_1965:
	s_and_b64 vcc, exec, s[50:51]
	s_cbranch_vccz .LBB0_2000
	s_cmp_eq_u32 s47, 4
	s_cselect_b64 s[56:57], -1, 0
	s_lshl_b32 s4, s48, 2
	v_lshl_or_b32 v154, s48, 8, v159
	s_ashr_i32 s5, s4, 31
	v_ashrrev_i32_e32 v155, 31, v154
	s_lshl_b64 s[4:5], s[4:5], 2
	v_lshl_add_u64 v[154:155], v[154:155], 1, v[152:153]
	s_or_b64 s[50:51], s[10:11], s[4:5]
	v_mad_i64_i32 v[156:157], s[4:5], s45, v150, 0
	s_cmp_lg_u32 s47, 4
	v_lshl_add_u64 v[156:157], v[156:157], 1, v[154:155]
	v_cvt_pk_bf16_f32 v164, v122, v123
	v_cvt_pk_bf16_f32 v165, v124, v125
	v_cvt_pk_bf16_f32 v166, v118, v119
	v_cvt_pk_bf16_f32 v167, v120, v121
	global_store_dwordx4 v[156:157], v[164:167], off
	s_nop 1
	v_cvt_pk_bf16_f32 v164, v126, v127
	v_cvt_pk_bf16_f32 v165, v128, v129
	v_cvt_pk_bf16_f32 v166, v114, v115
	v_cvt_pk_bf16_f32 v167, v116, v117
	global_store_dwordx4 v[156:157], v[164:167], off offset:256
	s_cbranch_scc1 .LBB0_1970
	v_mul_f32_e32 v151, v123, v123
	v_mul_f32_e32 v156, v125, v125
	v_fmac_f32_e32 v151, v122, v122
	v_fmac_f32_e32 v156, v124, v124
	v_add_f32_e32 v151, v151, v156
	v_mul_f32_e32 v156, v119, v119
	v_fmac_f32_e32 v156, v118, v118
	v_add_f32_e32 v151, v156, v151
	v_mul_f32_e32 v156, v127, v127
	v_mul_f32_e32 v157, v129, v129
	v_mul_f32_e32 v138, v121, v121
	v_fmac_f32_e32 v156, v126, v126
	v_fmac_f32_e32 v157, v128, v128
	v_fmac_f32_e32 v138, v120, v120
	v_add_f32_e32 v156, v156, v157
	v_mul_f32_e32 v157, v115, v115
	v_add_f32_e32 v138, v138, v151
	v_mul_f32_e32 v151, v117, v117
	v_fmac_f32_e32 v157, v114, v114
	v_fmac_f32_e32 v151, v116, v116
	v_add_f32_e32 v156, v157, v156
	v_add_f32_e32 v151, v151, v156
	v_and_b32_e32 v156, 64, v161
	v_add_f32_e32 v138, v151, v138
	v_xor_b32_e32 v151, 16, v161
	v_add_u32_e32 v156, 64, v156
	v_cmp_lt_i32_e32 vcc, v151, v156
	s_nop 1
	v_cndmask_b32_e32 v151, v161, v151, vcc
	v_lshlrev_b32_e32 v151, 2, v151
	v_mov_b32_e32 v151, v138
	s_nop 1
	v_permlane16_swap_b32 v151, v138
	s_waitcnt lgkmcnt(0)
	v_add_f32_e32 v138, v138, v151
	v_xor_b32_e32 v151, 32, v161
	v_cmp_lt_i32_e32 vcc, v151, v156
	s_nop 1
	v_cndmask_b32_e32 v151, v161, v151, vcc
	v_lshlrev_b32_e32 v151, 2, v151
	v_mov_b32_e32 v156, v138
	s_nop 1
	v_permlane32_swap_b32 v156, v138
	s_and_saveexec_b64 s[4:5], s[0:1]
	s_cbranch_execz .LBB0_1969
	v_ashrrev_i32_e32 v151, 31, v150
	s_waitcnt lgkmcnt(0)
	v_add_f32_e32 v138, v138, v156
	v_lshlrev_b64 v[156:157], 6, v[150:151]
	v_lshl_add_u64 v[156:157], s[50:51], 0, v[156:157]
	global_store_dword v[156:157], v138, off

.LBB0_1970:
	s_waitcnt lgkmcnt(0)
	v_or_b32_e32 v156, 16, v150
	v_mad_i64_i32 v[164:165], s[4:5], s45, v156, 0
	v_cndmask_b32_e64 v138, 0, 1, s[56:57]
	v_lshl_add_u64 v[168:169], v[164:165], 1, v[154:155]
	v_cvt_pk_bf16_f32 v164, v110, v111
	v_cvt_pk_bf16_f32 v165, v112, v113
	v_cvt_pk_bf16_f32 v166, v102, v103
	v_cvt_pk_bf16_f32 v167, v104, v105
	v_cmp_ne_u32_e64 s[4:5], 1, v138
	s_andn2_b64 vcc, exec, s[56:57]
	global_store_dwordx4 v[168:169], v[164:167], off
	s_nop 1
	v_cvt_pk_bf16_f32 v164, v106, v107
	v_cvt_pk_bf16_f32 v165, v108, v109
	v_cvt_pk_bf16_f32 v166, v98, v99
	v_cvt_pk_bf16_f32 v167, v100, v101
	global_store_dwordx4 v[168:169], v[164:167], off offset:256
	s_cbranch_vccnz .LBB0_1974
	v_mul_f32_e32 v151, v111, v111
	v_mul_f32_e32 v157, v113, v113
	v_fmac_f32_e32 v151, v110, v110
	v_fmac_f32_e32 v157, v112, v112
	v_add_f32_e32 v151, v151, v157
	v_mul_f32_e32 v157, v103, v103
	v_fmac_f32_e32 v157, v102, v102
	v_add_f32_e32 v151, v157, v151
	v_mul_f32_e32 v157, v107, v107
	v_mul_f32_e32 v163, v109, v109
	v_mul_f32_e32 v138, v105, v105
	v_fmac_f32_e32 v157, v106, v106
	v_fmac_f32_e32 v163, v108, v108
	v_fmac_f32_e32 v138, v104, v104
	v_add_f32_e32 v157, v157, v163
	v_mul_f32_e32 v163, v99, v99
	v_add_f32_e32 v138, v138, v151
	v_mul_f32_e32 v151, v101, v101
	v_fmac_f32_e32 v163, v98, v98
	v_fmac_f32_e32 v151, v100, v100
	v_add_f32_e32 v157, v163, v157
	v_add_f32_e32 v151, v151, v157
	v_and_b32_e32 v157, 64, v161
	v_add_f32_e32 v138, v151, v138
	v_xor_b32_e32 v151, 16, v161
	v_add_u32_e32 v157, 64, v157
	v_cmp_lt_i32_e32 vcc, v151, v157
	s_nop 1
	v_cndmask_b32_e32 v151, v161, v151, vcc
	v_lshlrev_b32_e32 v151, 2, v151
	v_mov_b32_e32 v151, v138
	s_nop 1
	v_permlane16_swap_b32 v151, v138
	s_waitcnt lgkmcnt(0)
	v_add_f32_e32 v138, v138, v151
	v_xor_b32_e32 v151, 32, v161
	v_cmp_lt_i32_e32 vcc, v151, v157
	s_nop 1
	v_cndmask_b32_e32 v151, v161, v151, vcc
	v_lshlrev_b32_e32 v151, 2, v151
	v_mov_b32_e32 v151, v138
	s_nop 1
	v_permlane32_swap_b32 v151, v138
	s_and_saveexec_b64 s[56:57], s[0:1]
	s_cbranch_execz .LBB0_1973
	v_ashrrev_i32_e32 v157, 31, v156
	v_lshlrev_b64 v[156:157], 6, v[156:157]
	s_waitcnt lgkmcnt(0)
	v_add_f32_e32 v138, v138, v151
	v_lshl_add_u64 v[156:157], s[50:51], 0, v[156:157]
	global_store_dword v[156:157], v138, off

.LBB0_1974:
	v_or_b32_e32 v156, 32, v150
	v_mad_i64_i32 v[164:165], s[56:57], s45, v156, 0
	v_lshl_add_u64 v[168:169], v[164:165], 1, v[154:155]
	v_cvt_pk_bf16_f32 v164, v94, v95
	v_cvt_pk_bf16_f32 v165, v96, v97
	v_cvt_pk_bf16_f32 v166, v86, v87
	v_cvt_pk_bf16_f32 v167, v88, v89
	s_and_b64 vcc, exec, s[4:5]
	global_store_dwordx4 v[168:169], v[164:167], off
	s_nop 1
	v_cvt_pk_bf16_f32 v164, v90, v91
	v_cvt_pk_bf16_f32 v165, v92, v93
	v_cvt_pk_bf16_f32 v166, v82, v83
	v_cvt_pk_bf16_f32 v167, v84, v85
	global_store_dwordx4 v[168:169], v[164:167], off offset:256
	s_cbranch_vccnz .LBB0_1978
	s_waitcnt lgkmcnt(0)
	v_mul_f32_e32 v151, v95, v95
	v_mul_f32_e32 v157, v97, v97
	v_fmac_f32_e32 v151, v94, v94
	v_fmac_f32_e32 v157, v96, v96
	v_add_f32_e32 v151, v151, v157
	v_mul_f32_e32 v157, v87, v87
	v_fmac_f32_e32 v157, v86, v86
	v_add_f32_e32 v151, v157, v151
	v_mul_f32_e32 v157, v91, v91
	v_mul_f32_e32 v163, v93, v93
	v_mul_f32_e32 v138, v89, v89
	v_fmac_f32_e32 v157, v90, v90
	v_fmac_f32_e32 v163, v92, v92
	v_fmac_f32_e32 v138, v88, v88
	v_add_f32_e32 v157, v157, v163
	v_mul_f32_e32 v163, v83, v83
	v_add_f32_e32 v138, v138, v151
	v_mul_f32_e32 v151, v85, v85
	v_fmac_f32_e32 v163, v82, v82
	v_fmac_f32_e32 v151, v84, v84
	v_add_f32_e32 v157, v163, v157
	v_add_f32_e32 v151, v151, v157
	v_and_b32_e32 v157, 64, v161
	v_add_f32_e32 v138, v151, v138
	v_xor_b32_e32 v151, 16, v161
	v_add_u32_e32 v157, 64, v157
	v_cmp_lt_i32_e32 vcc, v151, v157
	s_nop 1
	v_cndmask_b32_e32 v151, v161, v151, vcc
	v_lshlrev_b32_e32 v151, 2, v151
	v_mov_b32_e32 v151, v138
	s_nop 1
	v_permlane16_swap_b32 v151, v138
	s_waitcnt lgkmcnt(0)
	v_add_f32_e32 v138, v138, v151
	v_xor_b32_e32 v151, 32, v161
	v_cmp_lt_i32_e32 vcc, v151, v157
	s_nop 1
	v_cndmask_b32_e32 v151, v161, v151, vcc
	v_lshlrev_b32_e32 v151, 2, v151
	v_mov_b32_e32 v151, v138
	s_nop 1
	v_permlane32_swap_b32 v151, v138
	s_and_saveexec_b64 s[56:57], s[0:1]
	s_cbranch_execz .LBB0_1977
	v_ashrrev_i32_e32 v157, 31, v156
	v_lshlrev_b64 v[156:157], 6, v[156:157]
	s_waitcnt lgkmcnt(0)
	v_add_f32_e32 v138, v138, v151
	v_lshl_add_u64 v[156:157], s[50:51], 0, v[156:157]
	global_store_dword v[156:157], v138, off

.LBB0_1978:
	v_or_b32_e32 v156, 48, v150
	v_mad_i64_i32 v[164:165], s[56:57], s45, v156, 0
	v_lshl_add_u64 v[168:169], v[164:165], 1, v[154:155]
	v_cvt_pk_bf16_f32 v164, v78, v79
	v_cvt_pk_bf16_f32 v165, v80, v81
	v_cvt_pk_bf16_f32 v166, v70, v71
	v_cvt_pk_bf16_f32 v167, v72, v73
	s_and_b64 vcc, exec, s[4:5]
	global_store_dwordx4 v[168:169], v[164:167], off
	s_nop 1
	v_cvt_pk_bf16_f32 v164, v74, v75
	v_cvt_pk_bf16_f32 v165, v76, v77
	v_cvt_pk_bf16_f32 v166, v66, v67
	v_cvt_pk_bf16_f32 v167, v68, v69
	global_store_dwordx4 v[168:169], v[164:167], off offset:256
	s_cbranch_vccnz .LBB0_1982
	s_waitcnt lgkmcnt(0)
	v_mul_f32_e32 v151, v79, v79
	v_mul_f32_e32 v157, v81, v81
	v_fmac_f32_e32 v151, v78, v78
	v_fmac_f32_e32 v157, v80, v80
	v_add_f32_e32 v151, v151, v157
	v_mul_f32_e32 v157, v71, v71
	v_fmac_f32_e32 v157, v70, v70
	v_add_f32_e32 v151, v157, v151
	v_mul_f32_e32 v157, v75, v75
	v_mul_f32_e32 v163, v77, v77
	v_mul_f32_e32 v138, v73, v73
	v_fmac_f32_e32 v157, v74, v74
	v_fmac_f32_e32 v163, v76, v76
	v_fmac_f32_e32 v138, v72, v72
	v_add_f32_e32 v157, v157, v163
	v_mul_f32_e32 v163, v67, v67
	v_add_f32_e32 v138, v138, v151
	v_mul_f32_e32 v151, v69, v69
	v_fmac_f32_e32 v163, v66, v66
	v_fmac_f32_e32 v151, v68, v68
	v_add_f32_e32 v157, v163, v157
	v_add_f32_e32 v151, v151, v157
	v_and_b32_e32 v157, 64, v161
	v_add_f32_e32 v138, v151, v138
	v_xor_b32_e32 v151, 16, v161
	v_add_u32_e32 v157, 64, v157
	v_cmp_lt_i32_e32 vcc, v151, v157
	s_nop 1
	v_cndmask_b32_e32 v151, v161, v151, vcc
	v_lshlrev_b32_e32 v151, 2, v151
	v_mov_b32_e32 v151, v138
	s_nop 1
	v_permlane16_swap_b32 v151, v138
	s_waitcnt lgkmcnt(0)
	v_add_f32_e32 v138, v138, v151
	v_xor_b32_e32 v151, 32, v161
	v_cmp_lt_i32_e32 vcc, v151, v157
	s_nop 1
	v_cndmask_b32_e32 v151, v161, v151, vcc
	v_lshlrev_b32_e32 v151, 2, v151
	v_mov_b32_e32 v151, v138
	s_nop 1
	v_permlane32_swap_b32 v151, v138
	s_and_saveexec_b64 s[56:57], s[0:1]
	s_cbranch_execz .LBB0_1981
	v_ashrrev_i32_e32 v157, 31, v156
	v_lshlrev_b64 v[156:157], 6, v[156:157]
	s_waitcnt lgkmcnt(0)
	v_add_f32_e32 v138, v138, v151
	v_lshl_add_u64 v[156:157], s[50:51], 0, v[156:157]
	global_store_dword v[156:157], v138, off

.LBB0_1982:
	v_add_u32_e32 v156, 0x80, v150
	v_mad_i64_i32 v[164:165], s[56:57], s45, v156, 0
	v_lshl_add_u64 v[168:169], v[164:165], 1, v[154:155]
	v_cvt_pk_bf16_f32 v164, v62, v63
	v_cvt_pk_bf16_f32 v165, v64, v65
	v_cvt_pk_bf16_f32 v166, v54, v55
	v_cvt_pk_bf16_f32 v167, v56, v57
	s_and_b64 vcc, exec, s[4:5]
	global_store_dwordx4 v[168:169], v[164:167], off
	s_nop 1
	v_cvt_pk_bf16_f32 v164, v58, v59
	v_cvt_pk_bf16_f32 v165, v60, v61
	v_cvt_pk_bf16_f32 v166, v50, v51
	v_cvt_pk_bf16_f32 v167, v52, v53
	global_store_dwordx4 v[168:169], v[164:167], off offset:256
	s_cbranch_vccnz .LBB0_1986
	s_waitcnt lgkmcnt(0)
	v_mul_f32_e32 v151, v63, v63
	v_mul_f32_e32 v157, v65, v65
	v_fmac_f32_e32 v151, v62, v62
	v_fmac_f32_e32 v157, v64, v64
	v_add_f32_e32 v151, v151, v157
	v_mul_f32_e32 v157, v55, v55
	v_fmac_f32_e32 v157, v54, v54
	v_add_f32_e32 v151, v157, v151
	v_mul_f32_e32 v157, v59, v59
	v_mul_f32_e32 v163, v61, v61
	v_mul_f32_e32 v138, v57, v57
	v_fmac_f32_e32 v157, v58, v58
	v_fmac_f32_e32 v163, v60, v60
	v_fmac_f32_e32 v138, v56, v56
	v_add_f32_e32 v157, v157, v163
	v_mul_f32_e32 v163, v51, v51
	v_add_f32_e32 v138, v138, v151
	v_mul_f32_e32 v151, v53, v53
	v_fmac_f32_e32 v163, v50, v50
	v_fmac_f32_e32 v151, v52, v52
	v_add_f32_e32 v157, v163, v157
	v_add_f32_e32 v151, v151, v157
	v_and_b32_e32 v157, 64, v161
	v_add_f32_e32 v138, v151, v138
	v_xor_b32_e32 v151, 16, v161
	v_add_u32_e32 v157, 64, v157
	v_cmp_lt_i32_e32 vcc, v151, v157
	s_nop 1
	v_cndmask_b32_e32 v151, v161, v151, vcc
	v_lshlrev_b32_e32 v151, 2, v151
	v_mov_b32_e32 v151, v138
	s_nop 1
	v_permlane16_swap_b32 v151, v138
	s_waitcnt lgkmcnt(0)
	v_add_f32_e32 v138, v138, v151
	v_xor_b32_e32 v151, 32, v161
	v_cmp_lt_i32_e32 vcc, v151, v157
	s_nop 1
	v_cndmask_b32_e32 v151, v161, v151, vcc
	v_lshlrev_b32_e32 v151, 2, v151
	v_mov_b32_e32 v151, v138
	s_nop 1
	v_permlane32_swap_b32 v151, v138
	s_and_saveexec_b64 s[56:57], s[0:1]
	s_cbranch_execz .LBB0_1985
	v_ashrrev_i32_e32 v157, 31, v156
	v_lshlrev_b64 v[156:157], 6, v[156:157]
	s_waitcnt lgkmcnt(0)
	v_add_f32_e32 v138, v138, v151
	v_lshl_add_u64 v[156:157], s[50:51], 0, v[156:157]
	global_store_dword v[156:157], v138, off

.LBB0_1986:
	v_add_u32_e32 v156, 0x90, v150
	v_mad_i64_i32 v[164:165], s[56:57], s45, v156, 0
	v_lshl_add_u64 v[168:169], v[164:165], 1, v[154:155]
	v_cvt_pk_bf16_f32 v164, v46, v47
	v_cvt_pk_bf16_f32 v165, v48, v49
	v_cvt_pk_bf16_f32 v166, v38, v39
	v_cvt_pk_bf16_f32 v167, v40, v41
	s_and_b64 vcc, exec, s[4:5]
	global_store_dwordx4 v[168:169], v[164:167], off
	s_nop 1
	v_cvt_pk_bf16_f32 v164, v42, v43
	v_cvt_pk_bf16_f32 v165, v44, v45
	v_cvt_pk_bf16_f32 v166, v34, v35
	v_cvt_pk_bf16_f32 v167, v36, v37
	global_store_dwordx4 v[168:169], v[164:167], off offset:256
	s_cbranch_vccnz .LBB0_1990
	s_waitcnt lgkmcnt(0)
	v_mul_f32_e32 v151, v47, v47
	v_mul_f32_e32 v157, v49, v49
	v_fmac_f32_e32 v151, v46, v46
	v_fmac_f32_e32 v157, v48, v48
	v_add_f32_e32 v151, v151, v157
	v_mul_f32_e32 v157, v39, v39
	v_fmac_f32_e32 v157, v38, v38
	v_add_f32_e32 v151, v157, v151
	v_mul_f32_e32 v157, v43, v43
	v_mul_f32_e32 v163, v45, v45
	v_mul_f32_e32 v138, v41, v41
	v_fmac_f32_e32 v157, v42, v42
	v_fmac_f32_e32 v163, v44, v44
	v_fmac_f32_e32 v138, v40, v40
	v_add_f32_e32 v157, v157, v163
	v_mul_f32_e32 v163, v35, v35
	v_add_f32_e32 v138, v138, v151
	v_mul_f32_e32 v151, v37, v37
	v_fmac_f32_e32 v163, v34, v34
	v_fmac_f32_e32 v151, v36, v36
	v_add_f32_e32 v157, v163, v157
	v_add_f32_e32 v151, v151, v157
	v_and_b32_e32 v157, 64, v161
	v_add_f32_e32 v138, v151, v138
	v_xor_b32_e32 v151, 16, v161
	v_add_u32_e32 v157, 64, v157
	v_cmp_lt_i32_e32 vcc, v151, v157
	s_nop 1
	v_cndmask_b32_e32 v151, v161, v151, vcc
	v_lshlrev_b32_e32 v151, 2, v151
	v_mov_b32_e32 v151, v138
	s_nop 1
	v_permlane16_swap_b32 v151, v138
	s_waitcnt lgkmcnt(0)
	v_add_f32_e32 v138, v138, v151
	v_xor_b32_e32 v151, 32, v161
	v_cmp_lt_i32_e32 vcc, v151, v157
	s_nop 1
	v_cndmask_b32_e32 v151, v161, v151, vcc
	v_lshlrev_b32_e32 v151, 2, v151
	v_mov_b32_e32 v151, v138
	s_nop 1
	v_permlane32_swap_b32 v151, v138
	s_and_saveexec_b64 s[56:57], s[0:1]
	s_cbranch_execz .LBB0_1989
	v_ashrrev_i32_e32 v157, 31, v156
	v_lshlrev_b64 v[156:157], 6, v[156:157]
	s_waitcnt lgkmcnt(0)
	v_add_f32_e32 v138, v138, v151
	v_lshl_add_u64 v[156:157], s[50:51], 0, v[156:157]
	global_store_dword v[156:157], v138, off

.LBB0_1990:
	v_add_u32_e32 v156, 0xa0, v150
	v_mad_i64_i32 v[164:165], s[56:57], s45, v156, 0
	v_lshl_add_u64 v[168:169], v[164:165], 1, v[154:155]
	v_cvt_pk_bf16_f32 v164, v30, v31
	v_cvt_pk_bf16_f32 v165, v32, v33
	v_cvt_pk_bf16_f32 v166, v22, v23
	v_cvt_pk_bf16_f32 v167, v24, v25
	s_and_b64 vcc, exec, s[4:5]
	global_store_dwordx4 v[168:169], v[164:167], off
	s_nop 1
	v_cvt_pk_bf16_f32 v164, v26, v27
	v_cvt_pk_bf16_f32 v165, v28, v29
	v_cvt_pk_bf16_f32 v166, v18, v19
	v_cvt_pk_bf16_f32 v167, v20, v21
	global_store_dwordx4 v[168:169], v[164:167], off offset:256
	s_cbranch_vccnz .LBB0_1994
	s_waitcnt lgkmcnt(0)
	v_mul_f32_e32 v151, v31, v31
	v_mul_f32_e32 v157, v33, v33
	v_fmac_f32_e32 v151, v30, v30
	v_fmac_f32_e32 v157, v32, v32
	v_add_f32_e32 v151, v151, v157
	v_mul_f32_e32 v157, v23, v23
	v_fmac_f32_e32 v157, v22, v22
	v_add_f32_e32 v151, v157, v151
	v_mul_f32_e32 v157, v27, v27
	v_mul_f32_e32 v163, v29, v29
	v_mul_f32_e32 v138, v25, v25
	v_fmac_f32_e32 v157, v26, v26
	v_fmac_f32_e32 v163, v28, v28
	v_fmac_f32_e32 v138, v24, v24
	v_add_f32_e32 v157, v157, v163
	v_mul_f32_e32 v163, v19, v19
	v_add_f32_e32 v138, v138, v151
	v_mul_f32_e32 v151, v21, v21
	v_fmac_f32_e32 v163, v18, v18
	v_fmac_f32_e32 v151, v20, v20
	v_add_f32_e32 v157, v163, v157
	v_add_f32_e32 v151, v151, v157
	v_and_b32_e32 v157, 64, v161
	v_add_f32_e32 v138, v151, v138
	v_xor_b32_e32 v151, 16, v161
	v_add_u32_e32 v157, 64, v157
	v_cmp_lt_i32_e32 vcc, v151, v157
	s_nop 1
	v_cndmask_b32_e32 v151, v161, v151, vcc
	v_lshlrev_b32_e32 v151, 2, v151
	v_mov_b32_e32 v151, v138
	s_nop 1
	v_permlane16_swap_b32 v151, v138
	s_waitcnt lgkmcnt(0)
	v_add_f32_e32 v138, v138, v151
	v_xor_b32_e32 v151, 32, v161
	v_cmp_lt_i32_e32 vcc, v151, v157
	s_nop 1
	v_cndmask_b32_e32 v151, v161, v151, vcc
	v_lshlrev_b32_e32 v151, 2, v151
	v_mov_b32_e32 v151, v138
	s_nop 1
	v_permlane32_swap_b32 v151, v138
	s_and_saveexec_b64 s[56:57], s[0:1]
	s_cbranch_execz .LBB0_1993
	v_ashrrev_i32_e32 v157, 31, v156
	v_lshlrev_b64 v[156:157], 6, v[156:157]
	s_waitcnt lgkmcnt(0)
	v_add_f32_e32 v138, v138, v151
	v_lshl_add_u64 v[156:157], s[50:51], 0, v[156:157]
	global_store_dword v[156:157], v138, off

.LBB0_1994:
	v_add_u32_e32 v156, 0xb0, v150
	v_mad_i64_i32 v[164:165], s[56:57], s45, v156, 0
	v_lshl_add_u64 v[154:155], v[164:165], 1, v[154:155]
	v_cvt_pk_bf16_f32 v164, v14, v15
	v_cvt_pk_bf16_f32 v165, v16, v17
	v_cvt_pk_bf16_f32 v166, v6, v7
	v_cvt_pk_bf16_f32 v167, v8, v9
	s_and_b64 vcc, exec, s[4:5]
	global_store_dwordx4 v[154:155], v[164:167], off
	s_nop 1
	v_cvt_pk_bf16_f32 v164, v10, v11
	v_cvt_pk_bf16_f32 v165, v12, v13
	v_cvt_pk_bf16_f32 v166, v2, v3
	v_cvt_pk_bf16_f32 v167, v4, v5
	global_store_dwordx4 v[154:155], v[164:167], off offset:256
	s_cbranch_vccnz .LBB0_1998
	s_waitcnt lgkmcnt(0)
	v_mul_f32_e32 v151, v15, v15
	v_mul_f32_e32 v154, v17, v17
	v_fmac_f32_e32 v151, v14, v14
	v_fmac_f32_e32 v154, v16, v16
	v_add_f32_e32 v151, v151, v154
	v_mul_f32_e32 v154, v7, v7
	v_fmac_f32_e32 v154, v6, v6
	v_add_f32_e32 v151, v154, v151
	v_mul_f32_e32 v154, v11, v11
	v_mul_f32_e32 v155, v13, v13
	v_mul_f32_e32 v138, v9, v9
	v_fmac_f32_e32 v154, v10, v10
	v_fmac_f32_e32 v155, v12, v12
	v_fmac_f32_e32 v138, v8, v8
	v_add_f32_e32 v154, v154, v155
	v_mul_f32_e32 v155, v3, v3
	v_add_f32_e32 v138, v138, v151
	v_mul_f32_e32 v151, v5, v5
	v_fmac_f32_e32 v155, v2, v2
	v_fmac_f32_e32 v151, v4, v4
	v_add_f32_e32 v154, v155, v154
	v_add_f32_e32 v151, v151, v154
	v_and_b32_e32 v154, 64, v161
	v_add_f32_e32 v138, v151, v138
	v_xor_b32_e32 v151, 16, v161
	v_add_u32_e32 v154, 64, v154
	v_cmp_lt_i32_e32 vcc, v151, v154
	s_nop 1
	v_cndmask_b32_e32 v151, v161, v151, vcc
	v_lshlrev_b32_e32 v151, 2, v151
	v_mov_b32_e32 v151, v138
	s_nop 1
	v_permlane16_swap_b32 v151, v138
	s_waitcnt lgkmcnt(0)
	v_add_f32_e32 v138, v138, v151
	v_xor_b32_e32 v151, 32, v161
	v_cmp_lt_i32_e32 vcc, v151, v154
	s_nop 1
	v_cndmask_b32_e32 v151, v161, v151, vcc
	v_lshlrev_b32_e32 v151, 2, v151
	v_mov_b32_e32 v151, v138
	s_nop 1
	v_permlane32_swap_b32 v151, v138
	s_and_saveexec_b64 s[4:5], s[0:1]
	s_cbranch_execz .LBB0_1997
	v_ashrrev_i32_e32 v157, 31, v156
	v_lshlrev_b64 v[154:155], 6, v[156:157]
	s_waitcnt lgkmcnt(0)
	v_add_f32_e32 v138, v138, v151
	v_lshl_add_u64 v[154:155], s[50:51], 0, v[154:155]
	global_store_dword v[154:155], v138, off

.LBB0_2096:
	s_and_b64 vcc, exec, s[24:25]
	s_cbranch_vccz .LBB0_2131
	s_cmp_eq_u32 s76, 4
	s_cselect_b64 s[28:29], -1, 0
	s_lshl_b32 s4, s74, 2
	s_ashr_i32 s5, s4, 31
	v_lshl_or_b32 v154, s74, 8, v159
	s_lshl_b64 s[4:5], s[4:5], 2
	v_ashrrev_i32_e32 v155, 31, v154
	s_add_u32 s24, s59, s4
	v_lshl_add_u64 v[154:155], v[154:155], 1, v[152:153]
	s_addc_u32 s25, s60, s5
	v_mad_i64_i32 v[156:157], s[4:5], s75, v150, 0
	s_cmp_lg_u32 s76, 4
	v_lshl_add_u64 v[156:157], v[156:157], 1, v[154:155]
	v_cvt_pk_bf16_f32 v164, v122, v123
	v_cvt_pk_bf16_f32 v165, v124, v125
	v_cvt_pk_bf16_f32 v166, v118, v119
	v_cvt_pk_bf16_f32 v167, v120, v121
	global_store_dwordx4 v[156:157], v[164:167], off
	s_nop 1
	v_cvt_pk_bf16_f32 v164, v126, v127
	v_cvt_pk_bf16_f32 v165, v128, v129
	v_cvt_pk_bf16_f32 v166, v114, v115
	v_cvt_pk_bf16_f32 v167, v116, v117
	global_store_dwordx4 v[156:157], v[164:167], off offset:256
	s_cbranch_scc1 .LBB0_2101
	v_mul_f32_e32 v151, v123, v123
	v_mul_f32_e32 v156, v125, v125
	v_fmac_f32_e32 v151, v122, v122
	v_fmac_f32_e32 v156, v124, v124
	v_add_f32_e32 v151, v151, v156
	v_mul_f32_e32 v156, v119, v119
	v_fmac_f32_e32 v156, v118, v118
	v_add_f32_e32 v151, v156, v151
	v_mul_f32_e32 v156, v127, v127
	v_mul_f32_e32 v157, v129, v129
	v_mul_f32_e32 v138, v121, v121
	v_fmac_f32_e32 v156, v126, v126
	v_fmac_f32_e32 v157, v128, v128
	v_fmac_f32_e32 v138, v120, v120
	v_add_f32_e32 v156, v156, v157
	v_mul_f32_e32 v157, v115, v115
	v_add_f32_e32 v138, v138, v151
	v_mul_f32_e32 v151, v117, v117
	v_fmac_f32_e32 v157, v114, v114
	v_fmac_f32_e32 v151, v116, v116
	v_add_f32_e32 v156, v157, v156
	v_add_f32_e32 v151, v151, v156
	v_and_b32_e32 v156, 64, v161
	v_add_f32_e32 v138, v151, v138
	v_xor_b32_e32 v151, 16, v161
	v_add_u32_e32 v156, 64, v156
	v_cmp_lt_i32_e32 vcc, v151, v156
	s_nop 1
	v_cndmask_b32_e32 v151, v161, v151, vcc
	v_lshlrev_b32_e32 v151, 2, v151
	v_mov_b32_e32 v151, v138
	s_nop 1
	v_permlane16_swap_b32 v151, v138
	s_waitcnt lgkmcnt(0)
	v_add_f32_e32 v138, v138, v151
	v_xor_b32_e32 v151, 32, v161
	v_cmp_lt_i32_e32 vcc, v151, v156
	s_nop 1
	v_cndmask_b32_e32 v151, v161, v151, vcc
	v_lshlrev_b32_e32 v151, 2, v151
	v_mov_b32_e32 v156, v138
	s_nop 1
	v_permlane32_swap_b32 v156, v138
	s_and_saveexec_b64 s[4:5], s[0:1]
	s_cbranch_execz .LBB0_2100
	v_ashrrev_i32_e32 v151, 31, v150
	s_waitcnt lgkmcnt(0)
	v_add_f32_e32 v138, v138, v156
	v_lshlrev_b64 v[156:157], 6, v[150:151]
	v_lshl_add_u64 v[156:157], s[24:25], 0, v[156:157]
	global_store_dword v[156:157], v138, off

.LBB0_2101:
	s_waitcnt lgkmcnt(0)
	v_or_b32_e32 v156, 16, v150
	v_mad_i64_i32 v[164:165], s[4:5], s75, v156, 0
	v_cndmask_b32_e64 v138, 0, 1, s[28:29]
	v_lshl_add_u64 v[168:169], v[164:165], 1, v[154:155]
	v_cvt_pk_bf16_f32 v164, v110, v111
	v_cvt_pk_bf16_f32 v165, v112, v113
	v_cvt_pk_bf16_f32 v166, v102, v103
	v_cvt_pk_bf16_f32 v167, v104, v105
	v_cmp_ne_u32_e64 s[4:5], 1, v138
	s_andn2_b64 vcc, exec, s[28:29]
	global_store_dwordx4 v[168:169], v[164:167], off
	s_nop 1
	v_cvt_pk_bf16_f32 v164, v106, v107
	v_cvt_pk_bf16_f32 v165, v108, v109
	v_cvt_pk_bf16_f32 v166, v98, v99
	v_cvt_pk_bf16_f32 v167, v100, v101
	global_store_dwordx4 v[168:169], v[164:167], off offset:256
	s_cbranch_vccnz .LBB0_2105
	v_mul_f32_e32 v151, v111, v111
	v_mul_f32_e32 v157, v113, v113
	v_fmac_f32_e32 v151, v110, v110
	v_fmac_f32_e32 v157, v112, v112
	v_add_f32_e32 v151, v151, v157
	v_mul_f32_e32 v157, v103, v103
	v_fmac_f32_e32 v157, v102, v102
	v_add_f32_e32 v151, v157, v151
	v_mul_f32_e32 v157, v107, v107
	v_mul_f32_e32 v163, v109, v109
	v_mul_f32_e32 v138, v105, v105
	v_fmac_f32_e32 v157, v106, v106
	v_fmac_f32_e32 v163, v108, v108
	v_fmac_f32_e32 v138, v104, v104
	v_add_f32_e32 v157, v157, v163
	v_mul_f32_e32 v163, v99, v99
	v_add_f32_e32 v138, v138, v151
	v_mul_f32_e32 v151, v101, v101
	v_fmac_f32_e32 v163, v98, v98
	v_fmac_f32_e32 v151, v100, v100
	v_add_f32_e32 v157, v163, v157
	v_add_f32_e32 v151, v151, v157
	v_and_b32_e32 v157, 64, v161
	v_add_f32_e32 v138, v151, v138
	v_xor_b32_e32 v151, 16, v161
	v_add_u32_e32 v157, 64, v157
	v_cmp_lt_i32_e32 vcc, v151, v157
	s_nop 1
	v_cndmask_b32_e32 v151, v161, v151, vcc
	v_lshlrev_b32_e32 v151, 2, v151
	v_mov_b32_e32 v151, v138
	s_nop 1
	v_permlane16_swap_b32 v151, v138
	s_waitcnt lgkmcnt(0)
	v_add_f32_e32 v138, v138, v151
	v_xor_b32_e32 v151, 32, v161
	v_cmp_lt_i32_e32 vcc, v151, v157
	s_nop 1
	v_cndmask_b32_e32 v151, v161, v151, vcc
	v_lshlrev_b32_e32 v151, 2, v151
	v_mov_b32_e32 v151, v138
	s_nop 1
	v_permlane32_swap_b32 v151, v138
	s_and_saveexec_b64 s[28:29], s[0:1]
	s_cbranch_execz .LBB0_2104
	v_ashrrev_i32_e32 v157, 31, v156
	v_lshlrev_b64 v[156:157], 6, v[156:157]
	s_waitcnt lgkmcnt(0)
	v_add_f32_e32 v138, v138, v151
	v_lshl_add_u64 v[156:157], s[24:25], 0, v[156:157]
	global_store_dword v[156:157], v138, off

.LBB0_2105:
	v_or_b32_e32 v156, 32, v150
	v_mad_i64_i32 v[164:165], s[28:29], s75, v156, 0
	v_lshl_add_u64 v[168:169], v[164:165], 1, v[154:155]
	v_cvt_pk_bf16_f32 v164, v94, v95
	v_cvt_pk_bf16_f32 v165, v96, v97
	v_cvt_pk_bf16_f32 v166, v86, v87
	v_cvt_pk_bf16_f32 v167, v88, v89
	s_and_b64 vcc, exec, s[4:5]
	global_store_dwordx4 v[168:169], v[164:167], off
	s_nop 1
	v_cvt_pk_bf16_f32 v164, v90, v91
	v_cvt_pk_bf16_f32 v165, v92, v93
	v_cvt_pk_bf16_f32 v166, v82, v83
	v_cvt_pk_bf16_f32 v167, v84, v85
	global_store_dwordx4 v[168:169], v[164:167], off offset:256
	s_cbranch_vccnz .LBB0_2109
	s_waitcnt lgkmcnt(0)
	v_mul_f32_e32 v151, v95, v95
	v_mul_f32_e32 v157, v97, v97
	v_fmac_f32_e32 v151, v94, v94
	v_fmac_f32_e32 v157, v96, v96
	v_add_f32_e32 v151, v151, v157
	v_mul_f32_e32 v157, v87, v87
	v_fmac_f32_e32 v157, v86, v86
	v_add_f32_e32 v151, v157, v151
	v_mul_f32_e32 v157, v91, v91
	v_mul_f32_e32 v163, v93, v93
	v_mul_f32_e32 v138, v89, v89
	v_fmac_f32_e32 v157, v90, v90
	v_fmac_f32_e32 v163, v92, v92
	v_fmac_f32_e32 v138, v88, v88
	v_add_f32_e32 v157, v157, v163
	v_mul_f32_e32 v163, v83, v83
	v_add_f32_e32 v138, v138, v151
	v_mul_f32_e32 v151, v85, v85
	v_fmac_f32_e32 v163, v82, v82
	v_fmac_f32_e32 v151, v84, v84
	v_add_f32_e32 v157, v163, v157
	v_add_f32_e32 v151, v151, v157
	v_and_b32_e32 v157, 64, v161
	v_add_f32_e32 v138, v151, v138
	v_xor_b32_e32 v151, 16, v161
	v_add_u32_e32 v157, 64, v157
	v_cmp_lt_i32_e32 vcc, v151, v157
	s_nop 1
	v_cndmask_b32_e32 v151, v161, v151, vcc
	v_lshlrev_b32_e32 v151, 2, v151
	v_mov_b32_e32 v151, v138
	s_nop 1
	v_permlane16_swap_b32 v151, v138
	s_waitcnt lgkmcnt(0)
	v_add_f32_e32 v138, v138, v151
	v_xor_b32_e32 v151, 32, v161
	v_cmp_lt_i32_e32 vcc, v151, v157
	s_nop 1
	v_cndmask_b32_e32 v151, v161, v151, vcc
	v_lshlrev_b32_e32 v151, 2, v151
	v_mov_b32_e32 v151, v138
	s_nop 1
	v_permlane32_swap_b32 v151, v138
	s_and_saveexec_b64 s[28:29], s[0:1]
	s_cbranch_execz .LBB0_2108
	v_ashrrev_i32_e32 v157, 31, v156
	v_lshlrev_b64 v[156:157], 6, v[156:157]
	s_waitcnt lgkmcnt(0)
	v_add_f32_e32 v138, v138, v151
	v_lshl_add_u64 v[156:157], s[24:25], 0, v[156:157]
	global_store_dword v[156:157], v138, off

.LBB0_2109:
	v_or_b32_e32 v156, 48, v150
	v_mad_i64_i32 v[164:165], s[28:29], s75, v156, 0
	v_lshl_add_u64 v[168:169], v[164:165], 1, v[154:155]
	v_cvt_pk_bf16_f32 v164, v78, v79
	v_cvt_pk_bf16_f32 v165, v80, v81
	v_cvt_pk_bf16_f32 v166, v70, v71
	v_cvt_pk_bf16_f32 v167, v72, v73
	s_and_b64 vcc, exec, s[4:5]
	global_store_dwordx4 v[168:169], v[164:167], off
	s_nop 1
	v_cvt_pk_bf16_f32 v164, v74, v75
	v_cvt_pk_bf16_f32 v165, v76, v77
	v_cvt_pk_bf16_f32 v166, v66, v67
	v_cvt_pk_bf16_f32 v167, v68, v69
	global_store_dwordx4 v[168:169], v[164:167], off offset:256
	s_cbranch_vccnz .LBB0_2113
	s_waitcnt lgkmcnt(0)
	v_mul_f32_e32 v151, v79, v79
	v_mul_f32_e32 v157, v81, v81
	v_fmac_f32_e32 v151, v78, v78
	v_fmac_f32_e32 v157, v80, v80
	v_add_f32_e32 v151, v151, v157
	v_mul_f32_e32 v157, v71, v71
	v_fmac_f32_e32 v157, v70, v70
	v_add_f32_e32 v151, v157, v151
	v_mul_f32_e32 v157, v75, v75
	v_mul_f32_e32 v163, v77, v77
	v_mul_f32_e32 v138, v73, v73
	v_fmac_f32_e32 v157, v74, v74
	v_fmac_f32_e32 v163, v76, v76
	v_fmac_f32_e32 v138, v72, v72
	v_add_f32_e32 v157, v157, v163
	v_mul_f32_e32 v163, v67, v67
	v_add_f32_e32 v138, v138, v151
	v_mul_f32_e32 v151, v69, v69
	v_fmac_f32_e32 v163, v66, v66
	v_fmac_f32_e32 v151, v68, v68
	v_add_f32_e32 v157, v163, v157
	v_add_f32_e32 v151, v151, v157
	v_and_b32_e32 v157, 64, v161
	v_add_f32_e32 v138, v151, v138
	v_xor_b32_e32 v151, 16, v161
	v_add_u32_e32 v157, 64, v157
	v_cmp_lt_i32_e32 vcc, v151, v157
	s_nop 1
	v_cndmask_b32_e32 v151, v161, v151, vcc
	v_lshlrev_b32_e32 v151, 2, v151
	v_mov_b32_e32 v151, v138
	s_nop 1
	v_permlane16_swap_b32 v151, v138
	s_waitcnt lgkmcnt(0)
	v_add_f32_e32 v138, v138, v151
	v_xor_b32_e32 v151, 32, v161
	v_cmp_lt_i32_e32 vcc, v151, v157
	s_nop 1
	v_cndmask_b32_e32 v151, v161, v151, vcc
	v_lshlrev_b32_e32 v151, 2, v151
	v_mov_b32_e32 v151, v138
	s_nop 1
	v_permlane32_swap_b32 v151, v138
	s_and_saveexec_b64 s[28:29], s[0:1]
	s_cbranch_execz .LBB0_2112
	v_ashrrev_i32_e32 v157, 31, v156
	v_lshlrev_b64 v[156:157], 6, v[156:157]
	s_waitcnt lgkmcnt(0)
	v_add_f32_e32 v138, v138, v151
	v_lshl_add_u64 v[156:157], s[24:25], 0, v[156:157]
	global_store_dword v[156:157], v138, off

.LBB0_2113:
	v_add_u32_e32 v156, 0x80, v150
	v_mad_i64_i32 v[164:165], s[28:29], s75, v156, 0
	v_lshl_add_u64 v[168:169], v[164:165], 1, v[154:155]
	v_cvt_pk_bf16_f32 v164, v62, v63
	v_cvt_pk_bf16_f32 v165, v64, v65
	v_cvt_pk_bf16_f32 v166, v54, v55
	v_cvt_pk_bf16_f32 v167, v56, v57
	s_and_b64 vcc, exec, s[4:5]
	global_store_dwordx4 v[168:169], v[164:167], off
	s_nop 1
	v_cvt_pk_bf16_f32 v164, v58, v59
	v_cvt_pk_bf16_f32 v165, v60, v61
	v_cvt_pk_bf16_f32 v166, v50, v51
	v_cvt_pk_bf16_f32 v167, v52, v53
	global_store_dwordx4 v[168:169], v[164:167], off offset:256
	s_cbranch_vccnz .LBB0_2117
	s_waitcnt lgkmcnt(0)
	v_mul_f32_e32 v151, v63, v63
	v_mul_f32_e32 v157, v65, v65
	v_fmac_f32_e32 v151, v62, v62
	v_fmac_f32_e32 v157, v64, v64
	v_add_f32_e32 v151, v151, v157
	v_mul_f32_e32 v157, v55, v55
	v_fmac_f32_e32 v157, v54, v54
	v_add_f32_e32 v151, v157, v151
	v_mul_f32_e32 v157, v59, v59
	v_mul_f32_e32 v163, v61, v61
	v_mul_f32_e32 v138, v57, v57
	v_fmac_f32_e32 v157, v58, v58
	v_fmac_f32_e32 v163, v60, v60
	v_fmac_f32_e32 v138, v56, v56
	v_add_f32_e32 v157, v157, v163
	v_mul_f32_e32 v163, v51, v51
	v_add_f32_e32 v138, v138, v151
	v_mul_f32_e32 v151, v53, v53
	v_fmac_f32_e32 v163, v50, v50
	v_fmac_f32_e32 v151, v52, v52
	v_add_f32_e32 v157, v163, v157
	v_add_f32_e32 v151, v151, v157
	v_and_b32_e32 v157, 64, v161
	v_add_f32_e32 v138, v151, v138
	v_xor_b32_e32 v151, 16, v161
	v_add_u32_e32 v157, 64, v157
	v_cmp_lt_i32_e32 vcc, v151, v157
	s_nop 1
	v_cndmask_b32_e32 v151, v161, v151, vcc
	v_lshlrev_b32_e32 v151, 2, v151
	v_mov_b32_e32 v151, v138
	s_nop 1
	v_permlane16_swap_b32 v151, v138
	s_waitcnt lgkmcnt(0)
	v_add_f32_e32 v138, v138, v151
	v_xor_b32_e32 v151, 32, v161
	v_cmp_lt_i32_e32 vcc, v151, v157
	s_nop 1
	v_cndmask_b32_e32 v151, v161, v151, vcc
	v_lshlrev_b32_e32 v151, 2, v151
	v_mov_b32_e32 v151, v138
	s_nop 1
	v_permlane32_swap_b32 v151, v138
	s_and_saveexec_b64 s[28:29], s[0:1]
	s_cbranch_execz .LBB0_2116
	v_ashrrev_i32_e32 v157, 31, v156
	v_lshlrev_b64 v[156:157], 6, v[156:157]
	s_waitcnt lgkmcnt(0)
	v_add_f32_e32 v138, v138, v151
	v_lshl_add_u64 v[156:157], s[24:25], 0, v[156:157]
	global_store_dword v[156:157], v138, off

.LBB0_2117:
	v_add_u32_e32 v156, 0x90, v150
	v_mad_i64_i32 v[164:165], s[28:29], s75, v156, 0
	v_lshl_add_u64 v[168:169], v[164:165], 1, v[154:155]
	v_cvt_pk_bf16_f32 v164, v46, v47
	v_cvt_pk_bf16_f32 v165, v48, v49
	v_cvt_pk_bf16_f32 v166, v38, v39
	v_cvt_pk_bf16_f32 v167, v40, v41
	s_and_b64 vcc, exec, s[4:5]
	global_store_dwordx4 v[168:169], v[164:167], off
	s_nop 1
	v_cvt_pk_bf16_f32 v164, v42, v43
	v_cvt_pk_bf16_f32 v165, v44, v45
	v_cvt_pk_bf16_f32 v166, v34, v35
	v_cvt_pk_bf16_f32 v167, v36, v37
	global_store_dwordx4 v[168:169], v[164:167], off offset:256
	s_cbranch_vccnz .LBB0_2121
	s_waitcnt lgkmcnt(0)
	v_mul_f32_e32 v151, v47, v47
	v_mul_f32_e32 v157, v49, v49
	v_fmac_f32_e32 v151, v46, v46
	v_fmac_f32_e32 v157, v48, v48
	v_add_f32_e32 v151, v151, v157
	v_mul_f32_e32 v157, v39, v39
	v_fmac_f32_e32 v157, v38, v38
	v_add_f32_e32 v151, v157, v151
	v_mul_f32_e32 v157, v43, v43
	v_mul_f32_e32 v163, v45, v45
	v_mul_f32_e32 v138, v41, v41
	v_fmac_f32_e32 v157, v42, v42
	v_fmac_f32_e32 v163, v44, v44
	v_fmac_f32_e32 v138, v40, v40
	v_add_f32_e32 v157, v157, v163
	v_mul_f32_e32 v163, v35, v35
	v_add_f32_e32 v138, v138, v151
	v_mul_f32_e32 v151, v37, v37
	v_fmac_f32_e32 v163, v34, v34
	v_fmac_f32_e32 v151, v36, v36
	v_add_f32_e32 v157, v163, v157
	v_add_f32_e32 v151, v151, v157
	v_and_b32_e32 v157, 64, v161
	v_add_f32_e32 v138, v151, v138
	v_xor_b32_e32 v151, 16, v161
	v_add_u32_e32 v157, 64, v157
	v_cmp_lt_i32_e32 vcc, v151, v157
	s_nop 1
	v_cndmask_b32_e32 v151, v161, v151, vcc
	v_lshlrev_b32_e32 v151, 2, v151
	v_mov_b32_e32 v151, v138
	s_nop 1
	v_permlane16_swap_b32 v151, v138
	s_waitcnt lgkmcnt(0)
	v_add_f32_e32 v138, v138, v151
	v_xor_b32_e32 v151, 32, v161
	v_cmp_lt_i32_e32 vcc, v151, v157
	s_nop 1
	v_cndmask_b32_e32 v151, v161, v151, vcc
	v_lshlrev_b32_e32 v151, 2, v151
	v_mov_b32_e32 v151, v138
	s_nop 1
	v_permlane32_swap_b32 v151, v138
	s_and_saveexec_b64 s[28:29], s[0:1]
	s_cbranch_execz .LBB0_2120
	v_ashrrev_i32_e32 v157, 31, v156
	v_lshlrev_b64 v[156:157], 6, v[156:157]
	s_waitcnt lgkmcnt(0)
	v_add_f32_e32 v138, v138, v151
	v_lshl_add_u64 v[156:157], s[24:25], 0, v[156:157]
	global_store_dword v[156:157], v138, off

.LBB0_2121:
	v_add_u32_e32 v156, 0xa0, v150
	v_mad_i64_i32 v[164:165], s[28:29], s75, v156, 0
	v_lshl_add_u64 v[168:169], v[164:165], 1, v[154:155]
	v_cvt_pk_bf16_f32 v164, v30, v31
	v_cvt_pk_bf16_f32 v165, v32, v33
	v_cvt_pk_bf16_f32 v166, v22, v23
	v_cvt_pk_bf16_f32 v167, v24, v25
	s_and_b64 vcc, exec, s[4:5]
	global_store_dwordx4 v[168:169], v[164:167], off
	s_nop 1
	v_cvt_pk_bf16_f32 v164, v26, v27
	v_cvt_pk_bf16_f32 v165, v28, v29
	v_cvt_pk_bf16_f32 v166, v18, v19
	v_cvt_pk_bf16_f32 v167, v20, v21
	global_store_dwordx4 v[168:169], v[164:167], off offset:256
	s_cbranch_vccnz .LBB0_2125
	s_waitcnt lgkmcnt(0)
	v_mul_f32_e32 v151, v31, v31
	v_mul_f32_e32 v157, v33, v33
	v_fmac_f32_e32 v151, v30, v30
	v_fmac_f32_e32 v157, v32, v32
	v_add_f32_e32 v151, v151, v157
	v_mul_f32_e32 v157, v23, v23
	v_fmac_f32_e32 v157, v22, v22
	v_add_f32_e32 v151, v157, v151
	v_mul_f32_e32 v157, v27, v27
	v_mul_f32_e32 v163, v29, v29
	v_mul_f32_e32 v138, v25, v25
	v_fmac_f32_e32 v157, v26, v26
	v_fmac_f32_e32 v163, v28, v28
	v_fmac_f32_e32 v138, v24, v24
	v_add_f32_e32 v157, v157, v163
	v_mul_f32_e32 v163, v19, v19
	v_add_f32_e32 v138, v138, v151
	v_mul_f32_e32 v151, v21, v21
	v_fmac_f32_e32 v163, v18, v18
	v_fmac_f32_e32 v151, v20, v20
	v_add_f32_e32 v157, v163, v157
	v_add_f32_e32 v151, v151, v157
	v_and_b32_e32 v157, 64, v161
	v_add_f32_e32 v138, v151, v138
	v_xor_b32_e32 v151, 16, v161
	v_add_u32_e32 v157, 64, v157
	v_cmp_lt_i32_e32 vcc, v151, v157
	s_nop 1
	v_cndmask_b32_e32 v151, v161, v151, vcc
	v_lshlrev_b32_e32 v151, 2, v151
	v_mov_b32_e32 v151, v138
	s_nop 1
	v_permlane16_swap_b32 v151, v138
	s_waitcnt lgkmcnt(0)
	v_add_f32_e32 v138, v138, v151
	v_xor_b32_e32 v151, 32, v161
	v_cmp_lt_i32_e32 vcc, v151, v157
	s_nop 1
	v_cndmask_b32_e32 v151, v161, v151, vcc
	v_lshlrev_b32_e32 v151, 2, v151
	v_mov_b32_e32 v151, v138
	s_nop 1
	v_permlane32_swap_b32 v151, v138
	s_and_saveexec_b64 s[28:29], s[0:1]
	s_cbranch_execz .LBB0_2124
	v_ashrrev_i32_e32 v157, 31, v156
	v_lshlrev_b64 v[156:157], 6, v[156:157]
	s_waitcnt lgkmcnt(0)
	v_add_f32_e32 v138, v138, v151
	v_lshl_add_u64 v[156:157], s[24:25], 0, v[156:157]
	global_store_dword v[156:157], v138, off

.LBB0_2125:
	v_add_u32_e32 v156, 0xb0, v150
	v_mad_i64_i32 v[164:165], s[28:29], s75, v156, 0
	v_lshl_add_u64 v[154:155], v[164:165], 1, v[154:155]
	v_cvt_pk_bf16_f32 v164, v14, v15
	v_cvt_pk_bf16_f32 v165, v16, v17
	v_cvt_pk_bf16_f32 v166, v6, v7
	v_cvt_pk_bf16_f32 v167, v8, v9
	s_and_b64 vcc, exec, s[4:5]
	global_store_dwordx4 v[154:155], v[164:167], off
	s_nop 1
	v_cvt_pk_bf16_f32 v164, v10, v11
	v_cvt_pk_bf16_f32 v165, v12, v13
	v_cvt_pk_bf16_f32 v166, v2, v3
	v_cvt_pk_bf16_f32 v167, v4, v5
	global_store_dwordx4 v[154:155], v[164:167], off offset:256
	s_cbranch_vccnz .LBB0_2129
	s_waitcnt lgkmcnt(0)
	v_mul_f32_e32 v151, v15, v15
	v_mul_f32_e32 v154, v17, v17
	v_fmac_f32_e32 v151, v14, v14
	v_fmac_f32_e32 v154, v16, v16
	v_add_f32_e32 v151, v151, v154
	v_mul_f32_e32 v154, v7, v7
	v_fmac_f32_e32 v154, v6, v6
	v_add_f32_e32 v151, v154, v151
	v_mul_f32_e32 v154, v11, v11
	v_mul_f32_e32 v155, v13, v13
	v_mul_f32_e32 v138, v9, v9
	v_fmac_f32_e32 v154, v10, v10
	v_fmac_f32_e32 v155, v12, v12
	v_fmac_f32_e32 v138, v8, v8
	v_add_f32_e32 v154, v154, v155
	v_mul_f32_e32 v155, v3, v3
	v_add_f32_e32 v138, v138, v151
	v_mul_f32_e32 v151, v5, v5
	v_fmac_f32_e32 v155, v2, v2
	v_fmac_f32_e32 v151, v4, v4
	v_add_f32_e32 v154, v155, v154
	v_add_f32_e32 v151, v151, v154
	v_and_b32_e32 v154, 64, v161
	v_add_f32_e32 v138, v151, v138
	v_xor_b32_e32 v151, 16, v161
	v_add_u32_e32 v154, 64, v154
	v_cmp_lt_i32_e32 vcc, v151, v154
	s_nop 1
	v_cndmask_b32_e32 v151, v161, v151, vcc
	v_lshlrev_b32_e32 v151, 2, v151
	v_mov_b32_e32 v151, v138
	s_nop 1
	v_permlane16_swap_b32 v151, v138
	s_waitcnt lgkmcnt(0)
	v_add_f32_e32 v138, v138, v151
	v_xor_b32_e32 v151, 32, v161
	v_cmp_lt_i32_e32 vcc, v151, v154
	s_nop 1
	v_cndmask_b32_e32 v151, v161, v151, vcc
	v_lshlrev_b32_e32 v151, 2, v151
	v_mov_b32_e32 v151, v138
	s_nop 1
	v_permlane32_swap_b32 v151, v138
	s_and_saveexec_b64 s[4:5], s[0:1]
	s_cbranch_execz .LBB0_2128
	v_ashrrev_i32_e32 v157, 31, v156
	v_lshlrev_b64 v[154:155], 6, v[156:157]
	s_waitcnt lgkmcnt(0)
	v_add_f32_e32 v138, v138, v151
	v_lshl_add_u64 v[154:155], s[24:25], 0, v[154:155]
	global_store_dword v[154:155], v138, off
